# counted lgkmcnt ladder inside every K-loop MFMA burst instead of lgkmcnt(0) after the barrier
# speedup vs baseline: 1.0054x; 1.0054x over previous
; #define PG8_STAGE(bufoff, gbase, voff) do { _Pragma("unroll") for (int _i = 0; _i < 2; ++_i) \
;         __builtin_amdgcn_global_load_lds((const unsigned*)((const char*)(gbase) + (voff)[_i]), (LAS unsigned*)(lds + (bufoff) + ldsw + _i * 8192), 16, 0, 0); } while (0)
; #define PG8_LDA(dst, b, h) do { _Pragma("unroll") for (int m = 0; m < 4; ++m) _Pragma("unroll") for (int k = 0; k < 2; ++k) dst[m][k] = *(const LAS bf16x8*)(lds + PG8_SA(b, h) + aoff + m * 2048 + k * 1024); } while (0)
; #define PG8_LDB(dst, b, h) do { _Pragma("unroll") for (int n = 0; n < 2; ++n) _Pragma("unroll") for (int k = 0; k < 2; ++k) dst[n][k] = *(const LAS bf16x8*)(lds + PG8_SB(b, h) + boff + n * 2048 + k * 1024); } while (0)
; #define PG8_MMA(ai, bj, At, Bt) do { __builtin_amdgcn_s_setprio(1); _Pragma("unroll") for (int m = 0; m < 4; ++m) _Pragma("unroll") for (int n = 0; n < 2; ++n) _Pragma("unroll") for (int k = 0; k < 2; ++k) \
;         acc[ai][bj][m][n] = __builtin_amdgcn_mfma_f32_16x16x32_bf16(Bt[n][k], At[m][k], acc[ai][bj][m][n], 0, 0, 0); __builtin_amdgcn_s_setprio(0); } while (0)
; #define PG8_WAIT_L(n) asm volatile("s_waitcnt lgkmcnt(" #n ")" ::: "memory")
; #define PG8_BAR __builtin_amdgcn_s_barrier()
; template <class Epi>
; DI void gemm_phase(LAS unsigned char* lds, const Gemm g, const StaticOrder& S, const Epi& E) {
;     ...
;         const bool has_next = S.next(ui + 1, nxt);
;         const char* nA = has_next ? (const char*)g.A + (size_t)nxt.pm * tstep : cA; const char* nB = has_next ? (const char*)g.Bt + (size_t)nxt.pn * tstep : cB;
;         for (int t = 0; t < nt; t += 2) {
;             const bool last = (t == nt - 2);
;             const char* a1 = cA + (size_t)(t + 1) * kstep;
;             const char* a2 = last ? nA : cA + (size_t)(t + 2) * kstep; const char* b2 = last ? nB : cB + (size_t)(t + 2) * kstep;
;             const char* a3 = a2 + kstep; const char* b3 = b2 + kstep;
;             PG8_LDB(B0, 0, 0); PG8_SCHED; PG8_LDA(At, 0, 0); PG8_STAGE(PG8_SA(1, 1), a1 + hstep, voffA);
;             PG8_WAIT_L(8); PG8_BAR; PG8_WAIT_L(0); PG8_MMA(0, 0, At, B0); PG8_BAR; PG8_SCHED;
;             PG8_LDB(B1, 0, 1); PG8_STAGE(PG8_SB(0, 0), b2, voffB);
;             PG8_BAR; PG8_WAIT_L(0); PG8_MMA(0, 1, At, B1); PG8_BAR;
;             PG8_LDA(At, 0, 1); PG8_STAGE(PG8_SA(0, 0), a2, voffA);
;             PG8_BAR; PG8_WAIT_L(0); PG8_MMA(1, 0, At, B0); PG8_BAR; PG8_SCHED;
.LBB0_210:
	s_ashr_i32 s17, s16, 31
	v_cmp_lt_i64_e32 vcc, s[18:19], v[140:141]
	s_lshl_b64 s[18:19], s[16:17], 19
	s_add_u32 s18, s43, s18
	s_addc_u32 s19, s44, s19
	s_and_b64 s[22:23], vcc, exec
	s_cselect_b32 s17, s19, s25
	s_cselect_b32 s76, s18, s24
	s_ashr_i32 s15, s14, 31
	s_lshl_b64 s[22:23], s[14:15], 19
	s_add_u32 s22, s30, s22
	s_addc_u32 s23, s31, s23
	s_and_b64 s[40:41], vcc, exec
	s_cselect_b32 s15, s23, s39
	s_cselect_b32 s77, s22, s38
	s_add_u32 s24, s24, 0x40080
	s_addc_u32 s25, s25, 0
	s_add_u32 s78, s38, 0x100
	s_addc_u32 s79, s39, 0
	s_mov_b32 s80, -2
	ds_read_b128 v[150:153], v147
	ds_read_b128 v[154:157], v147 offset:1024
	ds_read_b128 v[158:161], v147 offset:2048
	ds_read_b128 v[162:165], v147 offset:3072
	s_add_u32 s38, s24, 0xfffc0080
	s_addc_u32 s39, s25, -1
	s_cmp_eq_u32 s80, 12
	s_cselect_b32 s41, s17, s39
	s_cselect_b32 s40, s76, s38
	s_cselect_b32 s39, s15, s79
	s_cselect_b32 s38, s77, s78
	s_add_i32 m0, s13, 0xc000
	ds_read_b128 v[166:169], v148
	ds_read_b128 v[170:173], v148 offset:1024
	ds_read_b128 v[174:177], v148 offset:2048
	ds_read_b128 v[182:185], v148 offset:3072
	ds_read_b128 v[186:189], v148 offset:4096
	ds_read_b128 v[190:193], v148 offset:5120
	ds_read_b128 v[194:197], v148 offset:6144
	ds_read_b128 v[198:201], v148 offset:7168
	global_load_lds_dwordx4 v136, s[24:25]
	s_add_i32 m0, s13, 0xe000
	s_nop 0
	global_load_lds_dwordx4 v138, s[24:25]
	s_waitcnt lgkmcnt(8)
	s_barrier
	s_waitcnt lgkmcnt(7)
	v_mfma_f32_16x16x32_bf16 v[124:127], v[150:153], v[166:169], 0
	v_mfma_f32_16x16x32_bf16 v[120:123], v[158:161], v[166:169], 0
	s_waitcnt lgkmcnt(5)
	v_mfma_f32_16x16x32_bf16 v[116:119], v[150:153], v[174:177], 0
	v_mfma_f32_16x16x32_bf16 v[112:115], v[158:161], v[174:177], 0
	s_waitcnt lgkmcnt(3)
	v_mfma_f32_16x16x32_bf16 v[100:103], v[150:153], v[186:189], 0
	v_mfma_f32_16x16x32_bf16 v[96:99], v[158:161], v[186:189], 0
	s_waitcnt lgkmcnt(1)
	v_mfma_f32_16x16x32_bf16 v[84:87], v[150:153], v[194:197], 0
	v_mfma_f32_16x16x32_bf16 v[80:83], v[158:161], v[194:197], 0
	v_mfma_f32_16x16x32_bf16 v[124:127], v[154:157], v[170:173], v[124:127]
	v_mfma_f32_16x16x32_bf16 v[120:123], v[162:165], v[170:173], v[120:123]
	v_mfma_f32_16x16x32_bf16 v[116:119], v[154:157], v[182:185], v[116:119]
	v_mfma_f32_16x16x32_bf16 v[112:115], v[162:165], v[182:185], v[112:115]
	v_mfma_f32_16x16x32_bf16 v[100:103], v[154:157], v[190:193], v[100:103]
	v_mfma_f32_16x16x32_bf16 v[96:99], v[162:165], v[190:193], v[96:99]
	s_waitcnt lgkmcnt(0)
	v_mfma_f32_16x16x32_bf16 v[84:87], v[154:157], v[198:201], v[84:87]
	v_mfma_f32_16x16x32_bf16 v[80:83], v[162:165], v[198:201], v[80:83]
	s_barrier
	s_add_i32 s81, s71, s45
	s_add_u32 s86, s38, s8
	s_addc_u32 s87, s39, s9
	s_mov_b32 m0, s81
	ds_read_b128 v[202:205], v149
	ds_read_b128 v[206:209], v149 offset:1024
	ds_read_b128 v[210:213], v149 offset:2048
	ds_read_b128 v[214:217], v149 offset:3072
	global_load_lds_dwordx4 v132, s[38:39]
	s_add_i32 m0, s81, 0x2000
	s_nop 0
	global_load_lds_dwordx4 v128, s[38:39]
	s_barrier
	s_waitcnt lgkmcnt(3)
	v_mfma_f32_16x16x32_bf16 v[108:111], v[202:205], v[166:169], 0
	s_waitcnt lgkmcnt(1)
	v_mfma_f32_16x16x32_bf16 v[104:107], v[210:213], v[166:169], 0
	v_mfma_f32_16x16x32_bf16 v[92:95], v[202:205], v[174:177], 0
	v_mfma_f32_16x16x32_bf16 v[88:91], v[210:213], v[174:177], 0
	v_mfma_f32_16x16x32_bf16 v[76:79], v[202:205], v[186:189], 0
	v_mfma_f32_16x16x32_bf16 v[72:75], v[210:213], v[186:189], 0
	v_mfma_f32_16x16x32_bf16 v[68:71], v[202:205], v[194:197], 0
	v_mfma_f32_16x16x32_bf16 v[64:67], v[210:213], v[194:197], 0
	v_mfma_f32_16x16x32_bf16 v[108:111], v[206:209], v[170:173], v[108:111]
	s_waitcnt lgkmcnt(0)
	v_mfma_f32_16x16x32_bf16 v[104:107], v[214:217], v[170:173], v[104:107]
	v_mfma_f32_16x16x32_bf16 v[92:95], v[206:209], v[182:185], v[92:95]
	v_mfma_f32_16x16x32_bf16 v[88:91], v[214:217], v[182:185], v[88:91]
	v_mfma_f32_16x16x32_bf16 v[76:79], v[206:209], v[190:193], v[76:79]
	v_mfma_f32_16x16x32_bf16 v[72:75], v[214:217], v[190:193], v[72:75]
	v_mfma_f32_16x16x32_bf16 v[68:71], v[206:209], v[198:201], v[68:71]
	v_mfma_f32_16x16x32_bf16 v[64:67], v[214:217], v[198:201], v[64:67]
	s_mov_b32 m0, s13
	s_add_u32 s88, s40, s8
	s_addc_u32 s89, s41, s9
	s_barrier
	ds_read_b128 v[166:169], v148 offset:16384
	ds_read_b128 v[170:173], v148 offset:17408
	ds_read_b128 v[174:177], v148 offset:18432
	ds_read_b128 v[182:185], v148 offset:19456
	ds_read_b128 v[186:189], v148 offset:20480
	ds_read_b128 v[190:193], v148 offset:21504
	ds_read_b128 v[194:197], v148 offset:22528
	ds_read_b128 v[198:201], v148 offset:23552
	global_load_lds_dwordx4 v134, s[40:41]
	s_mov_b32 m0, s48
	s_nop 0
	global_load_lds_dwordx4 v130, s[40:41]
	s_barrier
	s_waitcnt lgkmcnt(7)
	v_mfma_f32_16x16x32_bf16 v[60:63], v[150:153], v[166:169], 0
	v_mfma_f32_16x16x32_bf16 v[56:59], v[158:161], v[166:169], 0
	s_waitcnt lgkmcnt(5)
	v_mfma_f32_16x16x32_bf16 v[52:55], v[150:153], v[174:177], 0
	v_mfma_f32_16x16x32_bf16 v[48:51], v[158:161], v[174:177], 0
	s_waitcnt lgkmcnt(3)
	v_mfma_f32_16x16x32_bf16 v[36:39], v[150:153], v[186:189], 0
	v_mfma_f32_16x16x32_bf16 v[32:35], v[158:161], v[186:189], 0
	s_waitcnt lgkmcnt(1)
	v_mfma_f32_16x16x32_bf16 v[20:23], v[150:153], v[194:197], 0
	v_mfma_f32_16x16x32_bf16 v[16:19], v[158:161], v[194:197], 0
	v_mfma_f32_16x16x32_bf16 v[60:63], v[154:157], v[170:173], v[60:63]
	v_mfma_f32_16x16x32_bf16 v[56:59], v[162:165], v[170:173], v[56:59]
	v_mfma_f32_16x16x32_bf16 v[52:55], v[154:157], v[182:185], v[52:55]
	v_mfma_f32_16x16x32_bf16 v[48:51], v[162:165], v[182:185], v[48:51]
	v_mfma_f32_16x16x32_bf16 v[36:39], v[154:157], v[190:193], v[36:39]
	v_mfma_f32_16x16x32_bf16 v[32:35], v[162:165], v[190:193], v[32:35]
	s_waitcnt lgkmcnt(0)
	v_mfma_f32_16x16x32_bf16 v[20:23], v[154:157], v[198:201], v[20:23]
	v_mfma_f32_16x16x32_bf16 v[16:19], v[162:165], v[198:201], v[16:19]
	s_barrier
; #define PG8_STAGE(bufoff, gbase, voff) do { _Pragma("unroll") for (int _i = 0; _i < 2; ++_i) \
;         __builtin_amdgcn_global_load_lds((const unsigned*)((const char*)(gbase) + (voff)[_i]), (LAS unsigned*)(lds + (bufoff) + ldsw + _i * 8192), 16, 0, 0); } while (0)
; #define PG8_LDA(dst, b, h) do { _Pragma("unroll") for (int m = 0; m < 4; ++m) _Pragma("unroll") for (int k = 0; k < 2; ++k) dst[m][k] = *(const LAS bf16x8*)(lds + PG8_SA(b, h) + aoff + m * 2048 + k * 1024); } while (0)
; #define PG8_LDB(dst, b, h) do { _Pragma("unroll") for (int n = 0; n < 2; ++n) _Pragma("unroll") for (int k = 0; k < 2; ++k) dst[n][k] = *(const LAS bf16x8*)(lds + PG8_SB(b, h) + boff + n * 2048 + k * 1024); } while (0)
; #define PG8_MMA(ai, bj, At, Bt) do { __builtin_amdgcn_s_setprio(1); _Pragma("unroll") for (int m = 0; m < 4; ++m) _Pragma("unroll") for (int n = 0; n < 2; ++n) _Pragma("unroll") for (int k = 0; k < 2; ++k) \
;         acc[ai][bj][m][n] = __builtin_amdgcn_mfma_f32_16x16x32_bf16(Bt[n][k], At[m][k], acc[ai][bj][m][n], 0, 0, 0); __builtin_amdgcn_s_setprio(0); } while (0)
; #define PG8_WAIT_V(n) asm volatile("s_waitcnt vmcnt(" #n ")" ::: "memory")
; #define PG8_WAIT_L(n) asm volatile("s_waitcnt lgkmcnt(" #n ")" ::: "memory")
; #define PG8_BAR __builtin_amdgcn_s_barrier()
; #define PG8_SCHED __builtin_amdgcn_sched_barrier(0)
; template <class Epi>
; DI void gemm_phase(LAS unsigned char* lds, const Gemm g, const StaticOrder& S, const Epi& E) {
;     ...
;             PG8_STAGE(PG8_SB(0, 1), b2 + hstep, voffB);
;             PG8_WAIT_V(6); PG8_BAR; PG8_MMA(1, 1, At, B1); PG8_BAR;
;             PG8_LDB(B0, 1, 0); PG8_SCHED; PG8_LDA(At, 1, 0); PG8_STAGE(PG8_SA(0, 1), a2 + hstep, voffA);
;             PG8_WAIT_L(8); PG8_BAR; PG8_WAIT_L(0); PG8_MMA(0, 0, At, B0); PG8_BAR; PG8_SCHED;
;             PG8_LDB(B1, 1, 1); PG8_STAGE(PG8_SB(1, 0), b3, voffB);
;             PG8_BAR; PG8_WAIT_L(0); PG8_MMA(0, 1, At, B1); PG8_BAR;
;             PG8_LDA(At, 1, 1); PG8_STAGE(PG8_SA(1, 0), a3, voffA);
	s_add_u32 s82, s38, 0x40000
	s_addc_u32 s83, s39, 0
	s_add_i32 s81, s72, s45
	s_mov_b32 m0, s81
	s_nop 0
	global_load_lds_dwordx4 v132, s[82:83]
	s_add_i32 m0, s81, 0x2000
	s_nop 0
	global_load_lds_dwordx4 v128, s[82:83]
	s_waitcnt vmcnt(6)
	s_barrier
	v_mfma_f32_16x16x32_bf16 v[44:47], v[202:205], v[166:169], 0
	v_mfma_f32_16x16x32_bf16 v[40:43], v[210:213], v[166:169], 0
	v_mfma_f32_16x16x32_bf16 v[28:31], v[202:205], v[174:177], 0
	v_mfma_f32_16x16x32_bf16 v[24:27], v[210:213], v[174:177], 0
	v_mfma_f32_16x16x32_bf16 v[12:15], v[202:205], v[186:189], 0
	v_mfma_f32_16x16x32_bf16 v[8:11], v[210:213], v[186:189], 0
	v_mfma_f32_16x16x32_bf16 v[4:7], v[202:205], v[194:197], 0
	v_mfma_f32_16x16x32_bf16 v[0:3], v[210:213], v[194:197], 0
	v_mfma_f32_16x16x32_bf16 v[44:47], v[206:209], v[170:173], v[44:47]
	v_mfma_f32_16x16x32_bf16 v[40:43], v[214:217], v[170:173], v[40:43]
	v_mfma_f32_16x16x32_bf16 v[28:31], v[206:209], v[182:185], v[28:31]
	v_mfma_f32_16x16x32_bf16 v[24:27], v[214:217], v[182:185], v[24:27]
	v_mfma_f32_16x16x32_bf16 v[12:15], v[206:209], v[190:193], v[12:15]
	v_mfma_f32_16x16x32_bf16 v[8:11], v[214:217], v[190:193], v[8:11]
	v_mfma_f32_16x16x32_bf16 v[4:7], v[206:209], v[198:201], v[4:7]
	v_mfma_f32_16x16x32_bf16 v[0:3], v[214:217], v[198:201], v[0:3]
	s_add_i32 s81, 0, 0x18000
	v_add_u32_e32 v162, s81, v145
	s_barrier
	ds_read_b128 v[150:153], v162
	ds_read_b128 v[154:157], v162 offset:1024
	ds_read_b128 v[158:161], v162 offset:2048
	ds_read_b128 v[162:165], v162 offset:3072
	s_add_u32 s40, s40, 0x40000
	s_addc_u32 s41, s41, 0
	s_mov_b32 m0, s49
	ds_read_b128 v[166:169], v148 offset:32768
	ds_read_b128 v[170:173], v148 offset:33792
	ds_read_b128 v[174:177], v148 offset:34816
	ds_read_b128 v[182:185], v148 offset:35840
	ds_read_b128 v[186:189], v148 offset:36864
	ds_read_b128 v[190:193], v148 offset:37888
	ds_read_b128 v[194:197], v148 offset:38912
	ds_read_b128 v[198:201], v148 offset:39936
	global_load_lds_dwordx4 v134, s[40:41]
	s_mov_b32 m0, s50
	s_nop 0
	global_load_lds_dwordx4 v130, s[40:41]
	s_waitcnt lgkmcnt(8)
	s_barrier
	s_waitcnt lgkmcnt(7)
	v_mfma_f32_16x16x32_bf16 v[124:127], v[150:153], v[166:169], v[124:127]
	v_mfma_f32_16x16x32_bf16 v[120:123], v[158:161], v[166:169], v[120:123]
	s_waitcnt lgkmcnt(5)
	v_mfma_f32_16x16x32_bf16 v[116:119], v[150:153], v[174:177], v[116:119]
	v_mfma_f32_16x16x32_bf16 v[112:115], v[158:161], v[174:177], v[112:115]
	s_waitcnt lgkmcnt(3)
	v_mfma_f32_16x16x32_bf16 v[100:103], v[150:153], v[186:189], v[100:103]
	v_mfma_f32_16x16x32_bf16 v[96:99], v[158:161], v[186:189], v[96:99]
	s_waitcnt lgkmcnt(1)
	v_mfma_f32_16x16x32_bf16 v[84:87], v[150:153], v[194:197], v[84:87]
	v_mfma_f32_16x16x32_bf16 v[80:83], v[158:161], v[194:197], v[80:83]
	v_mfma_f32_16x16x32_bf16 v[124:127], v[154:157], v[170:173], v[124:127]
	v_mfma_f32_16x16x32_bf16 v[120:123], v[162:165], v[170:173], v[120:123]
	v_mfma_f32_16x16x32_bf16 v[116:119], v[154:157], v[182:185], v[116:119]
	v_mfma_f32_16x16x32_bf16 v[112:115], v[162:165], v[182:185], v[112:115]
	v_mfma_f32_16x16x32_bf16 v[100:103], v[154:157], v[190:193], v[100:103]
	v_mfma_f32_16x16x32_bf16 v[96:99], v[162:165], v[190:193], v[96:99]
	s_waitcnt lgkmcnt(0)
	v_mfma_f32_16x16x32_bf16 v[84:87], v[154:157], v[198:201], v[84:87]
	v_mfma_f32_16x16x32_bf16 v[80:83], v[162:165], v[198:201], v[80:83]
	s_barrier
	s_add_i32 s40, 0, 0x1c000
	s_add_i32 s41, s81, s45
	v_add_u32_e32 v214, s40, v145
	s_mov_b32 m0, s41
	ds_read_b128 v[202:205], v214
	ds_read_b128 v[206:209], v214 offset:1024
	ds_read_b128 v[210:213], v214 offset:2048
	ds_read_b128 v[214:217], v214 offset:3072
	global_load_lds_dwordx4 v132, s[86:87]
	s_add_i32 m0, s41, 0x2000
	s_nop 0
	global_load_lds_dwordx4 v128, s[86:87]
	s_barrier
	s_waitcnt lgkmcnt(3)
	v_mfma_f32_16x16x32_bf16 v[108:111], v[202:205], v[166:169], v[108:111]
	s_waitcnt lgkmcnt(1)
	v_mfma_f32_16x16x32_bf16 v[104:107], v[210:213], v[166:169], v[104:107]
	v_mfma_f32_16x16x32_bf16 v[92:95], v[202:205], v[174:177], v[92:95]
	v_mfma_f32_16x16x32_bf16 v[88:91], v[210:213], v[174:177], v[88:91]
	v_mfma_f32_16x16x32_bf16 v[76:79], v[202:205], v[186:189], v[76:79]
	v_mfma_f32_16x16x32_bf16 v[72:75], v[210:213], v[186:189], v[72:75]
	v_mfma_f32_16x16x32_bf16 v[68:71], v[202:205], v[194:197], v[68:71]
	v_mfma_f32_16x16x32_bf16 v[64:67], v[210:213], v[194:197], v[64:67]
	v_mfma_f32_16x16x32_bf16 v[108:111], v[206:209], v[170:173], v[108:111]
	s_waitcnt lgkmcnt(0)
	v_mfma_f32_16x16x32_bf16 v[104:107], v[214:217], v[170:173], v[104:107]
	v_mfma_f32_16x16x32_bf16 v[92:95], v[206:209], v[182:185], v[92:95]
	v_mfma_f32_16x16x32_bf16 v[88:91], v[214:217], v[182:185], v[88:91]
	v_mfma_f32_16x16x32_bf16 v[76:79], v[206:209], v[190:193], v[76:79]
	v_mfma_f32_16x16x32_bf16 v[72:75], v[214:217], v[190:193], v[72:75]
	v_mfma_f32_16x16x32_bf16 v[68:71], v[206:209], v[198:201], v[68:71]
	v_mfma_f32_16x16x32_bf16 v[64:67], v[214:217], v[198:201], v[64:67]
	s_mov_b32 m0, s66
	s_barrier
	ds_read_b128 v[166:169], v148 offset:49152
	ds_read_b128 v[170:173], v148 offset:50176
	ds_read_b128 v[174:177], v148 offset:51200
	ds_read_b128 v[182:185], v148 offset:52224
	ds_read_b128 v[186:189], v148 offset:53248
	ds_read_b128 v[190:193], v148 offset:54272
	ds_read_b128 v[194:197], v148 offset:55296
	ds_read_b128 v[198:201], v148 offset:56320
	global_load_lds_dwordx4 v134, s[88:89]
	s_mov_b32 m0, s67
	s_nop 0
	global_load_lds_dwordx4 v130, s[88:89]
	s_barrier
; #define PG8_STAGE(bufoff, gbase, voff) do { _Pragma("unroll") for (int _i = 0; _i < 2; ++_i) \
;         __builtin_amdgcn_global_load_lds((const unsigned*)((const char*)(gbase) + (voff)[_i]), (LAS unsigned*)(lds + (bufoff) + ldsw + _i * 8192), 16, 0, 0); } while (0)
; #define PG8_LDA(dst, b, h) do { _Pragma("unroll") for (int m = 0; m < 4; ++m) _Pragma("unroll") for (int k = 0; k < 2; ++k) dst[m][k] = *(const LAS bf16x8*)(lds + PG8_SA(b, h) + aoff + m * 2048 + k * 1024); } while (0)
; #define PG8_LDB(dst, b, h) do { _Pragma("unroll") for (int n = 0; n < 2; ++n) _Pragma("unroll") for (int k = 0; k < 2; ++k) dst[n][k] = *(const LAS bf16x8*)(lds + PG8_SB(b, h) + boff + n * 2048 + k * 1024); } while (0)
; #define PG8_MMA(ai, bj, At, Bt) do { __builtin_amdgcn_s_setprio(1); _Pragma("unroll") for (int m = 0; m < 4; ++m) _Pragma("unroll") for (int n = 0; n < 2; ++n) _Pragma("unroll") for (int k = 0; k < 2; ++k) \
;         acc[ai][bj][m][n] = __builtin_amdgcn_mfma_f32_16x16x32_bf16(Bt[n][k], At[m][k], acc[ai][bj][m][n], 0, 0, 0); __builtin_amdgcn_s_setprio(0); } while (0)
; #define PG8_WAIT_V(n) asm volatile("s_waitcnt vmcnt(" #n ")" ::: "memory")
; #define PG8_WAIT_L(n) asm volatile("s_waitcnt lgkmcnt(" #n ")" ::: "memory")
; #define PG8_BAR __builtin_amdgcn_s_barrier()
; #define PG8_SCHED __builtin_amdgcn_sched_barrier(0)
; template <class Epi>
; DI void gemm_phase(LAS unsigned char* lds, const Gemm g, const StaticOrder& S, const Epi& E) {
;     ...
;         for (int t = 0; t < nt; t += 2) {
;             const bool last = (t == nt - 2);
;             const char* a1 = cA + (size_t)(t + 1) * kstep;
;             const char* a2 = last ? nA : cA + (size_t)(t + 2) * kstep; const char* b2 = last ? nB : cB + (size_t)(t + 2) * kstep;
;             const char* a3 = a2 + kstep; const char* b3 = b2 + kstep;
;             PG8_LDB(B0, 0, 0); PG8_SCHED; PG8_LDA(At, 0, 0); PG8_STAGE(PG8_SA(1, 1), a1 + hstep, voffA);
;             PG8_WAIT_L(8); PG8_BAR; PG8_WAIT_L(0); PG8_MMA(0, 0, At, B0); PG8_BAR; PG8_SCHED;
;             PG8_LDB(B1, 0, 1); PG8_STAGE(PG8_SB(0, 0), b2, voffB);
;     ...
;             PG8_LDA(At, 1, 1); PG8_STAGE(PG8_SA(1, 0), a3, voffA);
;             PG8_BAR; PG8_WAIT_L(0); PG8_MMA(1, 0, At, B0); PG8_BAR; PG8_SCHED;
;             PG8_STAGE(PG8_SB(1, 1), b3 + hstep, voffB);
;             PG8_WAIT_V(6); PG8_BAR; PG8_MMA(1, 1, At, B1); PG8_BAR;
	s_waitcnt lgkmcnt(7)
	v_mfma_f32_16x16x32_bf16 v[60:63], v[150:153], v[166:169], v[60:63]
	v_mfma_f32_16x16x32_bf16 v[56:59], v[158:161], v[166:169], v[56:59]
	s_waitcnt lgkmcnt(5)
	v_mfma_f32_16x16x32_bf16 v[52:55], v[150:153], v[174:177], v[52:55]
	v_mfma_f32_16x16x32_bf16 v[48:51], v[158:161], v[174:177], v[48:51]
	s_waitcnt lgkmcnt(3)
	v_mfma_f32_16x16x32_bf16 v[36:39], v[150:153], v[186:189], v[36:39]
	v_mfma_f32_16x16x32_bf16 v[32:35], v[158:161], v[186:189], v[32:35]
	s_waitcnt lgkmcnt(1)
	v_mfma_f32_16x16x32_bf16 v[20:23], v[150:153], v[194:197], v[20:23]
	v_mfma_f32_16x16x32_bf16 v[16:19], v[158:161], v[194:197], v[16:19]
	v_mfma_f32_16x16x32_bf16 v[60:63], v[154:157], v[170:173], v[60:63]
	v_mfma_f32_16x16x32_bf16 v[56:59], v[162:165], v[170:173], v[56:59]
	v_mfma_f32_16x16x32_bf16 v[52:55], v[154:157], v[182:185], v[52:55]
	v_mfma_f32_16x16x32_bf16 v[48:51], v[162:165], v[182:185], v[48:51]
	v_mfma_f32_16x16x32_bf16 v[36:39], v[154:157], v[190:193], v[36:39]
	v_mfma_f32_16x16x32_bf16 v[32:35], v[162:165], v[190:193], v[32:35]
	s_waitcnt lgkmcnt(0)
	v_mfma_f32_16x16x32_bf16 v[20:23], v[154:157], v[198:201], v[20:23]
	v_mfma_f32_16x16x32_bf16 v[16:19], v[162:165], v[198:201], v[16:19]
	s_barrier
	s_add_u32 s38, s38, 0x40080
	s_addc_u32 s39, s39, 0
	s_add_i32 s40, s40, s45
	s_mov_b32 m0, s40
	s_nop 0
	global_load_lds_dwordx4 v132, s[38:39]
	s_add_i32 m0, s40, 0x2000
	s_nop 0
	global_load_lds_dwordx4 v128, s[38:39]
	s_waitcnt vmcnt(6)
	s_barrier
	v_mfma_f32_16x16x32_bf16 v[44:47], v[202:205], v[166:169], v[44:47]
	v_mfma_f32_16x16x32_bf16 v[40:43], v[210:213], v[166:169], v[40:43]
	v_mfma_f32_16x16x32_bf16 v[28:31], v[202:205], v[174:177], v[28:31]
	v_mfma_f32_16x16x32_bf16 v[24:27], v[210:213], v[174:177], v[24:27]
	v_mfma_f32_16x16x32_bf16 v[12:15], v[202:205], v[186:189], v[12:15]
	v_mfma_f32_16x16x32_bf16 v[8:11], v[210:213], v[186:189], v[8:11]
	v_mfma_f32_16x16x32_bf16 v[4:7], v[202:205], v[194:197], v[4:7]
	v_mfma_f32_16x16x32_bf16 v[0:3], v[210:213], v[194:197], v[0:3]
	v_mfma_f32_16x16x32_bf16 v[44:47], v[206:209], v[170:173], v[44:47]
	v_mfma_f32_16x16x32_bf16 v[40:43], v[214:217], v[170:173], v[40:43]
	v_mfma_f32_16x16x32_bf16 v[28:31], v[206:209], v[182:185], v[28:31]
	v_mfma_f32_16x16x32_bf16 v[24:27], v[214:217], v[182:185], v[24:27]
	v_mfma_f32_16x16x32_bf16 v[12:15], v[206:209], v[190:193], v[12:15]
	v_mfma_f32_16x16x32_bf16 v[8:11], v[214:217], v[190:193], v[8:11]
	v_mfma_f32_16x16x32_bf16 v[4:7], v[206:209], v[198:201], v[4:7]
	v_mfma_f32_16x16x32_bf16 v[0:3], v[214:217], v[198:201], v[0:3]
	s_add_i32 s80, s80, 2
	s_add_u32 s24, s24, 0x100
	s_addc_u32 s25, s25, 0
	s_add_u32 s78, s78, 0x100
	s_addc_u32 s79, s79, 0
	s_cmp_gt_u32 s80, 13
	s_barrier
.LBB0_211:
	ds_read_b128 v[150:153], v147
	ds_read_b128 v[154:157], v147 offset:1024
	ds_read_b128 v[158:161], v147 offset:2048
	ds_read_b128 v[162:165], v147 offset:3072
	s_add_u32 s38, s24, 0xfffc0080
	s_addc_u32 s39, s25, -1
	s_cmp_eq_u32 s80, 12
	s_cselect_b32 s41, s17, s39
	s_cselect_b32 s40, s76, s38
	s_cselect_b32 s39, s15, s79
	s_cselect_b32 s38, s77, s78
	s_add_i32 m0, s13, 0xc000
	ds_read_b128 v[166:169], v148
	ds_read_b128 v[170:173], v148 offset:1024
	ds_read_b128 v[174:177], v148 offset:2048
	ds_read_b128 v[182:185], v148 offset:3072
	ds_read_b128 v[186:189], v148 offset:4096
	ds_read_b128 v[190:193], v148 offset:5120
	ds_read_b128 v[194:197], v148 offset:6144
	ds_read_b128 v[198:201], v148 offset:7168
	global_load_lds_dwordx4 v136, s[24:25]
	s_add_i32 m0, s13, 0xe000
	s_nop 0
	global_load_lds_dwordx4 v138, s[24:25]
	s_waitcnt lgkmcnt(8)
	s_barrier
	s_waitcnt lgkmcnt(7)
	v_mfma_f32_16x16x32_bf16 v[124:127], v[150:153], v[166:169], v[124:127]
	v_mfma_f32_16x16x32_bf16 v[120:123], v[158:161], v[166:169], v[120:123]
	s_waitcnt lgkmcnt(5)
	v_mfma_f32_16x16x32_bf16 v[116:119], v[150:153], v[174:177], v[116:119]
	v_mfma_f32_16x16x32_bf16 v[112:115], v[158:161], v[174:177], v[112:115]
	s_waitcnt lgkmcnt(3)
	v_mfma_f32_16x16x32_bf16 v[100:103], v[150:153], v[186:189], v[100:103]
	v_mfma_f32_16x16x32_bf16 v[96:99], v[158:161], v[186:189], v[96:99]
	s_waitcnt lgkmcnt(1)
	v_mfma_f32_16x16x32_bf16 v[84:87], v[150:153], v[194:197], v[84:87]
	v_mfma_f32_16x16x32_bf16 v[80:83], v[158:161], v[194:197], v[80:83]
	v_mfma_f32_16x16x32_bf16 v[124:127], v[154:157], v[170:173], v[124:127]
	v_mfma_f32_16x16x32_bf16 v[120:123], v[162:165], v[170:173], v[120:123]
	v_mfma_f32_16x16x32_bf16 v[116:119], v[154:157], v[182:185], v[116:119]
	v_mfma_f32_16x16x32_bf16 v[112:115], v[162:165], v[182:185], v[112:115]
	v_mfma_f32_16x16x32_bf16 v[100:103], v[154:157], v[190:193], v[100:103]
	v_mfma_f32_16x16x32_bf16 v[96:99], v[162:165], v[190:193], v[96:99]
	s_waitcnt lgkmcnt(0)
	v_mfma_f32_16x16x32_bf16 v[84:87], v[154:157], v[198:201], v[84:87]
	v_mfma_f32_16x16x32_bf16 v[80:83], v[162:165], v[198:201], v[80:83]
	s_barrier
	s_add_i32 s81, s71, s45
	s_add_u32 s86, s38, s8
	s_addc_u32 s87, s39, s9
	s_mov_b32 m0, s81
	ds_read_b128 v[202:205], v149
	ds_read_b128 v[206:209], v149 offset:1024
	ds_read_b128 v[210:213], v149 offset:2048
	ds_read_b128 v[214:217], v149 offset:3072
	global_load_lds_dwordx4 v132, s[38:39]
	s_add_i32 m0, s81, 0x2000
	s_nop 0
	global_load_lds_dwordx4 v128, s[38:39]
	s_barrier
; #define PG8_STAGE(bufoff, gbase, voff) do { _Pragma("unroll") for (int _i = 0; _i < 2; ++_i) \
;         __builtin_amdgcn_global_load_lds((const unsigned*)((const char*)(gbase) + (voff)[_i]), (LAS unsigned*)(lds + (bufoff) + ldsw + _i * 8192), 16, 0, 0); } while (0)
; #define PG8_LDA(dst, b, h) do { _Pragma("unroll") for (int m = 0; m < 4; ++m) _Pragma("unroll") for (int k = 0; k < 2; ++k) dst[m][k] = *(const LAS bf16x8*)(lds + PG8_SA(b, h) + aoff + m * 2048 + k * 1024); } while (0)
; #define PG8_LDB(dst, b, h) do { _Pragma("unroll") for (int n = 0; n < 2; ++n) _Pragma("unroll") for (int k = 0; k < 2; ++k) dst[n][k] = *(const LAS bf16x8*)(lds + PG8_SB(b, h) + boff + n * 2048 + k * 1024); } while (0)
; #define PG8_MMA(ai, bj, At, Bt) do { __builtin_amdgcn_s_setprio(1); _Pragma("unroll") for (int m = 0; m < 4; ++m) _Pragma("unroll") for (int n = 0; n < 2; ++n) _Pragma("unroll") for (int k = 0; k < 2; ++k) \
;         acc[ai][bj][m][n] = __builtin_amdgcn_mfma_f32_16x16x32_bf16(Bt[n][k], At[m][k], acc[ai][bj][m][n], 0, 0, 0); __builtin_amdgcn_s_setprio(0); } while (0)
; #define PG8_WAIT_V(n) asm volatile("s_waitcnt vmcnt(" #n ")" ::: "memory")
; #define PG8_WAIT_L(n) asm volatile("s_waitcnt lgkmcnt(" #n ")" ::: "memory")
; #define PG8_BAR __builtin_amdgcn_s_barrier()
; #define PG8_SCHED __builtin_amdgcn_sched_barrier(0)
; template <class Epi>
; DI void gemm_phase(LAS unsigned char* lds, const Gemm g, const StaticOrder& S, const Epi& E) {
;     ...
;             PG8_BAR; PG8_WAIT_L(0); PG8_MMA(0, 1, At, B1); PG8_BAR;
;             PG8_LDA(At, 0, 1); PG8_STAGE(PG8_SA(0, 0), a2, voffA);
;             PG8_BAR; PG8_WAIT_L(0); PG8_MMA(1, 0, At, B0); PG8_BAR; PG8_SCHED;
;             PG8_STAGE(PG8_SB(0, 1), b2 + hstep, voffB);
;             PG8_WAIT_V(6); PG8_BAR; PG8_MMA(1, 1, At, B1); PG8_BAR;
;             PG8_LDB(B0, 1, 0); PG8_SCHED; PG8_LDA(At, 1, 0); PG8_STAGE(PG8_SA(0, 1), a2 + hstep, voffA);
;             PG8_WAIT_L(8); PG8_BAR; PG8_WAIT_L(0); PG8_MMA(0, 0, At, B0); PG8_BAR; PG8_SCHED;
	s_waitcnt lgkmcnt(3)
	v_mfma_f32_16x16x32_bf16 v[108:111], v[202:205], v[166:169], v[108:111]
	s_waitcnt lgkmcnt(1)
	v_mfma_f32_16x16x32_bf16 v[104:107], v[210:213], v[166:169], v[104:107]
	v_mfma_f32_16x16x32_bf16 v[92:95], v[202:205], v[174:177], v[92:95]
	v_mfma_f32_16x16x32_bf16 v[88:91], v[210:213], v[174:177], v[88:91]
	v_mfma_f32_16x16x32_bf16 v[76:79], v[202:205], v[186:189], v[76:79]
	v_mfma_f32_16x16x32_bf16 v[72:75], v[210:213], v[186:189], v[72:75]
	v_mfma_f32_16x16x32_bf16 v[68:71], v[202:205], v[194:197], v[68:71]
	v_mfma_f32_16x16x32_bf16 v[64:67], v[210:213], v[194:197], v[64:67]
	v_mfma_f32_16x16x32_bf16 v[108:111], v[206:209], v[170:173], v[108:111]
	s_waitcnt lgkmcnt(0)
	v_mfma_f32_16x16x32_bf16 v[104:107], v[214:217], v[170:173], v[104:107]
	v_mfma_f32_16x16x32_bf16 v[92:95], v[206:209], v[182:185], v[92:95]
	v_mfma_f32_16x16x32_bf16 v[88:91], v[214:217], v[182:185], v[88:91]
	v_mfma_f32_16x16x32_bf16 v[76:79], v[206:209], v[190:193], v[76:79]
	v_mfma_f32_16x16x32_bf16 v[72:75], v[214:217], v[190:193], v[72:75]
	v_mfma_f32_16x16x32_bf16 v[68:71], v[206:209], v[198:201], v[68:71]
	v_mfma_f32_16x16x32_bf16 v[64:67], v[214:217], v[198:201], v[64:67]
	s_mov_b32 m0, s13
	s_add_u32 s88, s40, s8
	s_addc_u32 s89, s41, s9
	s_barrier
	ds_read_b128 v[166:169], v148 offset:16384
	ds_read_b128 v[170:173], v148 offset:17408
	ds_read_b128 v[174:177], v148 offset:18432
	ds_read_b128 v[182:185], v148 offset:19456
	ds_read_b128 v[186:189], v148 offset:20480
	ds_read_b128 v[190:193], v148 offset:21504
	ds_read_b128 v[194:197], v148 offset:22528
	ds_read_b128 v[198:201], v148 offset:23552
	global_load_lds_dwordx4 v134, s[40:41]
	s_mov_b32 m0, s48
	s_nop 0
	global_load_lds_dwordx4 v130, s[40:41]
	s_barrier
	s_waitcnt lgkmcnt(7)
	v_mfma_f32_16x16x32_bf16 v[60:63], v[150:153], v[166:169], v[60:63]
	v_mfma_f32_16x16x32_bf16 v[56:59], v[158:161], v[166:169], v[56:59]
	s_waitcnt lgkmcnt(5)
	v_mfma_f32_16x16x32_bf16 v[52:55], v[150:153], v[174:177], v[52:55]
	v_mfma_f32_16x16x32_bf16 v[48:51], v[158:161], v[174:177], v[48:51]
	s_waitcnt lgkmcnt(3)
	v_mfma_f32_16x16x32_bf16 v[36:39], v[150:153], v[186:189], v[36:39]
	v_mfma_f32_16x16x32_bf16 v[32:35], v[158:161], v[186:189], v[32:35]
	s_waitcnt lgkmcnt(1)
	v_mfma_f32_16x16x32_bf16 v[20:23], v[150:153], v[194:197], v[20:23]
	v_mfma_f32_16x16x32_bf16 v[16:19], v[158:161], v[194:197], v[16:19]
	v_mfma_f32_16x16x32_bf16 v[60:63], v[154:157], v[170:173], v[60:63]
	v_mfma_f32_16x16x32_bf16 v[56:59], v[162:165], v[170:173], v[56:59]
	v_mfma_f32_16x16x32_bf16 v[52:55], v[154:157], v[182:185], v[52:55]
	v_mfma_f32_16x16x32_bf16 v[48:51], v[162:165], v[182:185], v[48:51]
	v_mfma_f32_16x16x32_bf16 v[36:39], v[154:157], v[190:193], v[36:39]
	v_mfma_f32_16x16x32_bf16 v[32:35], v[162:165], v[190:193], v[32:35]
	s_waitcnt lgkmcnt(0)
	v_mfma_f32_16x16x32_bf16 v[20:23], v[154:157], v[198:201], v[20:23]
	v_mfma_f32_16x16x32_bf16 v[16:19], v[162:165], v[198:201], v[16:19]
	s_barrier
	s_add_u32 s82, s38, 0x40000
	s_addc_u32 s83, s39, 0
	s_add_i32 s81, s72, s45
	s_mov_b32 m0, s81
	s_nop 0
	global_load_lds_dwordx4 v132, s[82:83]
	s_add_i32 m0, s81, 0x2000
	s_nop 0
	global_load_lds_dwordx4 v128, s[82:83]
	s_waitcnt vmcnt(6)
	s_barrier
	v_mfma_f32_16x16x32_bf16 v[44:47], v[202:205], v[166:169], v[44:47]
	v_mfma_f32_16x16x32_bf16 v[40:43], v[210:213], v[166:169], v[40:43]
	v_mfma_f32_16x16x32_bf16 v[28:31], v[202:205], v[174:177], v[28:31]
	v_mfma_f32_16x16x32_bf16 v[24:27], v[210:213], v[174:177], v[24:27]
	v_mfma_f32_16x16x32_bf16 v[12:15], v[202:205], v[186:189], v[12:15]
	v_mfma_f32_16x16x32_bf16 v[8:11], v[210:213], v[186:189], v[8:11]
	v_mfma_f32_16x16x32_bf16 v[4:7], v[202:205], v[194:197], v[4:7]
	v_mfma_f32_16x16x32_bf16 v[0:3], v[210:213], v[194:197], v[0:3]
	v_mfma_f32_16x16x32_bf16 v[44:47], v[206:209], v[170:173], v[44:47]
	v_mfma_f32_16x16x32_bf16 v[40:43], v[214:217], v[170:173], v[40:43]
	v_mfma_f32_16x16x32_bf16 v[28:31], v[206:209], v[182:185], v[28:31]
	v_mfma_f32_16x16x32_bf16 v[24:27], v[214:217], v[182:185], v[24:27]
	v_mfma_f32_16x16x32_bf16 v[12:15], v[206:209], v[190:193], v[12:15]
	v_mfma_f32_16x16x32_bf16 v[8:11], v[214:217], v[190:193], v[8:11]
	v_mfma_f32_16x16x32_bf16 v[4:7], v[206:209], v[198:201], v[4:7]
	v_mfma_f32_16x16x32_bf16 v[0:3], v[214:217], v[198:201], v[0:3]
	s_add_i32 s81, 0, 0x18000
	v_add_u32_e32 v162, s81, v145
	s_barrier
	ds_read_b128 v[150:153], v162
	ds_read_b128 v[154:157], v162 offset:1024
	ds_read_b128 v[158:161], v162 offset:2048
	ds_read_b128 v[162:165], v162 offset:3072
	s_add_u32 s40, s40, 0x40000
	s_addc_u32 s41, s41, 0
	s_mov_b32 m0, s49
	ds_read_b128 v[166:169], v148 offset:32768
	ds_read_b128 v[170:173], v148 offset:33792
	ds_read_b128 v[174:177], v148 offset:34816
	ds_read_b128 v[182:185], v148 offset:35840
	ds_read_b128 v[186:189], v148 offset:36864
	ds_read_b128 v[190:193], v148 offset:37888
	ds_read_b128 v[194:197], v148 offset:38912
	ds_read_b128 v[198:201], v148 offset:39936
	global_load_lds_dwordx4 v134, s[40:41]
	s_mov_b32 m0, s50
	s_nop 0
	global_load_lds_dwordx4 v130, s[40:41]
	s_waitcnt lgkmcnt(8)
	s_barrier
; #define PG8_STAGE(bufoff, gbase, voff) do { _Pragma("unroll") for (int _i = 0; _i < 2; ++_i) \
;         __builtin_amdgcn_global_load_lds((const unsigned*)((const char*)(gbase) + (voff)[_i]), (LAS unsigned*)(lds + (bufoff) + ldsw + _i * 8192), 16, 0, 0); } while (0)
; #define PG8_LDA(dst, b, h) do { _Pragma("unroll") for (int m = 0; m < 4; ++m) _Pragma("unroll") for (int k = 0; k < 2; ++k) dst[m][k] = *(const LAS bf16x8*)(lds + PG8_SA(b, h) + aoff + m * 2048 + k * 1024); } while (0)
; #define PG8_LDB(dst, b, h) do { _Pragma("unroll") for (int n = 0; n < 2; ++n) _Pragma("unroll") for (int k = 0; k < 2; ++k) dst[n][k] = *(const LAS bf16x8*)(lds + PG8_SB(b, h) + boff + n * 2048 + k * 1024); } while (0)
; #define PG8_MMA(ai, bj, At, Bt) do { __builtin_amdgcn_s_setprio(1); _Pragma("unroll") for (int m = 0; m < 4; ++m) _Pragma("unroll") for (int n = 0; n < 2; ++n) _Pragma("unroll") for (int k = 0; k < 2; ++k) \
;         acc[ai][bj][m][n] = __builtin_amdgcn_mfma_f32_16x16x32_bf16(Bt[n][k], At[m][k], acc[ai][bj][m][n], 0, 0, 0); __builtin_amdgcn_s_setprio(0); } while (0)
; #define PG8_WAIT_V(n) asm volatile("s_waitcnt vmcnt(" #n ")" ::: "memory")
; #define PG8_WAIT_L(n) asm volatile("s_waitcnt lgkmcnt(" #n ")" ::: "memory")
; #define PG8_BAR __builtin_amdgcn_s_barrier()
; #define PG8_SCHED __builtin_amdgcn_sched_barrier(0)
; template <class Epi>
; DI void gemm_phase(LAS unsigned char* lds, const Gemm g, const StaticOrder& S, const Epi& E) {
;     ...
;             PG8_WAIT_L(8); PG8_BAR; PG8_WAIT_L(0); PG8_MMA(0, 0, At, B0); PG8_BAR; PG8_SCHED;
;             PG8_LDB(B1, 1, 1); PG8_STAGE(PG8_SB(1, 0), b3, voffB);
;             PG8_BAR; PG8_WAIT_L(0); PG8_MMA(0, 1, At, B1); PG8_BAR;
;             PG8_LDA(At, 1, 1); PG8_STAGE(PG8_SA(1, 0), a3, voffA);
;             PG8_BAR; PG8_WAIT_L(0); PG8_MMA(1, 0, At, B0); PG8_BAR; PG8_SCHED;
;             PG8_STAGE(PG8_SB(1, 1), b3 + hstep, voffB);
;             PG8_WAIT_V(6); PG8_BAR; PG8_MMA(1, 1, At, B1); PG8_BAR;
	s_waitcnt lgkmcnt(7)
	v_mfma_f32_16x16x32_bf16 v[124:127], v[150:153], v[166:169], v[124:127]
	v_mfma_f32_16x16x32_bf16 v[120:123], v[158:161], v[166:169], v[120:123]
	s_waitcnt lgkmcnt(5)
	v_mfma_f32_16x16x32_bf16 v[116:119], v[150:153], v[174:177], v[116:119]
	v_mfma_f32_16x16x32_bf16 v[112:115], v[158:161], v[174:177], v[112:115]
	s_waitcnt lgkmcnt(3)
	v_mfma_f32_16x16x32_bf16 v[100:103], v[150:153], v[186:189], v[100:103]
	v_mfma_f32_16x16x32_bf16 v[96:99], v[158:161], v[186:189], v[96:99]
	s_waitcnt lgkmcnt(1)
	v_mfma_f32_16x16x32_bf16 v[84:87], v[150:153], v[194:197], v[84:87]
	v_mfma_f32_16x16x32_bf16 v[80:83], v[158:161], v[194:197], v[80:83]
	v_mfma_f32_16x16x32_bf16 v[124:127], v[154:157], v[170:173], v[124:127]
	v_mfma_f32_16x16x32_bf16 v[120:123], v[162:165], v[170:173], v[120:123]
	v_mfma_f32_16x16x32_bf16 v[116:119], v[154:157], v[182:185], v[116:119]
	v_mfma_f32_16x16x32_bf16 v[112:115], v[162:165], v[182:185], v[112:115]
	v_mfma_f32_16x16x32_bf16 v[100:103], v[154:157], v[190:193], v[100:103]
	v_mfma_f32_16x16x32_bf16 v[96:99], v[162:165], v[190:193], v[96:99]
	s_waitcnt lgkmcnt(0)
	v_mfma_f32_16x16x32_bf16 v[84:87], v[154:157], v[198:201], v[84:87]
	v_mfma_f32_16x16x32_bf16 v[80:83], v[162:165], v[198:201], v[80:83]
	s_barrier
	s_add_i32 s40, 0, 0x1c000
	s_add_i32 s41, s81, s45
	v_add_u32_e32 v214, s40, v145
	s_mov_b32 m0, s41
	ds_read_b128 v[202:205], v214
	ds_read_b128 v[206:209], v214 offset:1024
	ds_read_b128 v[210:213], v214 offset:2048
	ds_read_b128 v[214:217], v214 offset:3072
	global_load_lds_dwordx4 v132, s[86:87]
	s_add_i32 m0, s41, 0x2000
	s_nop 0
	global_load_lds_dwordx4 v128, s[86:87]
	s_barrier
	s_waitcnt lgkmcnt(3)
	v_mfma_f32_16x16x32_bf16 v[108:111], v[202:205], v[166:169], v[108:111]
	s_waitcnt lgkmcnt(1)
	v_mfma_f32_16x16x32_bf16 v[104:107], v[210:213], v[166:169], v[104:107]
	v_mfma_f32_16x16x32_bf16 v[92:95], v[202:205], v[174:177], v[92:95]
	v_mfma_f32_16x16x32_bf16 v[88:91], v[210:213], v[174:177], v[88:91]
	v_mfma_f32_16x16x32_bf16 v[76:79], v[202:205], v[186:189], v[76:79]
	v_mfma_f32_16x16x32_bf16 v[72:75], v[210:213], v[186:189], v[72:75]
	v_mfma_f32_16x16x32_bf16 v[68:71], v[202:205], v[194:197], v[68:71]
	v_mfma_f32_16x16x32_bf16 v[64:67], v[210:213], v[194:197], v[64:67]
	v_mfma_f32_16x16x32_bf16 v[108:111], v[206:209], v[170:173], v[108:111]
	s_waitcnt lgkmcnt(0)
	v_mfma_f32_16x16x32_bf16 v[104:107], v[214:217], v[170:173], v[104:107]
	v_mfma_f32_16x16x32_bf16 v[92:95], v[206:209], v[182:185], v[92:95]
	v_mfma_f32_16x16x32_bf16 v[88:91], v[214:217], v[182:185], v[88:91]
	v_mfma_f32_16x16x32_bf16 v[76:79], v[206:209], v[190:193], v[76:79]
	v_mfma_f32_16x16x32_bf16 v[72:75], v[214:217], v[190:193], v[72:75]
	v_mfma_f32_16x16x32_bf16 v[68:71], v[206:209], v[198:201], v[68:71]
	v_mfma_f32_16x16x32_bf16 v[64:67], v[214:217], v[198:201], v[64:67]
	s_mov_b32 m0, s66
	s_barrier
	ds_read_b128 v[166:169], v148 offset:49152
	ds_read_b128 v[170:173], v148 offset:50176
	ds_read_b128 v[174:177], v148 offset:51200
	ds_read_b128 v[182:185], v148 offset:52224
	ds_read_b128 v[186:189], v148 offset:53248
	ds_read_b128 v[190:193], v148 offset:54272
	ds_read_b128 v[194:197], v148 offset:55296
	ds_read_b128 v[198:201], v148 offset:56320
	global_load_lds_dwordx4 v134, s[88:89]
	s_mov_b32 m0, s67
	s_nop 0
	global_load_lds_dwordx4 v130, s[88:89]
	s_barrier
	s_waitcnt lgkmcnt(7)
	v_mfma_f32_16x16x32_bf16 v[60:63], v[150:153], v[166:169], v[60:63]
	v_mfma_f32_16x16x32_bf16 v[56:59], v[158:161], v[166:169], v[56:59]
	s_waitcnt lgkmcnt(5)
	v_mfma_f32_16x16x32_bf16 v[52:55], v[150:153], v[174:177], v[52:55]
	v_mfma_f32_16x16x32_bf16 v[48:51], v[158:161], v[174:177], v[48:51]
	s_waitcnt lgkmcnt(3)
	v_mfma_f32_16x16x32_bf16 v[36:39], v[150:153], v[186:189], v[36:39]
	v_mfma_f32_16x16x32_bf16 v[32:35], v[158:161], v[186:189], v[32:35]
	s_waitcnt lgkmcnt(1)
	v_mfma_f32_16x16x32_bf16 v[20:23], v[150:153], v[194:197], v[20:23]
	v_mfma_f32_16x16x32_bf16 v[16:19], v[158:161], v[194:197], v[16:19]
	v_mfma_f32_16x16x32_bf16 v[60:63], v[154:157], v[170:173], v[60:63]
	v_mfma_f32_16x16x32_bf16 v[56:59], v[162:165], v[170:173], v[56:59]
	v_mfma_f32_16x16x32_bf16 v[52:55], v[154:157], v[182:185], v[52:55]
	v_mfma_f32_16x16x32_bf16 v[48:51], v[162:165], v[182:185], v[48:51]
	v_mfma_f32_16x16x32_bf16 v[36:39], v[154:157], v[190:193], v[36:39]
	v_mfma_f32_16x16x32_bf16 v[32:35], v[162:165], v[190:193], v[32:35]
	s_waitcnt lgkmcnt(0)
	v_mfma_f32_16x16x32_bf16 v[20:23], v[154:157], v[198:201], v[20:23]
	v_mfma_f32_16x16x32_bf16 v[16:19], v[162:165], v[198:201], v[16:19]
	s_barrier
	s_add_u32 s38, s38, 0x40080
	s_addc_u32 s39, s39, 0
	s_add_i32 s40, s40, s45
	s_mov_b32 m0, s40
	s_nop 0
	global_load_lds_dwordx4 v132, s[38:39]
	s_add_i32 m0, s40, 0x2000
	s_nop 0
	global_load_lds_dwordx4 v128, s[38:39]
	s_waitcnt vmcnt(6)
	s_barrier
; DI unsigned pk2(float a, float b) { f32x2 v = {a, b}; bf16x2_t r = __builtin_convertvector(v, bf16x2_t); return __builtin_bit_cast(unsigned, r); }
; #define PG8_MMA(ai, bj, At, Bt) do { __builtin_amdgcn_s_setprio(1); _Pragma("unroll") for (int m = 0; m < 4; ++m) _Pragma("unroll") for (int n = 0; n < 2; ++n) _Pragma("unroll") for (int k = 0; k < 2; ++k) \
;         acc[ai][bj][m][n] = __builtin_amdgcn_mfma_f32_16x16x32_bf16(Bt[n][k], At[m][k], acc[ai][bj][m][n], 0, 0, 0); __builtin_amdgcn_s_setprio(0); } while (0)
; #define PG8_WAIT_V(n) asm volatile("s_waitcnt vmcnt(" #n ")" ::: "memory")
; #define PG8_BAR __builtin_amdgcn_s_barrier()
; template <class Epi>
; DI void gemm_phase(LAS unsigned char* lds, const Gemm g, const StaticOrder& S, const Epi& E) {
;     ...
;             PG8_WAIT_V(6); PG8_BAR; PG8_MMA(1, 1, At, B1); PG8_BAR;
;         }
;         E(acc, cur, wr, wc, fr, fq);
;         if (!has_next) break;
; #pragma unroll
;         for (int a = 0; a < 2; ++a)
; #pragma unroll
;             for (int b = 0; b < 2; ++b)
; #pragma unroll
;                 for (int m = 0; m < 4; ++m)
; #pragma unroll
;                     for (int n = 0; n < 2; ++n) acc[a][b][m][n] = (f32x4){0.f, 0.f, 0.f, 0.f};
;         cur = nxt; cA = nA; cB = nB; ++ui;
;     }
;     PG8_WAIT_V(0);
;     if (wr == 0) PG8_BAR;
;     PG8_BAR;
;     DI void operator()(const f32x4 (&acc)[2][2][4][2], const Unit& u, int wr, int wc, int fr, int fq) const {
;         const bool first = u.pn < 6; const int ldc = first ? P1W : P2W;
;         const int row0 = u.pm * BM + wr * 64 + fr, col0 = (first ? u.pn : u.pn - 6) * BM + wc * 32 + 8 * fq;
;         bf16_t* O = first ? O1 : O2;
; #pragma unroll
;         for (int ai = 0; ai < 2; ++ai)
; #pragma unroll
;             for (int m = 0; m < 4; ++m) { bf16_t* rowp = O + (size_t)(row0 + ai * HALF + m * 16) * ldc + col0;
; #pragma unroll
;                 for (int bj = 0; bj < 2; ++bj) { const f32x4 v0 = acc[ai][bj][m][0], v1 = acc[ai][bj][m][1];
;                     u32x4 w; w.x = pk2(v0[0], v0[1]); w.y = pk2(v0[2], v0[3]); w.z = pk2(v1[0], v1[1]); w.w = pk2(v1[2], v1[3]);
;                     *(u32x4*)(rowp + bj * HALF) = w; } }
	v_mfma_f32_16x16x32_bf16 v[44:47], v[202:205], v[166:169], v[44:47]
	v_mfma_f32_16x16x32_bf16 v[40:43], v[210:213], v[166:169], v[40:43]
	v_mfma_f32_16x16x32_bf16 v[28:31], v[202:205], v[174:177], v[28:31]
	v_mfma_f32_16x16x32_bf16 v[24:27], v[210:213], v[174:177], v[24:27]
	v_mfma_f32_16x16x32_bf16 v[12:15], v[202:205], v[186:189], v[12:15]
	v_mfma_f32_16x16x32_bf16 v[8:11], v[210:213], v[186:189], v[8:11]
	v_mfma_f32_16x16x32_bf16 v[4:7], v[202:205], v[194:197], v[4:7]
	v_mfma_f32_16x16x32_bf16 v[0:3], v[210:213], v[194:197], v[0:3]
	v_mfma_f32_16x16x32_bf16 v[44:47], v[206:209], v[170:173], v[44:47]
	v_mfma_f32_16x16x32_bf16 v[40:43], v[214:217], v[170:173], v[40:43]
	v_mfma_f32_16x16x32_bf16 v[28:31], v[206:209], v[182:185], v[28:31]
	v_mfma_f32_16x16x32_bf16 v[24:27], v[214:217], v[182:185], v[24:27]
	v_mfma_f32_16x16x32_bf16 v[12:15], v[206:209], v[190:193], v[12:15]
	v_mfma_f32_16x16x32_bf16 v[8:11], v[214:217], v[190:193], v[8:11]
	v_mfma_f32_16x16x32_bf16 v[4:7], v[206:209], v[198:201], v[4:7]
	v_mfma_f32_16x16x32_bf16 v[0:3], v[214:217], v[198:201], v[0:3]
	s_add_i32 s80, s80, 2
	s_add_u32 s24, s24, 0x100
	s_addc_u32 s25, s25, 0
	s_add_u32 s78, s78, 0x100
	s_addc_u32 s79, s79, 0
	s_cmp_gt_u32 s80, 13
	s_barrier
	s_cbranch_scc0 .LBB0_211
	s_lshl_b32 s15, s75, 8
	s_add_i32 s17, s15, 0xfffffa00
	s_cmp_lt_i32 s75, 6
	v_lshl_add_u32 v154, s12, 8, v144
	s_cselect_b32 s12, s15, s17
	v_or_b32_e32 v150, s12, v146
	s_cselect_b32 s12, s74, 0x1ef76000
	s_cselect_b32 s38, s73, 0xa00
	s_add_u32 s24, s30, s12
	s_addc_u32 s25, s31, 0
	v_ashrrev_i32_e32 v151, 31, v150
	v_lshl_add_u64 v[150:151], v[150:151], 1, s[24:25]
	v_mad_i64_i32 v[152:153], s[24:25], s38, v154, 0
	v_cvt_pk_bf16_f32 v108, v108, v109
	v_cvt_pk_bf16_f32 v109, v110, v111
	v_cvt_pk_bf16_f32 v110, v104, v105
	v_or_b32_e32 v104, 16, v154
	v_lshl_add_u64 v[152:153], v[152:153], 1, v[150:151]
	v_cvt_pk_bf16_f32 v111, v106, v107
	v_mad_i64_i32 v[104:105], s[24:25], s38, v104, 0
	v_cvt_pk_bf16_f32 v92, v92, v93
	v_cvt_pk_bf16_f32 v93, v94, v95
	v_cvt_pk_bf16_f32 v94, v88, v89
	v_or_b32_e32 v88, 32, v154
	v_cvt_pk_bf16_f32 v124, v124, v125
	v_cvt_pk_bf16_f32 v125, v126, v127
	v_cvt_pk_bf16_f32 v126, v120, v121
	v_cvt_pk_bf16_f32 v127, v122, v123
	global_store_dwordx4 v[152:153], v[108:111], off offset:256
	v_cvt_pk_bf16_f32 v95, v90, v91
	v_mad_i64_i32 v[88:89], s[24:25], s38, v88, 0
	v_lshl_add_u64 v[108:109], v[104:105], 1, v[150:151]
	v_cvt_pk_bf16_f32 v76, v76, v77
	v_cvt_pk_bf16_f32 v77, v78, v79
	v_cvt_pk_bf16_f32 v78, v72, v73
	v_or_b32_e32 v72, 48, v154
	v_cvt_pk_bf16_f32 v68, v68, v69
	v_cvt_pk_bf16_f32 v69, v70, v71
	v_cvt_pk_bf16_f32 v70, v64, v65
	v_add_u32_e32 v64, 0x80, v154
	global_store_dwordx4 v[152:153], v[124:127], off
	v_cvt_pk_bf16_f32 v104, v116, v117
	v_cvt_pk_bf16_f32 v105, v118, v119
	v_cvt_pk_bf16_f32 v106, v112, v113
	v_cvt_pk_bf16_f32 v107, v114, v115
	global_store_dwordx4 v[108:109], v[92:95], off offset:256
	v_cvt_pk_bf16_f32 v79, v74, v75
	v_mad_i64_i32 v[72:73], s[24:25], s38, v72, 0
	v_lshl_add_u64 v[92:93], v[88:89], 1, v[150:151]
	v_mad_i64_i32 v[64:65], s[24:25], s38, v64, 0
	v_cvt_pk_bf16_f32 v44, v44, v45
	v_cvt_pk_bf16_f32 v45, v46, v47
	v_cvt_pk_bf16_f32 v46, v40, v41
	v_add_u32_e32 v40, 0x90, v154
	global_store_dwordx4 v[108:109], v[104:107], off
	v_cvt_pk_bf16_f32 v88, v100, v101
	v_cvt_pk_bf16_f32 v89, v102, v103
	v_cvt_pk_bf16_f32 v90, v96, v97
	v_cvt_pk_bf16_f32 v91, v98, v99
	global_store_dwordx4 v[92:93], v[76:79], off offset:256
	v_cvt_pk_bf16_f32 v74, v80, v81
	v_cvt_pk_bf16_f32 v75, v82, v83
	v_lshl_add_u64 v[76:77], v[72:73], 1, v[150:151]
	v_cvt_pk_bf16_f32 v72, v84, v85
	v_cvt_pk_bf16_f32 v73, v86, v87
	v_cvt_pk_bf16_f32 v71, v66, v67
	v_lshl_add_u64 v[64:65], v[64:65], 1, v[150:151]
	v_cvt_pk_bf16_f32 v47, v42, v43
	v_mad_i64_i32 v[40:41], s[24:25], s38, v40, 0
	v_cvt_pk_bf16_f32 v28, v28, v29
	v_cvt_pk_bf16_f32 v29, v30, v31
	v_cvt_pk_bf16_f32 v30, v24, v25
	v_add_u32_e32 v24, 0xa0, v154
	global_store_dwordx4 v[92:93], v[88:91], off
	global_store_dwordx4 v[76:77], v[72:75], off
	global_store_dwordx4 v[76:77], v[68:71], off offset:256
	v_cvt_pk_bf16_f32 v60, v60, v61
	v_cvt_pk_bf16_f32 v61, v62, v63
	v_cvt_pk_bf16_f32 v62, v56, v57
	v_cvt_pk_bf16_f32 v63, v58, v59
	global_store_dwordx4 v[64:65], v[44:47], off offset:256
	v_cvt_pk_bf16_f32 v31, v26, v27
	v_mad_i64_i32 v[24:25], s[24:25], s38, v24, 0
	v_lshl_add_u64 v[44:45], v[40:41], 1, v[150:151]
	v_cvt_pk_bf16_f32 v12, v12, v13
	v_cvt_pk_bf16_f32 v13, v14, v15
	v_cvt_pk_bf16_f32 v14, v8, v9
	v_add_u32_e32 v8, 0xb0, v154
	global_store_dwordx4 v[64:65], v[60:63], off
	v_cvt_pk_bf16_f32 v40, v52, v53
	v_cvt_pk_bf16_f32 v41, v54, v55
	v_cvt_pk_bf16_f32 v42, v48, v49
	v_cvt_pk_bf16_f32 v43, v50, v51
	global_store_dwordx4 v[44:45], v[28:31], off offset:256
	v_cvt_pk_bf16_f32 v15, v10, v11
	v_mad_i64_i32 v[8:9], s[24:25], s38, v8, 0
	v_lshl_add_u64 v[28:29], v[24:25], 1, v[150:151]
	global_store_dwordx4 v[44:45], v[40:43], off
	v_cvt_pk_bf16_f32 v24, v36, v37
	v_cvt_pk_bf16_f32 v25, v38, v39
	v_cvt_pk_bf16_f32 v26, v32, v33
	v_cvt_pk_bf16_f32 v27, v34, v35
	global_store_dwordx4 v[28:29], v[12:15], off offset:256
	v_cvt_pk_bf16_f32 v10, v16, v17
	v_cvt_pk_bf16_f32 v11, v18, v19
	v_lshl_add_u64 v[12:13], v[8:9], 1, v[150:151]
	v_cvt_pk_bf16_f32 v8, v20, v21
	v_cvt_pk_bf16_f32 v9, v22, v23
	v_cvt_pk_bf16_f32 v4, v4, v5
	v_cvt_pk_bf16_f32 v5, v6, v7
	v_cvt_pk_bf16_f32 v6, v0, v1
	v_cvt_pk_bf16_f32 v7, v2, v3
	s_and_b64 vcc, exec, s[4:5]
	s_mov_b32 s75, s14
	s_mov_b32 s12, s16
	s_mov_b64 s[38:39], s[22:23]
	s_mov_b64 s[24:25], s[18:19]
	global_store_dwordx4 v[28:29], v[24:27], off
	global_store_dwordx4 v[12:13], v[8:11], off
	global_store_dwordx4 v[12:13], v[4:7], off offset:256
	s_cbranch_vccz .LBB0_208
	s_waitcnt vmcnt(0)
	s_cmpk_gt_u32 s42, 0xff
	s_cbranch_scc1 .LBB0_215
	s_barrier

; #define PG8_STAGE(bufoff, gbase, voff) do { _Pragma("unroll") for (int _i = 0; _i < 2; ++_i) \
;         __builtin_amdgcn_global_load_lds((const unsigned*)((const char*)(gbase) + (voff)[_i]), (LAS unsigned*)(lds + (bufoff) + ldsw + _i * 8192), 16, 0, 0); } while (0)
; #define PG8_LDA(dst, b, h) do { _Pragma("unroll") for (int m = 0; m < 4; ++m) _Pragma("unroll") for (int k = 0; k < 2; ++k) dst[m][k] = *(const LAS bf16x8*)(lds + PG8_SA(b, h) + aoff + m * 2048 + k * 1024); } while (0)
; #define PG8_LDB(dst, b, h) do { _Pragma("unroll") for (int n = 0; n < 2; ++n) _Pragma("unroll") for (int k = 0; k < 2; ++k) dst[n][k] = *(const LAS bf16x8*)(lds + PG8_SB(b, h) + boff + n * 2048 + k * 1024); } while (0)
; #define PG8_MMA(ai, bj, At, Bt) do { __builtin_amdgcn_s_setprio(1); _Pragma("unroll") for (int m = 0; m < 4; ++m) _Pragma("unroll") for (int n = 0; n < 2; ++n) _Pragma("unroll") for (int k = 0; k < 2; ++k) \
;         acc[ai][bj][m][n] = __builtin_amdgcn_mfma_f32_16x16x32_bf16(Bt[n][k], At[m][k], acc[ai][bj][m][n], 0, 0, 0); __builtin_amdgcn_s_setprio(0); } while (0)
; #define PG8_WAIT_L(n) asm volatile("s_waitcnt lgkmcnt(" #n ")" ::: "memory")
; #define PG8_BAR __builtin_amdgcn_s_barrier()
; template <class Epi>
; DI void gemm_phase(LAS unsigned char* lds, const Gemm g, const StaticOrder& S, const Epi& E) {
;     ...
;         const bool has_next = S.next(ui + 1, nxt);
;         const char* nA = has_next ? (const char*)g.A + (size_t)nxt.pm * tstep : cA; const char* nB = has_next ? (const char*)g.Bt + (size_t)nxt.pn * tstep : cB;
;         for (int t = 0; t < nt; t += 2) {
;             const bool last = (t == nt - 2);
;             const char* a1 = cA + (size_t)(t + 1) * kstep;
;             const char* a2 = last ? nA : cA + (size_t)(t + 2) * kstep; const char* b2 = last ? nB : cB + (size_t)(t + 2) * kstep;
;             const char* a3 = a2 + kstep; const char* b3 = b2 + kstep;
;             PG8_LDB(B0, 0, 0); PG8_SCHED; PG8_LDA(At, 0, 0); PG8_STAGE(PG8_SA(1, 1), a1 + hstep, voffA);
;             PG8_WAIT_L(8); PG8_BAR; PG8_WAIT_L(0); PG8_MMA(0, 0, At, B0); PG8_BAR; PG8_SCHED;
;             PG8_LDB(B1, 0, 1); PG8_STAGE(PG8_SB(0, 0), b2, voffB);
;             PG8_BAR; PG8_WAIT_L(0); PG8_MMA(0, 1, At, B1); PG8_BAR;
;             PG8_LDA(At, 0, 1); PG8_STAGE(PG8_SA(0, 0), a2, voffA);
;             PG8_BAR; PG8_WAIT_L(0); PG8_MMA(1, 0, At, B0); PG8_BAR; PG8_SCHED;
.LBB0_723:
	s_ashr_i32 s39, s38, 31
	v_cmp_lt_i64_e32 vcc, s[40:41], v[156:157]
	s_lshl_b64 s[40:41], s[38:39], 19
	s_add_u32 s40, s54, s40
	s_addc_u32 s41, s55, s41
	s_and_b64 s[42:43], vcc, exec
	s_cselect_b32 s39, s41, s47
	s_cselect_b32 s73, s40, s46
	s_ashr_i32 s25, s24, 31
	s_lshl_b64 s[42:43], s[24:25], 19
	s_add_u32 s42, s56, s42
	s_addc_u32 s43, s57, s43
	s_and_b64 s[50:51], vcc, exec
	s_cselect_b32 s25, s43, s49
	s_cselect_b32 s74, s42, s48
	s_add_u32 s46, s46, 0x40080
	s_addc_u32 s47, s47, 0
	s_add_u32 s75, s48, 0x100
	s_addc_u32 s76, s49, 0
	s_mov_b32 s77, -2
	ds_read_b128 v[128:131], v165
	ds_read_b128 v[132:135], v165 offset:1024
	ds_read_b128 v[136:139], v165 offset:2048
	ds_read_b128 v[140:143], v165 offset:3072
	s_add_u32 s48, s46, 0xfffc0080
	s_addc_u32 s49, s47, -1
	s_cmp_eq_u32 s77, 12
	s_cselect_b32 s51, s39, s49
	s_cselect_b32 s50, s73, s48
	s_cselect_b32 s49, s25, s76
	s_cselect_b32 s48, s74, s75
	s_add_i32 m0, s45, 0xc000
	ds_read_b128 v[168:171], v166
	ds_read_b128 v[172:175], v166 offset:1024
	ds_read_b128 v[176:179], v166 offset:2048
	ds_read_b128 v[182:185], v166 offset:3072
	ds_read_b128 v[186:189], v166 offset:4096
	ds_read_b128 v[190:193], v166 offset:5120
	ds_read_b128 v[194:197], v166 offset:6144
	ds_read_b128 v[198:201], v166 offset:7168
	global_load_lds_dwordx4 v152, s[46:47]
	s_add_i32 m0, s45, 0xe000
	s_nop 0
	global_load_lds_dwordx4 v154, s[46:47]
	s_waitcnt lgkmcnt(8)
	s_barrier
	s_waitcnt lgkmcnt(7)
	v_mfma_f32_16x16x32_bf16 v[124:127], v[128:131], v[168:171], 0
	v_mfma_f32_16x16x32_bf16 v[120:123], v[136:139], v[168:171], 0
	s_waitcnt lgkmcnt(5)
	v_mfma_f32_16x16x32_bf16 v[108:111], v[128:131], v[176:179], 0
	v_mfma_f32_16x16x32_bf16 v[104:107], v[136:139], v[176:179], 0
	s_waitcnt lgkmcnt(3)
	v_mfma_f32_16x16x32_bf16 v[92:95], v[128:131], v[186:189], 0
	v_mfma_f32_16x16x32_bf16 v[88:91], v[136:139], v[186:189], 0
	s_waitcnt lgkmcnt(1)
	v_mfma_f32_16x16x32_bf16 v[76:79], v[128:131], v[194:197], 0
	v_mfma_f32_16x16x32_bf16 v[72:75], v[136:139], v[194:197], 0
	v_mfma_f32_16x16x32_bf16 v[124:127], v[132:135], v[172:175], v[124:127]
	v_mfma_f32_16x16x32_bf16 v[120:123], v[140:143], v[172:175], v[120:123]
	v_mfma_f32_16x16x32_bf16 v[108:111], v[132:135], v[182:185], v[108:111]
	v_mfma_f32_16x16x32_bf16 v[104:107], v[140:143], v[182:185], v[104:107]
	v_mfma_f32_16x16x32_bf16 v[92:95], v[132:135], v[190:193], v[92:95]
	v_mfma_f32_16x16x32_bf16 v[88:91], v[140:143], v[190:193], v[88:91]
	s_waitcnt lgkmcnt(0)
	v_mfma_f32_16x16x32_bf16 v[76:79], v[132:135], v[198:201], v[76:79]
	v_mfma_f32_16x16x32_bf16 v[72:75], v[140:143], v[198:201], v[72:75]
	s_barrier
	s_add_i32 s78, s70, s58
	s_add_u32 s86, s48, s12
	s_addc_u32 s87, s49, s13
	s_mov_b32 m0, s78
	ds_read_b128 v[202:205], v167
	ds_read_b128 v[206:209], v167 offset:1024
	ds_read_b128 v[210:213], v167 offset:2048
	ds_read_b128 v[214:217], v167 offset:3072
	global_load_lds_dwordx4 v146, s[48:49]
	s_add_i32 m0, s78, 0x2000
	s_nop 0
	global_load_lds_dwordx4 v150, s[48:49]
	s_barrier
	s_waitcnt lgkmcnt(3)
	v_mfma_f32_16x16x32_bf16 v[116:119], v[202:205], v[168:171], 0
	s_waitcnt lgkmcnt(1)
	v_mfma_f32_16x16x32_bf16 v[112:115], v[210:213], v[168:171], 0
	v_mfma_f32_16x16x32_bf16 v[100:103], v[202:205], v[176:179], 0
	v_mfma_f32_16x16x32_bf16 v[96:99], v[210:213], v[176:179], 0
	v_mfma_f32_16x16x32_bf16 v[84:87], v[202:205], v[186:189], 0
	v_mfma_f32_16x16x32_bf16 v[80:83], v[210:213], v[186:189], 0
	v_mfma_f32_16x16x32_bf16 v[68:71], v[202:205], v[194:197], 0
	v_mfma_f32_16x16x32_bf16 v[64:67], v[210:213], v[194:197], 0
	v_mfma_f32_16x16x32_bf16 v[116:119], v[206:209], v[172:175], v[116:119]
	s_waitcnt lgkmcnt(0)
	v_mfma_f32_16x16x32_bf16 v[112:115], v[214:217], v[172:175], v[112:115]
	v_mfma_f32_16x16x32_bf16 v[100:103], v[206:209], v[182:185], v[100:103]
	v_mfma_f32_16x16x32_bf16 v[96:99], v[214:217], v[182:185], v[96:99]
	v_mfma_f32_16x16x32_bf16 v[84:87], v[206:209], v[190:193], v[84:87]
	v_mfma_f32_16x16x32_bf16 v[80:83], v[214:217], v[190:193], v[80:83]
	v_mfma_f32_16x16x32_bf16 v[68:71], v[206:209], v[198:201], v[68:71]
	v_mfma_f32_16x16x32_bf16 v[64:67], v[214:217], v[198:201], v[64:67]
	s_mov_b32 m0, s45
	s_add_u32 s88, s50, s12
	s_addc_u32 s89, s51, s13
	s_barrier
	ds_read_b128 v[168:171], v166 offset:16384
	ds_read_b128 v[172:175], v166 offset:17408
	ds_read_b128 v[176:179], v166 offset:18432
	ds_read_b128 v[182:185], v166 offset:19456
	ds_read_b128 v[186:189], v166 offset:20480
	ds_read_b128 v[190:193], v166 offset:21504
	ds_read_b128 v[194:197], v166 offset:22528
	ds_read_b128 v[198:201], v166 offset:23552
	global_load_lds_dwordx4 v144, s[50:51]
	s_mov_b32 m0, s59
	s_nop 0
	global_load_lds_dwordx4 v148, s[50:51]
	s_barrier
	s_waitcnt lgkmcnt(7)
	v_mfma_f32_16x16x32_bf16 v[60:63], v[128:131], v[168:171], 0
	v_mfma_f32_16x16x32_bf16 v[56:59], v[136:139], v[168:171], 0
	s_waitcnt lgkmcnt(5)
	v_mfma_f32_16x16x32_bf16 v[44:47], v[128:131], v[176:179], 0
	v_mfma_f32_16x16x32_bf16 v[40:43], v[136:139], v[176:179], 0
	s_waitcnt lgkmcnt(3)
	v_mfma_f32_16x16x32_bf16 v[28:31], v[128:131], v[186:189], 0
	v_mfma_f32_16x16x32_bf16 v[24:27], v[136:139], v[186:189], 0
	s_waitcnt lgkmcnt(1)
	v_mfma_f32_16x16x32_bf16 v[12:15], v[128:131], v[194:197], 0
	v_mfma_f32_16x16x32_bf16 v[8:11], v[136:139], v[194:197], 0
	v_mfma_f32_16x16x32_bf16 v[60:63], v[132:135], v[172:175], v[60:63]
	v_mfma_f32_16x16x32_bf16 v[56:59], v[140:143], v[172:175], v[56:59]
	v_mfma_f32_16x16x32_bf16 v[44:47], v[132:135], v[182:185], v[44:47]
	v_mfma_f32_16x16x32_bf16 v[40:43], v[140:143], v[182:185], v[40:43]
	v_mfma_f32_16x16x32_bf16 v[28:31], v[132:135], v[190:193], v[28:31]
	v_mfma_f32_16x16x32_bf16 v[24:27], v[140:143], v[190:193], v[24:27]
	s_waitcnt lgkmcnt(0)
	v_mfma_f32_16x16x32_bf16 v[12:15], v[132:135], v[198:201], v[12:15]
	v_mfma_f32_16x16x32_bf16 v[8:11], v[140:143], v[198:201], v[8:11]
	s_barrier
; #define PG8_STAGE(bufoff, gbase, voff) do { _Pragma("unroll") for (int _i = 0; _i < 2; ++_i) \
;         __builtin_amdgcn_global_load_lds((const unsigned*)((const char*)(gbase) + (voff)[_i]), (LAS unsigned*)(lds + (bufoff) + ldsw + _i * 8192), 16, 0, 0); } while (0)
; #define PG8_LDA(dst, b, h) do { _Pragma("unroll") for (int m = 0; m < 4; ++m) _Pragma("unroll") for (int k = 0; k < 2; ++k) dst[m][k] = *(const LAS bf16x8*)(lds + PG8_SA(b, h) + aoff + m * 2048 + k * 1024); } while (0)
; #define PG8_LDB(dst, b, h) do { _Pragma("unroll") for (int n = 0; n < 2; ++n) _Pragma("unroll") for (int k = 0; k < 2; ++k) dst[n][k] = *(const LAS bf16x8*)(lds + PG8_SB(b, h) + boff + n * 2048 + k * 1024); } while (0)
; #define PG8_MMA(ai, bj, At, Bt) do { __builtin_amdgcn_s_setprio(1); _Pragma("unroll") for (int m = 0; m < 4; ++m) _Pragma("unroll") for (int n = 0; n < 2; ++n) _Pragma("unroll") for (int k = 0; k < 2; ++k) \
;         acc[ai][bj][m][n] = __builtin_amdgcn_mfma_f32_16x16x32_bf16(Bt[n][k], At[m][k], acc[ai][bj][m][n], 0, 0, 0); __builtin_amdgcn_s_setprio(0); } while (0)
; #define PG8_WAIT_V(n) asm volatile("s_waitcnt vmcnt(" #n ")" ::: "memory")
; #define PG8_WAIT_L(n) asm volatile("s_waitcnt lgkmcnt(" #n ")" ::: "memory")
; #define PG8_BAR __builtin_amdgcn_s_barrier()
; #define PG8_SCHED __builtin_amdgcn_sched_barrier(0)
; template <class Epi>
; DI void gemm_phase(LAS unsigned char* lds, const Gemm g, const StaticOrder& S, const Epi& E) {
;     ...
;             PG8_STAGE(PG8_SB(0, 1), b2 + hstep, voffB);
;             PG8_WAIT_V(6); PG8_BAR; PG8_MMA(1, 1, At, B1); PG8_BAR;
;             PG8_LDB(B0, 1, 0); PG8_SCHED; PG8_LDA(At, 1, 0); PG8_STAGE(PG8_SA(0, 1), a2 + hstep, voffA);
;             PG8_WAIT_L(8); PG8_BAR; PG8_WAIT_L(0); PG8_MMA(0, 0, At, B0); PG8_BAR; PG8_SCHED;
;             PG8_LDB(B1, 1, 1); PG8_STAGE(PG8_SB(1, 0), b3, voffB);
;             PG8_BAR; PG8_WAIT_L(0); PG8_MMA(0, 1, At, B1); PG8_BAR;
;             PG8_LDA(At, 1, 1); PG8_STAGE(PG8_SA(1, 0), a3, voffA);
	s_add_u32 s78, s48, 0x40000
	s_addc_u32 s79, s49, 0
	s_add_i32 s80, s71, s58
	s_mov_b32 m0, s80
	s_nop 0
	global_load_lds_dwordx4 v146, s[78:79]
	s_add_i32 m0, s80, 0x2000
	s_nop 0
	global_load_lds_dwordx4 v150, s[78:79]
	s_lshl_b32 s84, s44, 20
	s_lshl_b32 s85, s72, 10
	s_add_u32 s84, s84, s85
	s_add_i32 s85, s77, 2
	s_lshl_b32 s85, s85, 13
	s_add_u32 s84, s84, s85
	s_add_u32 s84, s36, s84
	s_addc_u32 s85, s37, 0
	s_waitcnt vmcnt(6)
	global_load_dword v249, v248, s[84:85]
	s_barrier
	v_mfma_f32_16x16x32_bf16 v[52:55], v[202:205], v[168:171], 0
	v_mfma_f32_16x16x32_bf16 v[48:51], v[210:213], v[168:171], 0
	v_mfma_f32_16x16x32_bf16 v[36:39], v[202:205], v[176:179], 0
	v_mfma_f32_16x16x32_bf16 v[32:35], v[210:213], v[176:179], 0
	v_mfma_f32_16x16x32_bf16 v[20:23], v[202:205], v[186:189], 0
	v_mfma_f32_16x16x32_bf16 v[16:19], v[210:213], v[186:189], 0
	v_mfma_f32_16x16x32_bf16 v[4:7], v[202:205], v[194:197], 0
	v_mfma_f32_16x16x32_bf16 v[0:3], v[210:213], v[194:197], 0
	v_mfma_f32_16x16x32_bf16 v[52:55], v[206:209], v[172:175], v[52:55]
	v_mfma_f32_16x16x32_bf16 v[48:51], v[214:217], v[172:175], v[48:51]
	v_mfma_f32_16x16x32_bf16 v[36:39], v[206:209], v[182:185], v[36:39]
	v_mfma_f32_16x16x32_bf16 v[32:35], v[214:217], v[182:185], v[32:35]
	v_mfma_f32_16x16x32_bf16 v[20:23], v[206:209], v[190:193], v[20:23]
	v_mfma_f32_16x16x32_bf16 v[16:19], v[214:217], v[190:193], v[16:19]
	v_mfma_f32_16x16x32_bf16 v[4:7], v[206:209], v[198:201], v[4:7]
	v_mfma_f32_16x16x32_bf16 v[0:3], v[214:217], v[198:201], v[0:3]
	s_add_i32 s78, 0, 0x18000
	v_add_u32_e32 v140, s78, v163
	s_barrier
	ds_read_b128 v[128:131], v140
	ds_read_b128 v[132:135], v140 offset:1024
	ds_read_b128 v[136:139], v140 offset:2048
	ds_read_b128 v[140:143], v140 offset:3072
	s_add_u32 s50, s50, 0x40000
	s_addc_u32 s51, s51, 0
	s_mov_b32 m0, s60
	ds_read_b128 v[168:171], v166 offset:32768
	ds_read_b128 v[172:175], v166 offset:33792
	ds_read_b128 v[176:179], v166 offset:34816
	ds_read_b128 v[182:185], v166 offset:35840
	ds_read_b128 v[186:189], v166 offset:36864
	ds_read_b128 v[190:193], v166 offset:37888
	ds_read_b128 v[194:197], v166 offset:38912
	ds_read_b128 v[198:201], v166 offset:39936
	global_load_lds_dwordx4 v144, s[50:51]
	s_mov_b32 m0, s61
	s_nop 0
	global_load_lds_dwordx4 v148, s[50:51]
	s_waitcnt lgkmcnt(8)
	s_barrier
	s_waitcnt lgkmcnt(7)
	v_mfma_f32_16x16x32_bf16 v[124:127], v[128:131], v[168:171], v[124:127]
	v_mfma_f32_16x16x32_bf16 v[120:123], v[136:139], v[168:171], v[120:123]
	s_waitcnt lgkmcnt(5)
	v_mfma_f32_16x16x32_bf16 v[108:111], v[128:131], v[176:179], v[108:111]
	v_mfma_f32_16x16x32_bf16 v[104:107], v[136:139], v[176:179], v[104:107]
	s_waitcnt lgkmcnt(3)
	v_mfma_f32_16x16x32_bf16 v[92:95], v[128:131], v[186:189], v[92:95]
	v_mfma_f32_16x16x32_bf16 v[88:91], v[136:139], v[186:189], v[88:91]
	s_waitcnt lgkmcnt(1)
	v_mfma_f32_16x16x32_bf16 v[76:79], v[128:131], v[194:197], v[76:79]
	v_mfma_f32_16x16x32_bf16 v[72:75], v[136:139], v[194:197], v[72:75]
	v_mfma_f32_16x16x32_bf16 v[124:127], v[132:135], v[172:175], v[124:127]
	v_mfma_f32_16x16x32_bf16 v[120:123], v[140:143], v[172:175], v[120:123]
	v_mfma_f32_16x16x32_bf16 v[108:111], v[132:135], v[182:185], v[108:111]
	v_mfma_f32_16x16x32_bf16 v[104:107], v[140:143], v[182:185], v[104:107]
	v_mfma_f32_16x16x32_bf16 v[92:95], v[132:135], v[190:193], v[92:95]
	v_mfma_f32_16x16x32_bf16 v[88:91], v[140:143], v[190:193], v[88:91]
	s_waitcnt lgkmcnt(0)
	v_mfma_f32_16x16x32_bf16 v[76:79], v[132:135], v[198:201], v[76:79]
	v_mfma_f32_16x16x32_bf16 v[72:75], v[140:143], v[198:201], v[72:75]
	s_barrier
	s_add_i32 s50, 0, 0x1c000
	s_add_i32 s51, s78, s58
	v_add_u32_e32 v214, s50, v163
	s_mov_b32 m0, s51
	ds_read_b128 v[202:205], v214
	ds_read_b128 v[206:209], v214 offset:1024
	ds_read_b128 v[210:213], v214 offset:2048
	ds_read_b128 v[214:217], v214 offset:3072
	global_load_lds_dwordx4 v146, s[86:87]
	s_add_i32 m0, s51, 0x2000
	s_nop 0
	global_load_lds_dwordx4 v150, s[86:87]
	s_barrier
	s_waitcnt lgkmcnt(3)
	v_mfma_f32_16x16x32_bf16 v[116:119], v[202:205], v[168:171], v[116:119]
	s_waitcnt lgkmcnt(1)
	v_mfma_f32_16x16x32_bf16 v[112:115], v[210:213], v[168:171], v[112:115]
	v_mfma_f32_16x16x32_bf16 v[100:103], v[202:205], v[176:179], v[100:103]
	v_mfma_f32_16x16x32_bf16 v[96:99], v[210:213], v[176:179], v[96:99]
	v_mfma_f32_16x16x32_bf16 v[84:87], v[202:205], v[186:189], v[84:87]
	v_mfma_f32_16x16x32_bf16 v[80:83], v[210:213], v[186:189], v[80:83]
	v_mfma_f32_16x16x32_bf16 v[68:71], v[202:205], v[194:197], v[68:71]
	v_mfma_f32_16x16x32_bf16 v[64:67], v[210:213], v[194:197], v[64:67]
	v_mfma_f32_16x16x32_bf16 v[116:119], v[206:209], v[172:175], v[116:119]
	s_waitcnt lgkmcnt(0)
	v_mfma_f32_16x16x32_bf16 v[112:115], v[214:217], v[172:175], v[112:115]
	v_mfma_f32_16x16x32_bf16 v[100:103], v[206:209], v[182:185], v[100:103]
	v_mfma_f32_16x16x32_bf16 v[96:99], v[214:217], v[182:185], v[96:99]
	v_mfma_f32_16x16x32_bf16 v[84:87], v[206:209], v[190:193], v[84:87]
	v_mfma_f32_16x16x32_bf16 v[80:83], v[214:217], v[190:193], v[80:83]
	v_mfma_f32_16x16x32_bf16 v[68:71], v[206:209], v[198:201], v[68:71]
	v_mfma_f32_16x16x32_bf16 v[64:67], v[214:217], v[198:201], v[64:67]
	s_mov_b32 m0, s65
	s_barrier
	ds_read_b128 v[168:171], v166 offset:49152
	ds_read_b128 v[172:175], v166 offset:50176
	ds_read_b128 v[176:179], v166 offset:51200
	ds_read_b128 v[182:185], v166 offset:52224
	ds_read_b128 v[186:189], v166 offset:53248
	ds_read_b128 v[190:193], v166 offset:54272
	ds_read_b128 v[194:197], v166 offset:55296
	ds_read_b128 v[198:201], v166 offset:56320
	global_load_lds_dwordx4 v144, s[88:89]
	s_mov_b32 m0, s66
	s_nop 0
	global_load_lds_dwordx4 v148, s[88:89]
	s_barrier
; #define PG8_STAGE(bufoff, gbase, voff) do { _Pragma("unroll") for (int _i = 0; _i < 2; ++_i) \
;         __builtin_amdgcn_global_load_lds((const unsigned*)((const char*)(gbase) + (voff)[_i]), (LAS unsigned*)(lds + (bufoff) + ldsw + _i * 8192), 16, 0, 0); } while (0)
; #define PG8_LDA(dst, b, h) do { _Pragma("unroll") for (int m = 0; m < 4; ++m) _Pragma("unroll") for (int k = 0; k < 2; ++k) dst[m][k] = *(const LAS bf16x8*)(lds + PG8_SA(b, h) + aoff + m * 2048 + k * 1024); } while (0)
; #define PG8_LDB(dst, b, h) do { _Pragma("unroll") for (int n = 0; n < 2; ++n) _Pragma("unroll") for (int k = 0; k < 2; ++k) dst[n][k] = *(const LAS bf16x8*)(lds + PG8_SB(b, h) + boff + n * 2048 + k * 1024); } while (0)
; #define PG8_MMA(ai, bj, At, Bt) do { __builtin_amdgcn_s_setprio(1); _Pragma("unroll") for (int m = 0; m < 4; ++m) _Pragma("unroll") for (int n = 0; n < 2; ++n) _Pragma("unroll") for (int k = 0; k < 2; ++k) \
;         acc[ai][bj][m][n] = __builtin_amdgcn_mfma_f32_16x16x32_bf16(Bt[n][k], At[m][k], acc[ai][bj][m][n], 0, 0, 0); __builtin_amdgcn_s_setprio(0); } while (0)
; #define PG8_WAIT_V(n) asm volatile("s_waitcnt vmcnt(" #n ")" ::: "memory")
; #define PG8_WAIT_L(n) asm volatile("s_waitcnt lgkmcnt(" #n ")" ::: "memory")
; #define PG8_BAR __builtin_amdgcn_s_barrier()
; #define PG8_SCHED __builtin_amdgcn_sched_barrier(0)
; template <class Epi>
; DI void gemm_phase(LAS unsigned char* lds, const Gemm g, const StaticOrder& S, const Epi& E) {
;     ...
;         for (int t = 0; t < nt; t += 2) {
;             const bool last = (t == nt - 2);
;             const char* a1 = cA + (size_t)(t + 1) * kstep;
;             const char* a2 = last ? nA : cA + (size_t)(t + 2) * kstep; const char* b2 = last ? nB : cB + (size_t)(t + 2) * kstep;
;             const char* a3 = a2 + kstep; const char* b3 = b2 + kstep;
;             PG8_LDB(B0, 0, 0); PG8_SCHED; PG8_LDA(At, 0, 0); PG8_STAGE(PG8_SA(1, 1), a1 + hstep, voffA);
;             PG8_WAIT_L(8); PG8_BAR; PG8_WAIT_L(0); PG8_MMA(0, 0, At, B0); PG8_BAR; PG8_SCHED;
;             PG8_LDB(B1, 0, 1); PG8_STAGE(PG8_SB(0, 0), b2, voffB);
;     ...
;             PG8_LDA(At, 1, 1); PG8_STAGE(PG8_SA(1, 0), a3, voffA);
;             PG8_BAR; PG8_WAIT_L(0); PG8_MMA(1, 0, At, B0); PG8_BAR; PG8_SCHED;
;             PG8_STAGE(PG8_SB(1, 1), b3 + hstep, voffB);
;             PG8_WAIT_V(6); PG8_BAR; PG8_MMA(1, 1, At, B1); PG8_BAR;
	s_waitcnt lgkmcnt(7)
	v_mfma_f32_16x16x32_bf16 v[60:63], v[128:131], v[168:171], v[60:63]
	v_mfma_f32_16x16x32_bf16 v[56:59], v[136:139], v[168:171], v[56:59]
	s_waitcnt lgkmcnt(5)
	v_mfma_f32_16x16x32_bf16 v[44:47], v[128:131], v[176:179], v[44:47]
	v_mfma_f32_16x16x32_bf16 v[40:43], v[136:139], v[176:179], v[40:43]
	s_waitcnt lgkmcnt(3)
	v_mfma_f32_16x16x32_bf16 v[28:31], v[128:131], v[186:189], v[28:31]
	v_mfma_f32_16x16x32_bf16 v[24:27], v[136:139], v[186:189], v[24:27]
	s_waitcnt lgkmcnt(1)
	v_mfma_f32_16x16x32_bf16 v[12:15], v[128:131], v[194:197], v[12:15]
	v_mfma_f32_16x16x32_bf16 v[8:11], v[136:139], v[194:197], v[8:11]
	v_mfma_f32_16x16x32_bf16 v[60:63], v[132:135], v[172:175], v[60:63]
	v_mfma_f32_16x16x32_bf16 v[56:59], v[140:143], v[172:175], v[56:59]
	v_mfma_f32_16x16x32_bf16 v[44:47], v[132:135], v[182:185], v[44:47]
	v_mfma_f32_16x16x32_bf16 v[40:43], v[140:143], v[182:185], v[40:43]
	v_mfma_f32_16x16x32_bf16 v[28:31], v[132:135], v[190:193], v[28:31]
	v_mfma_f32_16x16x32_bf16 v[24:27], v[140:143], v[190:193], v[24:27]
	s_waitcnt lgkmcnt(0)
	v_mfma_f32_16x16x32_bf16 v[12:15], v[132:135], v[198:201], v[12:15]
	v_mfma_f32_16x16x32_bf16 v[8:11], v[140:143], v[198:201], v[8:11]
	s_barrier
	s_add_u32 s48, s48, 0x40080
	s_addc_u32 s49, s49, 0
	s_add_i32 s50, s50, s58
	s_mov_b32 m0, s50
	s_nop 0
	global_load_lds_dwordx4 v146, s[48:49]
	s_add_i32 m0, s50, 0x2000
	s_nop 0
	global_load_lds_dwordx4 v150, s[48:49]
	s_waitcnt vmcnt(6)
	s_barrier
	v_mfma_f32_16x16x32_bf16 v[52:55], v[202:205], v[168:171], v[52:55]
	v_mfma_f32_16x16x32_bf16 v[48:51], v[210:213], v[168:171], v[48:51]
	v_mfma_f32_16x16x32_bf16 v[36:39], v[202:205], v[176:179], v[36:39]
	v_mfma_f32_16x16x32_bf16 v[32:35], v[210:213], v[176:179], v[32:35]
	v_mfma_f32_16x16x32_bf16 v[20:23], v[202:205], v[186:189], v[20:23]
	v_mfma_f32_16x16x32_bf16 v[16:19], v[210:213], v[186:189], v[16:19]
	v_mfma_f32_16x16x32_bf16 v[4:7], v[202:205], v[194:197], v[4:7]
	v_mfma_f32_16x16x32_bf16 v[0:3], v[210:213], v[194:197], v[0:3]
	v_mfma_f32_16x16x32_bf16 v[52:55], v[206:209], v[172:175], v[52:55]
	v_mfma_f32_16x16x32_bf16 v[48:51], v[214:217], v[172:175], v[48:51]
	v_mfma_f32_16x16x32_bf16 v[36:39], v[206:209], v[182:185], v[36:39]
	v_mfma_f32_16x16x32_bf16 v[32:35], v[214:217], v[182:185], v[32:35]
	v_mfma_f32_16x16x32_bf16 v[20:23], v[206:209], v[190:193], v[20:23]
	v_mfma_f32_16x16x32_bf16 v[16:19], v[214:217], v[190:193], v[16:19]
	v_mfma_f32_16x16x32_bf16 v[4:7], v[206:209], v[198:201], v[4:7]
	v_mfma_f32_16x16x32_bf16 v[0:3], v[214:217], v[198:201], v[0:3]
	s_add_i32 s77, s77, 2
	s_add_u32 s46, s46, 0x100
	s_addc_u32 s47, s47, 0
	s_add_u32 s75, s75, 0x100
	s_addc_u32 s76, s76, 0
	s_cmp_gt_u32 s77, 13
	s_barrier
.LBB0_724:
	ds_read_b128 v[128:131], v165
	ds_read_b128 v[132:135], v165 offset:1024
	ds_read_b128 v[136:139], v165 offset:2048
	ds_read_b128 v[140:143], v165 offset:3072
	s_add_u32 s48, s46, 0xfffc0080
	s_addc_u32 s49, s47, -1
	s_cmp_eq_u32 s77, 12
	s_cselect_b32 s51, s39, s49
	s_cselect_b32 s50, s73, s48
	s_cselect_b32 s49, s25, s76
	s_cselect_b32 s48, s74, s75
	s_add_i32 m0, s45, 0xc000
	ds_read_b128 v[168:171], v166
	ds_read_b128 v[172:175], v166 offset:1024
	ds_read_b128 v[176:179], v166 offset:2048
	ds_read_b128 v[182:185], v166 offset:3072
	ds_read_b128 v[186:189], v166 offset:4096
	ds_read_b128 v[190:193], v166 offset:5120
	ds_read_b128 v[194:197], v166 offset:6144
	ds_read_b128 v[198:201], v166 offset:7168
	global_load_lds_dwordx4 v152, s[46:47]
	s_add_i32 m0, s45, 0xe000
	s_nop 0
	global_load_lds_dwordx4 v154, s[46:47]
	s_waitcnt lgkmcnt(8)
	s_barrier
	s_waitcnt lgkmcnt(7)
	v_mfma_f32_16x16x32_bf16 v[124:127], v[128:131], v[168:171], v[124:127]
	v_mfma_f32_16x16x32_bf16 v[120:123], v[136:139], v[168:171], v[120:123]
	s_waitcnt lgkmcnt(5)
	v_mfma_f32_16x16x32_bf16 v[108:111], v[128:131], v[176:179], v[108:111]
	v_mfma_f32_16x16x32_bf16 v[104:107], v[136:139], v[176:179], v[104:107]
	s_waitcnt lgkmcnt(3)
	v_mfma_f32_16x16x32_bf16 v[92:95], v[128:131], v[186:189], v[92:95]
	v_mfma_f32_16x16x32_bf16 v[88:91], v[136:139], v[186:189], v[88:91]
	s_waitcnt lgkmcnt(1)
	v_mfma_f32_16x16x32_bf16 v[76:79], v[128:131], v[194:197], v[76:79]
	v_mfma_f32_16x16x32_bf16 v[72:75], v[136:139], v[194:197], v[72:75]
	v_mfma_f32_16x16x32_bf16 v[124:127], v[132:135], v[172:175], v[124:127]
	v_mfma_f32_16x16x32_bf16 v[120:123], v[140:143], v[172:175], v[120:123]
	v_mfma_f32_16x16x32_bf16 v[108:111], v[132:135], v[182:185], v[108:111]
	v_mfma_f32_16x16x32_bf16 v[104:107], v[140:143], v[182:185], v[104:107]
	v_mfma_f32_16x16x32_bf16 v[92:95], v[132:135], v[190:193], v[92:95]
	v_mfma_f32_16x16x32_bf16 v[88:91], v[140:143], v[190:193], v[88:91]
	s_waitcnt lgkmcnt(0)
	v_mfma_f32_16x16x32_bf16 v[76:79], v[132:135], v[198:201], v[76:79]
	v_mfma_f32_16x16x32_bf16 v[72:75], v[140:143], v[198:201], v[72:75]
	s_barrier
	s_add_i32 s78, s70, s58
	s_add_u32 s86, s48, s12
	s_addc_u32 s87, s49, s13
	s_mov_b32 m0, s78
	ds_read_b128 v[202:205], v167
	ds_read_b128 v[206:209], v167 offset:1024
	ds_read_b128 v[210:213], v167 offset:2048
	ds_read_b128 v[214:217], v167 offset:3072
	global_load_lds_dwordx4 v146, s[48:49]
	s_add_i32 m0, s78, 0x2000
	s_nop 0
	global_load_lds_dwordx4 v150, s[48:49]
	s_barrier
; #define PG8_STAGE(bufoff, gbase, voff) do { _Pragma("unroll") for (int _i = 0; _i < 2; ++_i) \
;         __builtin_amdgcn_global_load_lds((const unsigned*)((const char*)(gbase) + (voff)[_i]), (LAS unsigned*)(lds + (bufoff) + ldsw + _i * 8192), 16, 0, 0); } while (0)
; #define PG8_LDA(dst, b, h) do { _Pragma("unroll") for (int m = 0; m < 4; ++m) _Pragma("unroll") for (int k = 0; k < 2; ++k) dst[m][k] = *(const LAS bf16x8*)(lds + PG8_SA(b, h) + aoff + m * 2048 + k * 1024); } while (0)
; #define PG8_LDB(dst, b, h) do { _Pragma("unroll") for (int n = 0; n < 2; ++n) _Pragma("unroll") for (int k = 0; k < 2; ++k) dst[n][k] = *(const LAS bf16x8*)(lds + PG8_SB(b, h) + boff + n * 2048 + k * 1024); } while (0)
; #define PG8_MMA(ai, bj, At, Bt) do { __builtin_amdgcn_s_setprio(1); _Pragma("unroll") for (int m = 0; m < 4; ++m) _Pragma("unroll") for (int n = 0; n < 2; ++n) _Pragma("unroll") for (int k = 0; k < 2; ++k) \
;         acc[ai][bj][m][n] = __builtin_amdgcn_mfma_f32_16x16x32_bf16(Bt[n][k], At[m][k], acc[ai][bj][m][n], 0, 0, 0); __builtin_amdgcn_s_setprio(0); } while (0)
; #define PG8_WAIT_V(n) asm volatile("s_waitcnt vmcnt(" #n ")" ::: "memory")
; #define PG8_WAIT_L(n) asm volatile("s_waitcnt lgkmcnt(" #n ")" ::: "memory")
; #define PG8_BAR __builtin_amdgcn_s_barrier()
; #define PG8_SCHED __builtin_amdgcn_sched_barrier(0)
; template <class Epi>
; DI void gemm_phase(LAS unsigned char* lds, const Gemm g, const StaticOrder& S, const Epi& E) {
;     ...
;             PG8_BAR; PG8_WAIT_L(0); PG8_MMA(0, 1, At, B1); PG8_BAR;
;             PG8_LDA(At, 0, 1); PG8_STAGE(PG8_SA(0, 0), a2, voffA);
;             PG8_BAR; PG8_WAIT_L(0); PG8_MMA(1, 0, At, B0); PG8_BAR; PG8_SCHED;
;             PG8_STAGE(PG8_SB(0, 1), b2 + hstep, voffB);
;             PG8_WAIT_V(6); PG8_BAR; PG8_MMA(1, 1, At, B1); PG8_BAR;
;             PG8_LDB(B0, 1, 0); PG8_SCHED; PG8_LDA(At, 1, 0); PG8_STAGE(PG8_SA(0, 1), a2 + hstep, voffA);
;             PG8_WAIT_L(8); PG8_BAR; PG8_WAIT_L(0); PG8_MMA(0, 0, At, B0); PG8_BAR; PG8_SCHED;
	s_waitcnt lgkmcnt(3)
	v_mfma_f32_16x16x32_bf16 v[116:119], v[202:205], v[168:171], v[116:119]
	s_waitcnt lgkmcnt(1)
	v_mfma_f32_16x16x32_bf16 v[112:115], v[210:213], v[168:171], v[112:115]
	v_mfma_f32_16x16x32_bf16 v[100:103], v[202:205], v[176:179], v[100:103]
	v_mfma_f32_16x16x32_bf16 v[96:99], v[210:213], v[176:179], v[96:99]
	v_mfma_f32_16x16x32_bf16 v[84:87], v[202:205], v[186:189], v[84:87]
	v_mfma_f32_16x16x32_bf16 v[80:83], v[210:213], v[186:189], v[80:83]
	v_mfma_f32_16x16x32_bf16 v[68:71], v[202:205], v[194:197], v[68:71]
	v_mfma_f32_16x16x32_bf16 v[64:67], v[210:213], v[194:197], v[64:67]
	v_mfma_f32_16x16x32_bf16 v[116:119], v[206:209], v[172:175], v[116:119]
	s_waitcnt lgkmcnt(0)
	v_mfma_f32_16x16x32_bf16 v[112:115], v[214:217], v[172:175], v[112:115]
	v_mfma_f32_16x16x32_bf16 v[100:103], v[206:209], v[182:185], v[100:103]
	v_mfma_f32_16x16x32_bf16 v[96:99], v[214:217], v[182:185], v[96:99]
	v_mfma_f32_16x16x32_bf16 v[84:87], v[206:209], v[190:193], v[84:87]
	v_mfma_f32_16x16x32_bf16 v[80:83], v[214:217], v[190:193], v[80:83]
	v_mfma_f32_16x16x32_bf16 v[68:71], v[206:209], v[198:201], v[68:71]
	v_mfma_f32_16x16x32_bf16 v[64:67], v[214:217], v[198:201], v[64:67]
	s_mov_b32 m0, s45
	s_add_u32 s88, s50, s12
	s_addc_u32 s89, s51, s13
	s_barrier
	ds_read_b128 v[168:171], v166 offset:16384
	ds_read_b128 v[172:175], v166 offset:17408
	ds_read_b128 v[176:179], v166 offset:18432
	ds_read_b128 v[182:185], v166 offset:19456
	ds_read_b128 v[186:189], v166 offset:20480
	ds_read_b128 v[190:193], v166 offset:21504
	ds_read_b128 v[194:197], v166 offset:22528
	ds_read_b128 v[198:201], v166 offset:23552
	global_load_lds_dwordx4 v144, s[50:51]
	s_mov_b32 m0, s59
	s_nop 0
	global_load_lds_dwordx4 v148, s[50:51]
	s_barrier
	s_waitcnt lgkmcnt(7)
	v_mfma_f32_16x16x32_bf16 v[60:63], v[128:131], v[168:171], v[60:63]
	v_mfma_f32_16x16x32_bf16 v[56:59], v[136:139], v[168:171], v[56:59]
	s_waitcnt lgkmcnt(5)
	v_mfma_f32_16x16x32_bf16 v[44:47], v[128:131], v[176:179], v[44:47]
	v_mfma_f32_16x16x32_bf16 v[40:43], v[136:139], v[176:179], v[40:43]
	s_waitcnt lgkmcnt(3)
	v_mfma_f32_16x16x32_bf16 v[28:31], v[128:131], v[186:189], v[28:31]
	v_mfma_f32_16x16x32_bf16 v[24:27], v[136:139], v[186:189], v[24:27]
	s_waitcnt lgkmcnt(1)
	v_mfma_f32_16x16x32_bf16 v[12:15], v[128:131], v[194:197], v[12:15]
	v_mfma_f32_16x16x32_bf16 v[8:11], v[136:139], v[194:197], v[8:11]
	v_mfma_f32_16x16x32_bf16 v[60:63], v[132:135], v[172:175], v[60:63]
	v_mfma_f32_16x16x32_bf16 v[56:59], v[140:143], v[172:175], v[56:59]
	v_mfma_f32_16x16x32_bf16 v[44:47], v[132:135], v[182:185], v[44:47]
	v_mfma_f32_16x16x32_bf16 v[40:43], v[140:143], v[182:185], v[40:43]
	v_mfma_f32_16x16x32_bf16 v[28:31], v[132:135], v[190:193], v[28:31]
	v_mfma_f32_16x16x32_bf16 v[24:27], v[140:143], v[190:193], v[24:27]
	s_waitcnt lgkmcnt(0)
	v_mfma_f32_16x16x32_bf16 v[12:15], v[132:135], v[198:201], v[12:15]
	v_mfma_f32_16x16x32_bf16 v[8:11], v[140:143], v[198:201], v[8:11]
	s_barrier
	s_add_u32 s78, s48, 0x40000
	s_addc_u32 s79, s49, 0
	s_add_i32 s80, s71, s58
	s_mov_b32 m0, s80
	s_nop 0
	global_load_lds_dwordx4 v146, s[78:79]
	s_add_i32 m0, s80, 0x2000
	s_nop 0
	global_load_lds_dwordx4 v150, s[78:79]
	s_lshl_b32 s84, s44, 20
	s_lshl_b32 s85, s72, 10
	s_add_u32 s84, s84, s85
	s_add_i32 s85, s77, 2
	s_lshl_b32 s85, s85, 13
	s_add_u32 s84, s84, s85
	s_add_u32 s84, s36, s84
	s_addc_u32 s85, s37, 0
	s_waitcnt vmcnt(6)
	global_load_dword v249, v248, s[84:85]
	s_barrier
	v_mfma_f32_16x16x32_bf16 v[52:55], v[202:205], v[168:171], v[52:55]
	v_mfma_f32_16x16x32_bf16 v[48:51], v[210:213], v[168:171], v[48:51]
	v_mfma_f32_16x16x32_bf16 v[36:39], v[202:205], v[176:179], v[36:39]
	v_mfma_f32_16x16x32_bf16 v[32:35], v[210:213], v[176:179], v[32:35]
	v_mfma_f32_16x16x32_bf16 v[20:23], v[202:205], v[186:189], v[20:23]
	v_mfma_f32_16x16x32_bf16 v[16:19], v[210:213], v[186:189], v[16:19]
	v_mfma_f32_16x16x32_bf16 v[4:7], v[202:205], v[194:197], v[4:7]
	v_mfma_f32_16x16x32_bf16 v[0:3], v[210:213], v[194:197], v[0:3]
	v_mfma_f32_16x16x32_bf16 v[52:55], v[206:209], v[172:175], v[52:55]
	v_mfma_f32_16x16x32_bf16 v[48:51], v[214:217], v[172:175], v[48:51]
	v_mfma_f32_16x16x32_bf16 v[36:39], v[206:209], v[182:185], v[36:39]
	v_mfma_f32_16x16x32_bf16 v[32:35], v[214:217], v[182:185], v[32:35]
	v_mfma_f32_16x16x32_bf16 v[20:23], v[206:209], v[190:193], v[20:23]
	v_mfma_f32_16x16x32_bf16 v[16:19], v[214:217], v[190:193], v[16:19]
	v_mfma_f32_16x16x32_bf16 v[4:7], v[206:209], v[198:201], v[4:7]
	v_mfma_f32_16x16x32_bf16 v[0:3], v[214:217], v[198:201], v[0:3]
	s_add_i32 s78, 0, 0x18000
	v_add_u32_e32 v140, s78, v163
	s_barrier
	ds_read_b128 v[128:131], v140
	ds_read_b128 v[132:135], v140 offset:1024
	ds_read_b128 v[136:139], v140 offset:2048
	ds_read_b128 v[140:143], v140 offset:3072
	s_add_u32 s50, s50, 0x40000
	s_addc_u32 s51, s51, 0
	s_mov_b32 m0, s60
	ds_read_b128 v[168:171], v166 offset:32768
	ds_read_b128 v[172:175], v166 offset:33792
	ds_read_b128 v[176:179], v166 offset:34816
	ds_read_b128 v[182:185], v166 offset:35840
	ds_read_b128 v[186:189], v166 offset:36864
	ds_read_b128 v[190:193], v166 offset:37888
	ds_read_b128 v[194:197], v166 offset:38912
	ds_read_b128 v[198:201], v166 offset:39936
	global_load_lds_dwordx4 v144, s[50:51]
	s_mov_b32 m0, s61
	s_nop 0
	global_load_lds_dwordx4 v148, s[50:51]
	s_waitcnt lgkmcnt(8)
	s_barrier
; #define PG8_STAGE(bufoff, gbase, voff) do { _Pragma("unroll") for (int _i = 0; _i < 2; ++_i) \
;         __builtin_amdgcn_global_load_lds((const unsigned*)((const char*)(gbase) + (voff)[_i]), (LAS unsigned*)(lds + (bufoff) + ldsw + _i * 8192), 16, 0, 0); } while (0)
; #define PG8_LDA(dst, b, h) do { _Pragma("unroll") for (int m = 0; m < 4; ++m) _Pragma("unroll") for (int k = 0; k < 2; ++k) dst[m][k] = *(const LAS bf16x8*)(lds + PG8_SA(b, h) + aoff + m * 2048 + k * 1024); } while (0)
; #define PG8_LDB(dst, b, h) do { _Pragma("unroll") for (int n = 0; n < 2; ++n) _Pragma("unroll") for (int k = 0; k < 2; ++k) dst[n][k] = *(const LAS bf16x8*)(lds + PG8_SB(b, h) + boff + n * 2048 + k * 1024); } while (0)
; #define PG8_MMA(ai, bj, At, Bt) do { __builtin_amdgcn_s_setprio(1); _Pragma("unroll") for (int m = 0; m < 4; ++m) _Pragma("unroll") for (int n = 0; n < 2; ++n) _Pragma("unroll") for (int k = 0; k < 2; ++k) \
;         acc[ai][bj][m][n] = __builtin_amdgcn_mfma_f32_16x16x32_bf16(Bt[n][k], At[m][k], acc[ai][bj][m][n], 0, 0, 0); __builtin_amdgcn_s_setprio(0); } while (0)
; #define PG8_WAIT_V(n) asm volatile("s_waitcnt vmcnt(" #n ")" ::: "memory")
; #define PG8_WAIT_L(n) asm volatile("s_waitcnt lgkmcnt(" #n ")" ::: "memory")
; #define PG8_BAR __builtin_amdgcn_s_barrier()
; #define PG8_SCHED __builtin_amdgcn_sched_barrier(0)
; template <class Epi>
; DI void gemm_phase(LAS unsigned char* lds, const Gemm g, const StaticOrder& S, const Epi& E) {
;     ...
;             PG8_WAIT_L(8); PG8_BAR; PG8_WAIT_L(0); PG8_MMA(0, 0, At, B0); PG8_BAR; PG8_SCHED;
;             PG8_LDB(B1, 1, 1); PG8_STAGE(PG8_SB(1, 0), b3, voffB);
;             PG8_BAR; PG8_WAIT_L(0); PG8_MMA(0, 1, At, B1); PG8_BAR;
;             PG8_LDA(At, 1, 1); PG8_STAGE(PG8_SA(1, 0), a3, voffA);
;             PG8_BAR; PG8_WAIT_L(0); PG8_MMA(1, 0, At, B0); PG8_BAR; PG8_SCHED;
;             PG8_STAGE(PG8_SB(1, 1), b3 + hstep, voffB);
;             PG8_WAIT_V(6); PG8_BAR; PG8_MMA(1, 1, At, B1); PG8_BAR;
	s_waitcnt lgkmcnt(7)
	v_mfma_f32_16x16x32_bf16 v[124:127], v[128:131], v[168:171], v[124:127]
	v_mfma_f32_16x16x32_bf16 v[120:123], v[136:139], v[168:171], v[120:123]
	s_waitcnt lgkmcnt(5)
	v_mfma_f32_16x16x32_bf16 v[108:111], v[128:131], v[176:179], v[108:111]
	v_mfma_f32_16x16x32_bf16 v[104:107], v[136:139], v[176:179], v[104:107]
	s_waitcnt lgkmcnt(3)
	v_mfma_f32_16x16x32_bf16 v[92:95], v[128:131], v[186:189], v[92:95]
	v_mfma_f32_16x16x32_bf16 v[88:91], v[136:139], v[186:189], v[88:91]
	s_waitcnt lgkmcnt(1)
	v_mfma_f32_16x16x32_bf16 v[76:79], v[128:131], v[194:197], v[76:79]
	v_mfma_f32_16x16x32_bf16 v[72:75], v[136:139], v[194:197], v[72:75]
	v_mfma_f32_16x16x32_bf16 v[124:127], v[132:135], v[172:175], v[124:127]
	v_mfma_f32_16x16x32_bf16 v[120:123], v[140:143], v[172:175], v[120:123]
	v_mfma_f32_16x16x32_bf16 v[108:111], v[132:135], v[182:185], v[108:111]
	v_mfma_f32_16x16x32_bf16 v[104:107], v[140:143], v[182:185], v[104:107]
	v_mfma_f32_16x16x32_bf16 v[92:95], v[132:135], v[190:193], v[92:95]
	v_mfma_f32_16x16x32_bf16 v[88:91], v[140:143], v[190:193], v[88:91]
	s_waitcnt lgkmcnt(0)
	v_mfma_f32_16x16x32_bf16 v[76:79], v[132:135], v[198:201], v[76:79]
	v_mfma_f32_16x16x32_bf16 v[72:75], v[140:143], v[198:201], v[72:75]
	s_barrier
	s_add_i32 s50, 0, 0x1c000
	s_add_i32 s51, s78, s58
	v_add_u32_e32 v214, s50, v163
	s_mov_b32 m0, s51
	ds_read_b128 v[202:205], v214
	ds_read_b128 v[206:209], v214 offset:1024
	ds_read_b128 v[210:213], v214 offset:2048
	ds_read_b128 v[214:217], v214 offset:3072
	global_load_lds_dwordx4 v146, s[86:87]
	s_add_i32 m0, s51, 0x2000
	s_nop 0
	global_load_lds_dwordx4 v150, s[86:87]
	s_barrier
	s_waitcnt lgkmcnt(3)
	v_mfma_f32_16x16x32_bf16 v[116:119], v[202:205], v[168:171], v[116:119]
	s_waitcnt lgkmcnt(1)
	v_mfma_f32_16x16x32_bf16 v[112:115], v[210:213], v[168:171], v[112:115]
	v_mfma_f32_16x16x32_bf16 v[100:103], v[202:205], v[176:179], v[100:103]
	v_mfma_f32_16x16x32_bf16 v[96:99], v[210:213], v[176:179], v[96:99]
	v_mfma_f32_16x16x32_bf16 v[84:87], v[202:205], v[186:189], v[84:87]
	v_mfma_f32_16x16x32_bf16 v[80:83], v[210:213], v[186:189], v[80:83]
	v_mfma_f32_16x16x32_bf16 v[68:71], v[202:205], v[194:197], v[68:71]
	v_mfma_f32_16x16x32_bf16 v[64:67], v[210:213], v[194:197], v[64:67]
	v_mfma_f32_16x16x32_bf16 v[116:119], v[206:209], v[172:175], v[116:119]
	s_waitcnt lgkmcnt(0)
	v_mfma_f32_16x16x32_bf16 v[112:115], v[214:217], v[172:175], v[112:115]
	v_mfma_f32_16x16x32_bf16 v[100:103], v[206:209], v[182:185], v[100:103]
	v_mfma_f32_16x16x32_bf16 v[96:99], v[214:217], v[182:185], v[96:99]
	v_mfma_f32_16x16x32_bf16 v[84:87], v[206:209], v[190:193], v[84:87]
	v_mfma_f32_16x16x32_bf16 v[80:83], v[214:217], v[190:193], v[80:83]
	v_mfma_f32_16x16x32_bf16 v[68:71], v[206:209], v[198:201], v[68:71]
	v_mfma_f32_16x16x32_bf16 v[64:67], v[214:217], v[198:201], v[64:67]
	s_mov_b32 m0, s65
	s_barrier
	ds_read_b128 v[168:171], v166 offset:49152
	ds_read_b128 v[172:175], v166 offset:50176
	ds_read_b128 v[176:179], v166 offset:51200
	ds_read_b128 v[182:185], v166 offset:52224
	ds_read_b128 v[186:189], v166 offset:53248
	ds_read_b128 v[190:193], v166 offset:54272
	ds_read_b128 v[194:197], v166 offset:55296
	ds_read_b128 v[198:201], v166 offset:56320
	global_load_lds_dwordx4 v144, s[88:89]
	s_mov_b32 m0, s66
	s_nop 0
	global_load_lds_dwordx4 v148, s[88:89]
	s_barrier
	s_waitcnt lgkmcnt(7)
	v_mfma_f32_16x16x32_bf16 v[60:63], v[128:131], v[168:171], v[60:63]
	v_mfma_f32_16x16x32_bf16 v[56:59], v[136:139], v[168:171], v[56:59]
	s_waitcnt lgkmcnt(5)
	v_mfma_f32_16x16x32_bf16 v[44:47], v[128:131], v[176:179], v[44:47]
	v_mfma_f32_16x16x32_bf16 v[40:43], v[136:139], v[176:179], v[40:43]
	s_waitcnt lgkmcnt(3)
	v_mfma_f32_16x16x32_bf16 v[28:31], v[128:131], v[186:189], v[28:31]
	v_mfma_f32_16x16x32_bf16 v[24:27], v[136:139], v[186:189], v[24:27]
	s_waitcnt lgkmcnt(1)
	v_mfma_f32_16x16x32_bf16 v[12:15], v[128:131], v[194:197], v[12:15]
	v_mfma_f32_16x16x32_bf16 v[8:11], v[136:139], v[194:197], v[8:11]
	v_mfma_f32_16x16x32_bf16 v[60:63], v[132:135], v[172:175], v[60:63]
	v_mfma_f32_16x16x32_bf16 v[56:59], v[140:143], v[172:175], v[56:59]
	v_mfma_f32_16x16x32_bf16 v[44:47], v[132:135], v[182:185], v[44:47]
	v_mfma_f32_16x16x32_bf16 v[40:43], v[140:143], v[182:185], v[40:43]
	v_mfma_f32_16x16x32_bf16 v[28:31], v[132:135], v[190:193], v[28:31]
	v_mfma_f32_16x16x32_bf16 v[24:27], v[140:143], v[190:193], v[24:27]
	s_waitcnt lgkmcnt(0)
	v_mfma_f32_16x16x32_bf16 v[12:15], v[132:135], v[198:201], v[12:15]
	v_mfma_f32_16x16x32_bf16 v[8:11], v[140:143], v[198:201], v[8:11]
	s_barrier
	s_add_u32 s48, s48, 0x40080
	s_addc_u32 s49, s49, 0
	s_add_i32 s50, s50, s58
	s_mov_b32 m0, s50
	s_nop 0
	global_load_lds_dwordx4 v146, s[48:49]
	s_add_i32 m0, s50, 0x2000
	s_nop 0
	global_load_lds_dwordx4 v150, s[48:49]
	s_waitcnt vmcnt(6)
	s_barrier
	v_mfma_f32_16x16x32_bf16 v[52:55], v[202:205], v[168:171], v[52:55]
	v_mfma_f32_16x16x32_bf16 v[48:51], v[210:213], v[168:171], v[48:51]
	v_mfma_f32_16x16x32_bf16 v[36:39], v[202:205], v[176:179], v[36:39]
	v_mfma_f32_16x16x32_bf16 v[32:35], v[210:213], v[176:179], v[32:35]
	v_mfma_f32_16x16x32_bf16 v[20:23], v[202:205], v[186:189], v[20:23]
	v_mfma_f32_16x16x32_bf16 v[16:19], v[210:213], v[186:189], v[16:19]
	v_mfma_f32_16x16x32_bf16 v[4:7], v[202:205], v[194:197], v[4:7]
	v_mfma_f32_16x16x32_bf16 v[0:3], v[210:213], v[194:197], v[0:3]
	v_mfma_f32_16x16x32_bf16 v[52:55], v[206:209], v[172:175], v[52:55]
	v_mfma_f32_16x16x32_bf16 v[48:51], v[214:217], v[172:175], v[48:51]
	v_mfma_f32_16x16x32_bf16 v[36:39], v[206:209], v[182:185], v[36:39]
	v_mfma_f32_16x16x32_bf16 v[32:35], v[214:217], v[182:185], v[32:35]
	v_mfma_f32_16x16x32_bf16 v[20:23], v[206:209], v[190:193], v[20:23]
	v_mfma_f32_16x16x32_bf16 v[16:19], v[214:217], v[190:193], v[16:19]
	v_mfma_f32_16x16x32_bf16 v[4:7], v[206:209], v[198:201], v[4:7]
	v_mfma_f32_16x16x32_bf16 v[0:3], v[214:217], v[198:201], v[0:3]
	s_add_i32 s77, s77, 2
	s_add_u32 s46, s46, 0x100
	s_addc_u32 s47, s47, 0
	s_add_u32 s75, s75, 0x100
	s_addc_u32 s76, s76, 0
	s_cmp_gt_u32 s77, 13
	s_barrier
; DI unsigned pk2(float a, float b) { f32x2 v = {a, b}; bf16x2_t r = __builtin_convertvector(v, bf16x2_t); return __builtin_bit_cast(unsigned, r); }
;     DI void operator()(const f32x4 (&acc)[2][2][4][2], const Unit& u, int wr, int wc, int fr, int fq) const {
;         const int row0 = u.pm * BM + wr * 64 + fr, col0 = u.pn * BM + wc * 32 + 8 * fq;
;         const float* gp = gate + (size_t)((u.pm * BM) >> 12) * NMODC + col0;
;         f32x4 gv[2][2];
; #pragma unroll
;         for (int bj = 0; bj < 2; ++bj)
; #pragma unroll
;             for (int n = 0; n < 2; ++n) gv[bj][n] = *(const f32x4*)(gp + bj * HALF + n * 4);
; #pragma unroll
;         for (int ai = 0; ai < 2; ++ai)
; #pragma unroll
;             for (int m = 0; m < 4; ++m) { const size_t ro = (size_t)(row0 + ai * HALF + m * 16) * DM + col0;
; #pragma unroll
;                 for (int bj = 0; bj < 2; ++bj) {
;                     const f32x4 x0 = *(const f32x4*)(base + ro + bj * HALF) + gv[bj][0] * acc[ai][bj][m][0], x1 = *(const f32x4*)(base + ro + bj * HALF + 4) + gv[bj][1] * acc[ai][bj][m][1];
;                     u32x4 w; w.x = pk2(x0.x, x0.y); w.y = pk2(x0.z, x0.w); w.z = pk2(x1.x, x1.y); w.w = pk2(x1.z, x1.w);
;                     *(u32x4*)(outb + ro + bj * HALF) = w; } }
	s_cbranch_scc0 .LBB0_724
	v_lshl_add_u32 v171, s44, 8, v162
	v_lshl_or_b32 v172, s72, 8, v164
	s_ashr_i32 s25, s44, 4
	s_mul_hi_i32 s39, s25, 0x6000
	s_mulk_i32 s25, 0x6000
	s_add_u32 s46, s63, s25
	s_addc_u32 s47, s64, s39
	v_lshlrev_b32_e32 v168, 2, v172
	v_lshlrev_b32_e32 v160, 12, v171
	v_lshlrev_b32_e32 v161, 11, v171
	global_load_dwordx4 v[128:131], v168, s[46:47]
	global_load_dwordx4 v[132:135], v168, s[46:47] offset:16
	global_load_dwordx4 v[136:139], v168, s[46:47] offset:512
	global_load_dwordx4 v[140:143], v168, s[46:47] offset:528
	v_lshl_add_u32 v160, v172, 2, v160
	v_lshl_add_u32 v161, v172, 1, v161
	s_mov_b32 s72, s24
	s_mov_b32 s44, s38
	s_mov_b64 s[48:49], s[42:43]
	s_mov_b64 s[46:47], s[40:41]
	global_load_dwordx4 v[184:187], v160, s[36:37]
	global_load_dwordx4 v[188:191], v160, s[36:37] offset:16
	global_load_dwordx4 v[192:195], v160, s[36:37] offset:512
	global_load_dwordx4 v[196:199], v160, s[36:37] offset:528
	v_add_u32_e32 v169, 0x10000, v160
	global_load_dwordx4 v[200:203], v169, s[36:37]
	global_load_dwordx4 v[204:207], v169, s[36:37] offset:16
	v_add_u32_e32 v169, 0x10000, v160
	global_load_dwordx4 v[208:211], v169, s[36:37] offset:512
	global_load_dwordx4 v[212:215], v169, s[36:37] offset:528
	v_add_u32_e32 v169, 0x20000, v160
	global_load_dwordx4 v[216:219], v169, s[36:37]
	global_load_dwordx4 v[220:223], v169, s[36:37] offset:16
	v_add_u32_e32 v169, 0x20000, v160
	global_load_dwordx4 v[224:227], v169, s[36:37] offset:512
	global_load_dwordx4 v[228:231], v169, s[36:37] offset:528
	v_add_u32_e32 v169, 0x30000, v160
	global_load_dwordx4 v[232:235], v169, s[36:37]
	global_load_dwordx4 v[236:239], v169, s[36:37] offset:16
	v_add_u32_e32 v169, 0x30000, v160
	global_load_dwordx4 v[240:243], v169, s[36:37] offset:512
	global_load_dwordx4 v[244:247], v169, s[36:37] offset:528
	s_waitcnt vmcnt(14)
	v_pk_fma_f32 v[124:125], v[124:125], v[128:129], v[184:185]
	v_pk_fma_f32 v[126:127], v[126:127], v[130:131], v[186:187]
	v_pk_fma_f32 v[120:121], v[120:121], v[132:133], v[188:189]
	v_pk_fma_f32 v[122:123], v[122:123], v[134:135], v[190:191]
	v_add_u32_e32 v169, 0x80000, v160
	global_load_dwordx4 v[184:187], v169, s[36:37]
	global_load_dwordx4 v[188:191], v169, s[36:37] offset:16
	v_cvt_pk_bf16_f32 v124, v124, v125
	v_cvt_pk_bf16_f32 v125, v126, v127
	v_cvt_pk_bf16_f32 v126, v120, v121
	v_cvt_pk_bf16_f32 v127, v122, v123
	global_store_dwordx4 v161, v[124:127], s[8:9]
	s_waitcnt vmcnt(15)
	v_pk_fma_f32 v[116:117], v[116:117], v[136:137], v[192:193]
	v_pk_fma_f32 v[118:119], v[118:119], v[138:139], v[194:195]
	v_pk_fma_f32 v[112:113], v[112:113], v[140:141], v[196:197]
	v_pk_fma_f32 v[114:115], v[114:115], v[142:143], v[198:199]
	v_add_u32_e32 v169, 0x80000, v160
	global_load_dwordx4 v[192:195], v169, s[36:37] offset:512
	global_load_dwordx4 v[196:199], v169, s[36:37] offset:528
	v_cvt_pk_bf16_f32 v116, v116, v117
	v_cvt_pk_bf16_f32 v117, v118, v119
	v_cvt_pk_bf16_f32 v118, v112, v113
	v_cvt_pk_bf16_f32 v119, v114, v115
	global_store_dwordx4 v161, v[116:119], s[8:9] offset:256
	s_waitcnt vmcnt(16)
	v_pk_fma_f32 v[108:109], v[108:109], v[128:129], v[200:201]
	v_pk_fma_f32 v[110:111], v[110:111], v[130:131], v[202:203]
	v_pk_fma_f32 v[104:105], v[104:105], v[132:133], v[204:205]
	v_pk_fma_f32 v[106:107], v[106:107], v[134:135], v[206:207]
	v_add_u32_e32 v169, 0x90000, v160
	global_load_dwordx4 v[200:203], v169, s[36:37]
	global_load_dwordx4 v[204:207], v169, s[36:37] offset:16
	v_cvt_pk_bf16_f32 v108, v108, v109
	v_cvt_pk_bf16_f32 v109, v110, v111
	v_cvt_pk_bf16_f32 v110, v104, v105
	v_cvt_pk_bf16_f32 v111, v106, v107
	v_add_u32_e32 v170, 0x8000, v161
	global_store_dwordx4 v170, v[108:111], s[8:9]
	s_waitcnt vmcnt(17)
	v_pk_fma_f32 v[100:101], v[100:101], v[136:137], v[208:209]
	v_pk_fma_f32 v[102:103], v[102:103], v[138:139], v[210:211]
	v_pk_fma_f32 v[96:97], v[96:97], v[140:141], v[212:213]
	v_pk_fma_f32 v[98:99], v[98:99], v[142:143], v[214:215]
	v_add_u32_e32 v169, 0x90000, v160
	global_load_dwordx4 v[208:211], v169, s[36:37] offset:512
	global_load_dwordx4 v[212:215], v169, s[36:37] offset:528
	v_cvt_pk_bf16_f32 v100, v100, v101
	v_cvt_pk_bf16_f32 v101, v102, v103
	v_cvt_pk_bf16_f32 v102, v96, v97
	v_cvt_pk_bf16_f32 v103, v98, v99
	v_add_u32_e32 v170, 0x8000, v161
	global_store_dwordx4 v170, v[100:103], s[8:9] offset:256
	s_waitcnt vmcnt(18)
	v_pk_fma_f32 v[92:93], v[92:93], v[128:129], v[216:217]
	v_pk_fma_f32 v[94:95], v[94:95], v[130:131], v[218:219]
	v_pk_fma_f32 v[88:89], v[88:89], v[132:133], v[220:221]
	v_pk_fma_f32 v[90:91], v[90:91], v[134:135], v[222:223]
	v_add_u32_e32 v169, 0xa0000, v160
	global_load_dwordx4 v[216:219], v169, s[36:37]
	global_load_dwordx4 v[220:223], v169, s[36:37] offset:16
	v_cvt_pk_bf16_f32 v92, v92, v93
	v_cvt_pk_bf16_f32 v93, v94, v95
	v_cvt_pk_bf16_f32 v94, v88, v89
	v_cvt_pk_bf16_f32 v95, v90, v91
	v_add_u32_e32 v170, 0x10000, v161
	global_store_dwordx4 v170, v[92:95], s[8:9]
	s_waitcnt vmcnt(19)
	v_pk_fma_f32 v[84:85], v[84:85], v[136:137], v[224:225]
	v_pk_fma_f32 v[86:87], v[86:87], v[138:139], v[226:227]
	v_pk_fma_f32 v[80:81], v[80:81], v[140:141], v[228:229]
	v_pk_fma_f32 v[82:83], v[82:83], v[142:143], v[230:231]
	v_add_u32_e32 v169, 0xa0000, v160
	global_load_dwordx4 v[224:227], v169, s[36:37] offset:512
	global_load_dwordx4 v[228:231], v169, s[36:37] offset:528
	v_cvt_pk_bf16_f32 v84, v84, v85
	v_cvt_pk_bf16_f32 v85, v86, v87
	v_cvt_pk_bf16_f32 v86, v80, v81
	v_cvt_pk_bf16_f32 v87, v82, v83
	v_add_u32_e32 v170, 0x10000, v161
	global_store_dwordx4 v170, v[84:87], s[8:9] offset:256
	s_waitcnt vmcnt(20)
; DI unsigned pk2(float a, float b) { f32x2 v = {a, b}; bf16x2_t r = __builtin_convertvector(v, bf16x2_t); return __builtin_bit_cast(unsigned, r); }
;     DI void operator()(const f32x4 (&acc)[2][2][4][2], const Unit& u, int wr, int wc, int fr, int fq) const {
;     ...
;             for (int m = 0; m < 4; ++m) { const size_t ro = (size_t)(row0 + ai * HALF + m * 16) * DM + col0;
; #pragma unroll
;                 for (int bj = 0; bj < 2; ++bj) {
;                     const f32x4 x0 = *(const f32x4*)(base + ro + bj * HALF) + gv[bj][0] * acc[ai][bj][m][0], x1 = *(const f32x4*)(base + ro + bj * HALF + 4) + gv[bj][1] * acc[ai][bj][m][1];
;                     u32x4 w; w.x = pk2(x0.x, x0.y); w.y = pk2(x0.z, x0.w); w.z = pk2(x1.x, x1.y); w.w = pk2(x1.z, x1.w);
;                     *(u32x4*)(outb + ro + bj * HALF) = w; } }
	v_pk_fma_f32 v[76:77], v[76:77], v[128:129], v[232:233]
	v_pk_fma_f32 v[78:79], v[78:79], v[130:131], v[234:235]
	v_pk_fma_f32 v[72:73], v[72:73], v[132:133], v[236:237]
	v_pk_fma_f32 v[74:75], v[74:75], v[134:135], v[238:239]
	v_add_u32_e32 v169, 0xb0000, v160
	global_load_dwordx4 v[232:235], v169, s[36:37]
	global_load_dwordx4 v[236:239], v169, s[36:37] offset:16
	v_cvt_pk_bf16_f32 v76, v76, v77
	v_cvt_pk_bf16_f32 v77, v78, v79
	v_cvt_pk_bf16_f32 v78, v72, v73
	v_cvt_pk_bf16_f32 v79, v74, v75
	v_add_u32_e32 v170, 0x18000, v161
	global_store_dwordx4 v170, v[76:79], s[8:9]
	s_waitcnt vmcnt(21)
	v_pk_fma_f32 v[68:69], v[68:69], v[136:137], v[240:241]
	v_pk_fma_f32 v[70:71], v[70:71], v[138:139], v[242:243]
	v_pk_fma_f32 v[64:65], v[64:65], v[140:141], v[244:245]
	v_pk_fma_f32 v[66:67], v[66:67], v[142:143], v[246:247]
	v_add_u32_e32 v169, 0xb0000, v160
	global_load_dwordx4 v[240:243], v169, s[36:37] offset:512
	global_load_dwordx4 v[244:247], v169, s[36:37] offset:528
	v_cvt_pk_bf16_f32 v68, v68, v69
	v_cvt_pk_bf16_f32 v69, v70, v71
	v_cvt_pk_bf16_f32 v70, v64, v65
	v_cvt_pk_bf16_f32 v71, v66, v67
	v_add_u32_e32 v170, 0x18000, v161
	global_store_dwordx4 v170, v[68:71], s[8:9] offset:256
	s_waitcnt vmcnt(22)
	v_pk_fma_f32 v[60:61], v[60:61], v[128:129], v[184:185]
	v_pk_fma_f32 v[62:63], v[62:63], v[130:131], v[186:187]
	v_pk_fma_f32 v[56:57], v[56:57], v[132:133], v[188:189]
	v_pk_fma_f32 v[58:59], v[58:59], v[134:135], v[190:191]
	v_cvt_pk_bf16_f32 v60, v60, v61
	v_cvt_pk_bf16_f32 v61, v62, v63
	v_cvt_pk_bf16_f32 v62, v56, v57
	v_cvt_pk_bf16_f32 v63, v58, v59
	v_add_u32_e32 v170, 0x40000, v161
	global_store_dwordx4 v170, v[60:63], s[8:9]
	s_waitcnt vmcnt(20)
	v_pk_fma_f32 v[52:53], v[52:53], v[136:137], v[192:193]
	v_pk_fma_f32 v[54:55], v[54:55], v[138:139], v[194:195]
	v_pk_fma_f32 v[48:49], v[48:49], v[140:141], v[196:197]
	v_pk_fma_f32 v[50:51], v[50:51], v[142:143], v[198:199]
	v_cvt_pk_bf16_f32 v52, v52, v53
	v_cvt_pk_bf16_f32 v53, v54, v55
	v_cvt_pk_bf16_f32 v54, v48, v49
	v_cvt_pk_bf16_f32 v55, v50, v51
	v_add_u32_e32 v170, 0x40000, v161
	global_store_dwordx4 v170, v[52:55], s[8:9] offset:256
	s_waitcnt vmcnt(18)
	v_pk_fma_f32 v[44:45], v[44:45], v[128:129], v[200:201]
	v_pk_fma_f32 v[46:47], v[46:47], v[130:131], v[202:203]
	v_pk_fma_f32 v[40:41], v[40:41], v[132:133], v[204:205]
	v_pk_fma_f32 v[42:43], v[42:43], v[134:135], v[206:207]
	v_cvt_pk_bf16_f32 v44, v44, v45
	v_cvt_pk_bf16_f32 v45, v46, v47
	v_cvt_pk_bf16_f32 v46, v40, v41
	v_cvt_pk_bf16_f32 v47, v42, v43
	v_add_u32_e32 v170, 0x48000, v161
	global_store_dwordx4 v170, v[44:47], s[8:9]
	s_waitcnt vmcnt(16)
	v_pk_fma_f32 v[36:37], v[36:37], v[136:137], v[208:209]
	v_pk_fma_f32 v[38:39], v[38:39], v[138:139], v[210:211]
	v_pk_fma_f32 v[32:33], v[32:33], v[140:141], v[212:213]
	v_pk_fma_f32 v[34:35], v[34:35], v[142:143], v[214:215]
	v_cvt_pk_bf16_f32 v36, v36, v37
	v_cvt_pk_bf16_f32 v37, v38, v39
	v_cvt_pk_bf16_f32 v38, v32, v33
	v_cvt_pk_bf16_f32 v39, v34, v35
	v_add_u32_e32 v170, 0x48000, v161
	global_store_dwordx4 v170, v[36:39], s[8:9] offset:256
	s_waitcnt vmcnt(14)
	v_pk_fma_f32 v[28:29], v[28:29], v[128:129], v[216:217]
	v_pk_fma_f32 v[30:31], v[30:31], v[130:131], v[218:219]
	v_pk_fma_f32 v[24:25], v[24:25], v[132:133], v[220:221]
	v_pk_fma_f32 v[26:27], v[26:27], v[134:135], v[222:223]
	v_cvt_pk_bf16_f32 v28, v28, v29
	v_cvt_pk_bf16_f32 v29, v30, v31
	v_cvt_pk_bf16_f32 v30, v24, v25
	v_cvt_pk_bf16_f32 v31, v26, v27
	v_add_u32_e32 v170, 0x50000, v161
	global_store_dwordx4 v170, v[28:31], s[8:9]
	s_waitcnt vmcnt(12)
	v_pk_fma_f32 v[20:21], v[20:21], v[136:137], v[224:225]
	v_pk_fma_f32 v[22:23], v[22:23], v[138:139], v[226:227]
	v_pk_fma_f32 v[16:17], v[16:17], v[140:141], v[228:229]
	v_pk_fma_f32 v[18:19], v[18:19], v[142:143], v[230:231]
	v_cvt_pk_bf16_f32 v20, v20, v21
	v_cvt_pk_bf16_f32 v21, v22, v23
	v_cvt_pk_bf16_f32 v22, v16, v17
	v_cvt_pk_bf16_f32 v23, v18, v19
	v_add_u32_e32 v170, 0x50000, v161
	global_store_dwordx4 v170, v[20:23], s[8:9] offset:256
	s_waitcnt vmcnt(10)
	v_pk_fma_f32 v[12:13], v[12:13], v[128:129], v[232:233]
	v_pk_fma_f32 v[14:15], v[14:15], v[130:131], v[234:235]
	v_pk_fma_f32 v[8:9], v[8:9], v[132:133], v[236:237]
	v_pk_fma_f32 v[10:11], v[10:11], v[134:135], v[238:239]
	v_cvt_pk_bf16_f32 v12, v12, v13
	v_cvt_pk_bf16_f32 v13, v14, v15
	v_cvt_pk_bf16_f32 v14, v8, v9
	v_cvt_pk_bf16_f32 v15, v10, v11
	v_add_u32_e32 v170, 0x58000, v161
	global_store_dwordx4 v170, v[12:15], s[8:9]
	s_waitcnt vmcnt(8)
	v_pk_fma_f32 v[4:5], v[4:5], v[136:137], v[240:241]
	v_pk_fma_f32 v[6:7], v[6:7], v[138:139], v[242:243]
	v_pk_fma_f32 v[0:1], v[0:1], v[140:141], v[244:245]
	v_pk_fma_f32 v[2:3], v[2:3], v[142:143], v[246:247]
	v_cvt_pk_bf16_f32 v4, v4, v5
	v_cvt_pk_bf16_f32 v5, v6, v7
	v_cvt_pk_bf16_f32 v6, v0, v1
	v_cvt_pk_bf16_f32 v7, v2, v3
	v_add_u32_e32 v170, 0x58000, v161
	global_store_dwordx4 v170, v[4:7], s[8:9] offset:256
	s_and_b64 vcc, exec, s[4:5]
	s_cbranch_vccz .LBB0_717
	s_waitcnt vmcnt(0)
	s_cmpk_gt_u32 s52, 0xff
	s_cbranch_scc1 .LBB0_728
	s_barrier

; #define PG8_STAGE(bufoff, gbase, voff) do { _Pragma("unroll") for (int _i = 0; _i < 2; ++_i) \
;         __builtin_amdgcn_global_load_lds((const unsigned*)((const char*)(gbase) + (voff)[_i]), (LAS unsigned*)(lds + (bufoff) + ldsw + _i * 8192), 16, 0, 0); } while (0)
; #define PG8_LDA(dst, b, h) do { _Pragma("unroll") for (int m = 0; m < 4; ++m) _Pragma("unroll") for (int k = 0; k < 2; ++k) dst[m][k] = *(const LAS bf16x8*)(lds + PG8_SA(b, h) + aoff + m * 2048 + k * 1024); } while (0)
; #define PG8_LDB(dst, b, h) do { _Pragma("unroll") for (int n = 0; n < 2; ++n) _Pragma("unroll") for (int k = 0; k < 2; ++k) dst[n][k] = *(const LAS bf16x8*)(lds + PG8_SB(b, h) + boff + n * 2048 + k * 1024); } while (0)
; #define PG8_MMA(ai, bj, At, Bt) do { __builtin_amdgcn_s_setprio(1); _Pragma("unroll") for (int m = 0; m < 4; ++m) _Pragma("unroll") for (int n = 0; n < 2; ++n) _Pragma("unroll") for (int k = 0; k < 2; ++k) \
;         acc[ai][bj][m][n] = __builtin_amdgcn_mfma_f32_16x16x32_bf16(Bt[n][k], At[m][k], acc[ai][bj][m][n], 0, 0, 0); __builtin_amdgcn_s_setprio(0); } while (0)
; #define PG8_WAIT_L(n) asm volatile("s_waitcnt lgkmcnt(" #n ")" ::: "memory")
; #define PG8_BAR __builtin_amdgcn_s_barrier()
; template <class Epi>
; DI void gemm_phase(LAS unsigned char* lds, const Gemm g, const StaticOrder& S, const Epi& E) {
;     ...
;         const bool has_next = S.next(ui + 1, nxt);
;         const char* nA = has_next ? (const char*)g.A + (size_t)nxt.pm * tstep : cA; const char* nB = has_next ? (const char*)g.Bt + (size_t)nxt.pn * tstep : cB;
;         for (int t = 0; t < nt; t += 2) {
;             const bool last = (t == nt - 2);
;             const char* a1 = cA + (size_t)(t + 1) * kstep;
;             const char* a2 = last ? nA : cA + (size_t)(t + 2) * kstep; const char* b2 = last ? nB : cB + (size_t)(t + 2) * kstep;
;             const char* a3 = a2 + kstep; const char* b3 = b2 + kstep;
;             PG8_LDB(B0, 0, 0); PG8_SCHED; PG8_LDA(At, 0, 0); PG8_STAGE(PG8_SA(1, 1), a1 + hstep, voffA);
;             PG8_WAIT_L(8); PG8_BAR; PG8_WAIT_L(0); PG8_MMA(0, 0, At, B0); PG8_BAR; PG8_SCHED;
;             PG8_LDB(B1, 0, 1); PG8_STAGE(PG8_SB(0, 0), b2, voffB);
;             PG8_BAR; PG8_WAIT_L(0); PG8_MMA(0, 1, At, B1); PG8_BAR;
;             PG8_LDA(At, 0, 1); PG8_STAGE(PG8_SA(0, 0), a2, voffA);
;             PG8_BAR; PG8_WAIT_L(0); PG8_MMA(1, 0, At, B0); PG8_BAR; PG8_SCHED;
.LBB0_848:
	s_ashr_i32 s17, s16, 31
	v_cmp_lt_i64_e32 vcc, s[18:19], v[140:141]
	s_lshl_b64 s[18:19], s[16:17], 19
	s_add_u32 s18, s41, s18
	s_addc_u32 s19, s42, s19
	s_and_b64 s[20:21], vcc, exec
	s_cselect_b32 s17, s19, s25
	s_cselect_b32 s59, s18, s24
	s_ashr_i32 s15, s14, 31
	s_lshl_b64 s[20:21], s[14:15], 19
	s_add_u32 s20, s43, s20
	s_addc_u32 s21, s44, s21
	s_and_b64 s[38:39], vcc, exec
	s_cselect_b32 s15, s21, s37
	s_cselect_b32 s60, s20, s36
	s_add_u32 s24, s24, 0x40080
	s_addc_u32 s25, s25, 0
	s_add_u32 s61, s36, 0x100
	s_addc_u32 s62, s37, 0
	s_mov_b32 s63, -2
	ds_read_b128 v[152:155], v149
	ds_read_b128 v[156:159], v149 offset:1024
	ds_read_b128 v[160:163], v149 offset:2048
	ds_read_b128 v[164:167], v149 offset:3072
	s_add_u32 s36, s24, 0xfffc0080
	s_addc_u32 s37, s25, -1
	s_cmp_eq_u32 s63, 12
	s_cselect_b32 s39, s17, s37
	s_cselect_b32 s38, s59, s36
	s_cselect_b32 s37, s15, s62
	s_cselect_b32 s36, s60, s61
	s_add_i32 m0, s23, 0xc000
	ds_read_b128 v[168:171], v150
	ds_read_b128 v[172:175], v150 offset:1024
	ds_read_b128 v[176:179], v150 offset:2048
	ds_read_b128 v[182:185], v150 offset:3072
	ds_read_b128 v[186:189], v150 offset:4096
	ds_read_b128 v[190:193], v150 offset:5120
	ds_read_b128 v[194:197], v150 offset:6144
	ds_read_b128 v[198:201], v150 offset:7168
	global_load_lds_dwordx4 v136, s[24:25]
	s_add_i32 m0, s23, 0xe000
	s_nop 0
	global_load_lds_dwordx4 v138, s[24:25]
	s_waitcnt lgkmcnt(8)
	s_barrier
	s_waitcnt lgkmcnt(7)
	v_mfma_f32_16x16x32_bf16 v[124:127], v[152:155], v[168:171], 0
	v_mfma_f32_16x16x32_bf16 v[120:123], v[160:163], v[168:171], 0
	s_waitcnt lgkmcnt(5)
	v_mfma_f32_16x16x32_bf16 v[108:111], v[152:155], v[176:179], 0
	v_mfma_f32_16x16x32_bf16 v[104:107], v[160:163], v[176:179], 0
	s_waitcnt lgkmcnt(3)
	v_mfma_f32_16x16x32_bf16 v[92:95], v[152:155], v[186:189], 0
	v_mfma_f32_16x16x32_bf16 v[88:91], v[160:163], v[186:189], 0
	s_waitcnt lgkmcnt(1)
	v_mfma_f32_16x16x32_bf16 v[76:79], v[152:155], v[194:197], 0
	v_mfma_f32_16x16x32_bf16 v[72:75], v[160:163], v[194:197], 0
	v_mfma_f32_16x16x32_bf16 v[124:127], v[156:159], v[172:175], v[124:127]
	v_mfma_f32_16x16x32_bf16 v[120:123], v[164:167], v[172:175], v[120:123]
	v_mfma_f32_16x16x32_bf16 v[108:111], v[156:159], v[182:185], v[108:111]
	v_mfma_f32_16x16x32_bf16 v[104:107], v[164:167], v[182:185], v[104:107]
	v_mfma_f32_16x16x32_bf16 v[92:95], v[156:159], v[190:193], v[92:95]
	v_mfma_f32_16x16x32_bf16 v[88:91], v[164:167], v[190:193], v[88:91]
	s_waitcnt lgkmcnt(0)
	v_mfma_f32_16x16x32_bf16 v[76:79], v[156:159], v[198:201], v[76:79]
	v_mfma_f32_16x16x32_bf16 v[72:75], v[164:167], v[198:201], v[72:75]
	s_barrier
	s_add_i32 s64, s55, s45
	s_add_u32 s86, s36, s12
	s_addc_u32 s87, s37, s13
	s_mov_b32 m0, s64
	ds_read_b128 v[202:205], v151
	ds_read_b128 v[206:209], v151 offset:1024
	ds_read_b128 v[210:213], v151 offset:2048
	ds_read_b128 v[214:217], v151 offset:3072
	global_load_lds_dwordx4 v132, s[36:37]
	s_add_i32 m0, s64, 0x2000
	s_nop 0
	global_load_lds_dwordx4 v128, s[36:37]
	s_barrier
	s_waitcnt lgkmcnt(3)
	v_mfma_f32_16x16x32_bf16 v[116:119], v[202:205], v[168:171], 0
	s_waitcnt lgkmcnt(1)
	v_mfma_f32_16x16x32_bf16 v[112:115], v[210:213], v[168:171], 0
	v_mfma_f32_16x16x32_bf16 v[100:103], v[202:205], v[176:179], 0
	v_mfma_f32_16x16x32_bf16 v[96:99], v[210:213], v[176:179], 0
	v_mfma_f32_16x16x32_bf16 v[84:87], v[202:205], v[186:189], 0
	v_mfma_f32_16x16x32_bf16 v[80:83], v[210:213], v[186:189], 0
	v_mfma_f32_16x16x32_bf16 v[68:71], v[202:205], v[194:197], 0
	v_mfma_f32_16x16x32_bf16 v[64:67], v[210:213], v[194:197], 0
	v_mfma_f32_16x16x32_bf16 v[116:119], v[206:209], v[172:175], v[116:119]
	s_waitcnt lgkmcnt(0)
	v_mfma_f32_16x16x32_bf16 v[112:115], v[214:217], v[172:175], v[112:115]
	v_mfma_f32_16x16x32_bf16 v[100:103], v[206:209], v[182:185], v[100:103]
	v_mfma_f32_16x16x32_bf16 v[96:99], v[214:217], v[182:185], v[96:99]
	v_mfma_f32_16x16x32_bf16 v[84:87], v[206:209], v[190:193], v[84:87]
	v_mfma_f32_16x16x32_bf16 v[80:83], v[214:217], v[190:193], v[80:83]
	v_mfma_f32_16x16x32_bf16 v[68:71], v[206:209], v[198:201], v[68:71]
	v_mfma_f32_16x16x32_bf16 v[64:67], v[214:217], v[198:201], v[64:67]
	s_mov_b32 m0, s23
	s_add_u32 s88, s38, s12
	s_addc_u32 s89, s39, s13
	s_barrier
	ds_read_b128 v[168:171], v150 offset:16384
	ds_read_b128 v[172:175], v150 offset:17408
	ds_read_b128 v[176:179], v150 offset:18432
	ds_read_b128 v[182:185], v150 offset:19456
	ds_read_b128 v[186:189], v150 offset:20480
	ds_read_b128 v[190:193], v150 offset:21504
	ds_read_b128 v[194:197], v150 offset:22528
	ds_read_b128 v[198:201], v150 offset:23552
	global_load_lds_dwordx4 v134, s[38:39]
	s_mov_b32 m0, s48
	s_nop 0
	global_load_lds_dwordx4 v130, s[38:39]
	s_barrier
	s_waitcnt lgkmcnt(7)
	v_mfma_f32_16x16x32_bf16 v[60:63], v[152:155], v[168:171], 0
	v_mfma_f32_16x16x32_bf16 v[56:59], v[160:163], v[168:171], 0
	s_waitcnt lgkmcnt(5)
	v_mfma_f32_16x16x32_bf16 v[44:47], v[152:155], v[176:179], 0
	v_mfma_f32_16x16x32_bf16 v[40:43], v[160:163], v[176:179], 0
	s_waitcnt lgkmcnt(3)
	v_mfma_f32_16x16x32_bf16 v[28:31], v[152:155], v[186:189], 0
	v_mfma_f32_16x16x32_bf16 v[24:27], v[160:163], v[186:189], 0
	s_waitcnt lgkmcnt(1)
	v_mfma_f32_16x16x32_bf16 v[12:15], v[152:155], v[194:197], 0
	v_mfma_f32_16x16x32_bf16 v[8:11], v[160:163], v[194:197], 0
	v_mfma_f32_16x16x32_bf16 v[60:63], v[156:159], v[172:175], v[60:63]
	v_mfma_f32_16x16x32_bf16 v[56:59], v[164:167], v[172:175], v[56:59]
	v_mfma_f32_16x16x32_bf16 v[44:47], v[156:159], v[182:185], v[44:47]
	v_mfma_f32_16x16x32_bf16 v[40:43], v[164:167], v[182:185], v[40:43]
	v_mfma_f32_16x16x32_bf16 v[28:31], v[156:159], v[190:193], v[28:31]
	v_mfma_f32_16x16x32_bf16 v[24:27], v[164:167], v[190:193], v[24:27]
	s_waitcnt lgkmcnt(0)
	v_mfma_f32_16x16x32_bf16 v[12:15], v[156:159], v[198:201], v[12:15]
	v_mfma_f32_16x16x32_bf16 v[8:11], v[164:167], v[198:201], v[8:11]
	s_barrier
; #define PG8_STAGE(bufoff, gbase, voff) do { _Pragma("unroll") for (int _i = 0; _i < 2; ++_i) \
;         __builtin_amdgcn_global_load_lds((const unsigned*)((const char*)(gbase) + (voff)[_i]), (LAS unsigned*)(lds + (bufoff) + ldsw + _i * 8192), 16, 0, 0); } while (0)
; #define PG8_LDA(dst, b, h) do { _Pragma("unroll") for (int m = 0; m < 4; ++m) _Pragma("unroll") for (int k = 0; k < 2; ++k) dst[m][k] = *(const LAS bf16x8*)(lds + PG8_SA(b, h) + aoff + m * 2048 + k * 1024); } while (0)
; #define PG8_LDB(dst, b, h) do { _Pragma("unroll") for (int n = 0; n < 2; ++n) _Pragma("unroll") for (int k = 0; k < 2; ++k) dst[n][k] = *(const LAS bf16x8*)(lds + PG8_SB(b, h) + boff + n * 2048 + k * 1024); } while (0)
; #define PG8_MMA(ai, bj, At, Bt) do { __builtin_amdgcn_s_setprio(1); _Pragma("unroll") for (int m = 0; m < 4; ++m) _Pragma("unroll") for (int n = 0; n < 2; ++n) _Pragma("unroll") for (int k = 0; k < 2; ++k) \
;         acc[ai][bj][m][n] = __builtin_amdgcn_mfma_f32_16x16x32_bf16(Bt[n][k], At[m][k], acc[ai][bj][m][n], 0, 0, 0); __builtin_amdgcn_s_setprio(0); } while (0)
; #define PG8_WAIT_V(n) asm volatile("s_waitcnt vmcnt(" #n ")" ::: "memory")
; #define PG8_WAIT_L(n) asm volatile("s_waitcnt lgkmcnt(" #n ")" ::: "memory")
; #define PG8_BAR __builtin_amdgcn_s_barrier()
; #define PG8_SCHED __builtin_amdgcn_sched_barrier(0)
; template <class Epi>
; DI void gemm_phase(LAS unsigned char* lds, const Gemm g, const StaticOrder& S, const Epi& E) {
;     ...
;             PG8_STAGE(PG8_SB(0, 1), b2 + hstep, voffB);
;             PG8_WAIT_V(6); PG8_BAR; PG8_MMA(1, 1, At, B1); PG8_BAR;
;             PG8_LDB(B0, 1, 0); PG8_SCHED; PG8_LDA(At, 1, 0); PG8_STAGE(PG8_SA(0, 1), a2 + hstep, voffA);
;             PG8_WAIT_L(8); PG8_BAR; PG8_WAIT_L(0); PG8_MMA(0, 0, At, B0); PG8_BAR; PG8_SCHED;
;             PG8_LDB(B1, 1, 1); PG8_STAGE(PG8_SB(1, 0), b3, voffB);
;             PG8_BAR; PG8_WAIT_L(0); PG8_MMA(0, 1, At, B1); PG8_BAR;
;             PG8_LDA(At, 1, 1); PG8_STAGE(PG8_SA(1, 0), a3, voffA);
	s_add_u32 s64, s36, 0x40000
	s_addc_u32 s65, s37, 0
	s_add_i32 s66, s56, s45
	s_mov_b32 m0, s66
	s_nop 0
	global_load_lds_dwordx4 v132, s[64:65]
	s_add_i32 m0, s66, 0x2000
	s_nop 0
	global_load_lds_dwordx4 v128, s[64:65]
	s_waitcnt vmcnt(6)
	s_barrier
	v_mfma_f32_16x16x32_bf16 v[52:55], v[202:205], v[168:171], 0
	v_mfma_f32_16x16x32_bf16 v[48:51], v[210:213], v[168:171], 0
	v_mfma_f32_16x16x32_bf16 v[36:39], v[202:205], v[176:179], 0
	v_mfma_f32_16x16x32_bf16 v[32:35], v[210:213], v[176:179], 0
	v_mfma_f32_16x16x32_bf16 v[20:23], v[202:205], v[186:189], 0
	v_mfma_f32_16x16x32_bf16 v[16:19], v[210:213], v[186:189], 0
	v_mfma_f32_16x16x32_bf16 v[4:7], v[202:205], v[194:197], 0
	v_mfma_f32_16x16x32_bf16 v[0:3], v[210:213], v[194:197], 0
	v_mfma_f32_16x16x32_bf16 v[52:55], v[206:209], v[172:175], v[52:55]
	v_mfma_f32_16x16x32_bf16 v[48:51], v[214:217], v[172:175], v[48:51]
	v_mfma_f32_16x16x32_bf16 v[36:39], v[206:209], v[182:185], v[36:39]
	v_mfma_f32_16x16x32_bf16 v[32:35], v[214:217], v[182:185], v[32:35]
	v_mfma_f32_16x16x32_bf16 v[20:23], v[206:209], v[190:193], v[20:23]
	v_mfma_f32_16x16x32_bf16 v[16:19], v[214:217], v[190:193], v[16:19]
	v_mfma_f32_16x16x32_bf16 v[4:7], v[206:209], v[198:201], v[4:7]
	v_mfma_f32_16x16x32_bf16 v[0:3], v[214:217], v[198:201], v[0:3]
	s_add_i32 s64, 0, 0x18000
	v_add_u32_e32 v164, s64, v147
	s_barrier
	ds_read_b128 v[152:155], v164
	ds_read_b128 v[156:159], v164 offset:1024
	ds_read_b128 v[160:163], v164 offset:2048
	ds_read_b128 v[164:167], v164 offset:3072
	s_add_u32 s38, s38, 0x40000
	s_addc_u32 s39, s39, 0
	s_mov_b32 m0, s49
	ds_read_b128 v[168:171], v150 offset:32768
	ds_read_b128 v[172:175], v150 offset:33792
	ds_read_b128 v[176:179], v150 offset:34816
	ds_read_b128 v[182:185], v150 offset:35840
	ds_read_b128 v[186:189], v150 offset:36864
	ds_read_b128 v[190:193], v150 offset:37888
	ds_read_b128 v[194:197], v150 offset:38912
	ds_read_b128 v[198:201], v150 offset:39936
	global_load_lds_dwordx4 v134, s[38:39]
	s_mov_b32 m0, s50
	s_nop 0
	global_load_lds_dwordx4 v130, s[38:39]
	s_waitcnt lgkmcnt(8)
	s_barrier
	s_waitcnt lgkmcnt(7)
	v_mfma_f32_16x16x32_bf16 v[124:127], v[152:155], v[168:171], v[124:127]
	v_mfma_f32_16x16x32_bf16 v[120:123], v[160:163], v[168:171], v[120:123]
	s_waitcnt lgkmcnt(5)
	v_mfma_f32_16x16x32_bf16 v[108:111], v[152:155], v[176:179], v[108:111]
	v_mfma_f32_16x16x32_bf16 v[104:107], v[160:163], v[176:179], v[104:107]
	s_waitcnt lgkmcnt(3)
	v_mfma_f32_16x16x32_bf16 v[92:95], v[152:155], v[186:189], v[92:95]
	v_mfma_f32_16x16x32_bf16 v[88:91], v[160:163], v[186:189], v[88:91]
	s_waitcnt lgkmcnt(1)
	v_mfma_f32_16x16x32_bf16 v[76:79], v[152:155], v[194:197], v[76:79]
	v_mfma_f32_16x16x32_bf16 v[72:75], v[160:163], v[194:197], v[72:75]
	v_mfma_f32_16x16x32_bf16 v[124:127], v[156:159], v[172:175], v[124:127]
	v_mfma_f32_16x16x32_bf16 v[120:123], v[164:167], v[172:175], v[120:123]
	v_mfma_f32_16x16x32_bf16 v[108:111], v[156:159], v[182:185], v[108:111]
	v_mfma_f32_16x16x32_bf16 v[104:107], v[164:167], v[182:185], v[104:107]
	v_mfma_f32_16x16x32_bf16 v[92:95], v[156:159], v[190:193], v[92:95]
	v_mfma_f32_16x16x32_bf16 v[88:91], v[164:167], v[190:193], v[88:91]
	s_waitcnt lgkmcnt(0)
	v_mfma_f32_16x16x32_bf16 v[76:79], v[156:159], v[198:201], v[76:79]
	v_mfma_f32_16x16x32_bf16 v[72:75], v[164:167], v[198:201], v[72:75]
	s_barrier
	s_add_i32 s38, 0, 0x1c000
	s_add_i32 s39, s64, s45
	v_add_u32_e32 v214, s38, v147
	s_mov_b32 m0, s39
	ds_read_b128 v[202:205], v214
	ds_read_b128 v[206:209], v214 offset:1024
	ds_read_b128 v[210:213], v214 offset:2048
	ds_read_b128 v[214:217], v214 offset:3072
	global_load_lds_dwordx4 v132, s[86:87]
	s_add_i32 m0, s39, 0x2000
	s_nop 0
	global_load_lds_dwordx4 v128, s[86:87]
	s_barrier
	s_waitcnt lgkmcnt(3)
	v_mfma_f32_16x16x32_bf16 v[116:119], v[202:205], v[168:171], v[116:119]
	s_waitcnt lgkmcnt(1)
	v_mfma_f32_16x16x32_bf16 v[112:115], v[210:213], v[168:171], v[112:115]
	v_mfma_f32_16x16x32_bf16 v[100:103], v[202:205], v[176:179], v[100:103]
	v_mfma_f32_16x16x32_bf16 v[96:99], v[210:213], v[176:179], v[96:99]
	v_mfma_f32_16x16x32_bf16 v[84:87], v[202:205], v[186:189], v[84:87]
	v_mfma_f32_16x16x32_bf16 v[80:83], v[210:213], v[186:189], v[80:83]
	v_mfma_f32_16x16x32_bf16 v[68:71], v[202:205], v[194:197], v[68:71]
	v_mfma_f32_16x16x32_bf16 v[64:67], v[210:213], v[194:197], v[64:67]
	v_mfma_f32_16x16x32_bf16 v[116:119], v[206:209], v[172:175], v[116:119]
	s_waitcnt lgkmcnt(0)
	v_mfma_f32_16x16x32_bf16 v[112:115], v[214:217], v[172:175], v[112:115]
	v_mfma_f32_16x16x32_bf16 v[100:103], v[206:209], v[182:185], v[100:103]
	v_mfma_f32_16x16x32_bf16 v[96:99], v[214:217], v[182:185], v[96:99]
	v_mfma_f32_16x16x32_bf16 v[84:87], v[206:209], v[190:193], v[84:87]
	v_mfma_f32_16x16x32_bf16 v[80:83], v[214:217], v[190:193], v[80:83]
	v_mfma_f32_16x16x32_bf16 v[68:71], v[206:209], v[198:201], v[68:71]
	v_mfma_f32_16x16x32_bf16 v[64:67], v[214:217], v[198:201], v[64:67]
	s_mov_b32 m0, s52
	s_barrier
	ds_read_b128 v[168:171], v150 offset:49152
	ds_read_b128 v[172:175], v150 offset:50176
	ds_read_b128 v[176:179], v150 offset:51200
	ds_read_b128 v[182:185], v150 offset:52224
	ds_read_b128 v[186:189], v150 offset:53248
	ds_read_b128 v[190:193], v150 offset:54272
	ds_read_b128 v[194:197], v150 offset:55296
	ds_read_b128 v[198:201], v150 offset:56320
	global_load_lds_dwordx4 v134, s[88:89]
	s_mov_b32 m0, s53
	s_nop 0
	global_load_lds_dwordx4 v130, s[88:89]
	s_barrier
; #define PG8_STAGE(bufoff, gbase, voff) do { _Pragma("unroll") for (int _i = 0; _i < 2; ++_i) \
;         __builtin_amdgcn_global_load_lds((const unsigned*)((const char*)(gbase) + (voff)[_i]), (LAS unsigned*)(lds + (bufoff) + ldsw + _i * 8192), 16, 0, 0); } while (0)
; #define PG8_LDA(dst, b, h) do { _Pragma("unroll") for (int m = 0; m < 4; ++m) _Pragma("unroll") for (int k = 0; k < 2; ++k) dst[m][k] = *(const LAS bf16x8*)(lds + PG8_SA(b, h) + aoff + m * 2048 + k * 1024); } while (0)
; #define PG8_LDB(dst, b, h) do { _Pragma("unroll") for (int n = 0; n < 2; ++n) _Pragma("unroll") for (int k = 0; k < 2; ++k) dst[n][k] = *(const LAS bf16x8*)(lds + PG8_SB(b, h) + boff + n * 2048 + k * 1024); } while (0)
; #define PG8_MMA(ai, bj, At, Bt) do { __builtin_amdgcn_s_setprio(1); _Pragma("unroll") for (int m = 0; m < 4; ++m) _Pragma("unroll") for (int n = 0; n < 2; ++n) _Pragma("unroll") for (int k = 0; k < 2; ++k) \
;         acc[ai][bj][m][n] = __builtin_amdgcn_mfma_f32_16x16x32_bf16(Bt[n][k], At[m][k], acc[ai][bj][m][n], 0, 0, 0); __builtin_amdgcn_s_setprio(0); } while (0)
; #define PG8_WAIT_V(n) asm volatile("s_waitcnt vmcnt(" #n ")" ::: "memory")
; #define PG8_WAIT_L(n) asm volatile("s_waitcnt lgkmcnt(" #n ")" ::: "memory")
; #define PG8_BAR __builtin_amdgcn_s_barrier()
; #define PG8_SCHED __builtin_amdgcn_sched_barrier(0)
; template <class Epi>
; DI void gemm_phase(LAS unsigned char* lds, const Gemm g, const StaticOrder& S, const Epi& E) {
;     ...
;         for (int t = 0; t < nt; t += 2) {
;             const bool last = (t == nt - 2);
;             const char* a1 = cA + (size_t)(t + 1) * kstep;
;             const char* a2 = last ? nA : cA + (size_t)(t + 2) * kstep; const char* b2 = last ? nB : cB + (size_t)(t + 2) * kstep;
;             const char* a3 = a2 + kstep; const char* b3 = b2 + kstep;
;             PG8_LDB(B0, 0, 0); PG8_SCHED; PG8_LDA(At, 0, 0); PG8_STAGE(PG8_SA(1, 1), a1 + hstep, voffA);
;             PG8_WAIT_L(8); PG8_BAR; PG8_WAIT_L(0); PG8_MMA(0, 0, At, B0); PG8_BAR; PG8_SCHED;
;             PG8_LDB(B1, 0, 1); PG8_STAGE(PG8_SB(0, 0), b2, voffB);
;     ...
;             PG8_LDA(At, 1, 1); PG8_STAGE(PG8_SA(1, 0), a3, voffA);
;             PG8_BAR; PG8_WAIT_L(0); PG8_MMA(1, 0, At, B0); PG8_BAR; PG8_SCHED;
;             PG8_STAGE(PG8_SB(1, 1), b3 + hstep, voffB);
;             PG8_WAIT_V(6); PG8_BAR; PG8_MMA(1, 1, At, B1); PG8_BAR;
	s_waitcnt lgkmcnt(7)
	v_mfma_f32_16x16x32_bf16 v[60:63], v[152:155], v[168:171], v[60:63]
	v_mfma_f32_16x16x32_bf16 v[56:59], v[160:163], v[168:171], v[56:59]
	s_waitcnt lgkmcnt(5)
	v_mfma_f32_16x16x32_bf16 v[44:47], v[152:155], v[176:179], v[44:47]
	v_mfma_f32_16x16x32_bf16 v[40:43], v[160:163], v[176:179], v[40:43]
	s_waitcnt lgkmcnt(3)
	v_mfma_f32_16x16x32_bf16 v[28:31], v[152:155], v[186:189], v[28:31]
	v_mfma_f32_16x16x32_bf16 v[24:27], v[160:163], v[186:189], v[24:27]
	s_waitcnt lgkmcnt(1)
	v_mfma_f32_16x16x32_bf16 v[12:15], v[152:155], v[194:197], v[12:15]
	v_mfma_f32_16x16x32_bf16 v[8:11], v[160:163], v[194:197], v[8:11]
	v_mfma_f32_16x16x32_bf16 v[60:63], v[156:159], v[172:175], v[60:63]
	v_mfma_f32_16x16x32_bf16 v[56:59], v[164:167], v[172:175], v[56:59]
	v_mfma_f32_16x16x32_bf16 v[44:47], v[156:159], v[182:185], v[44:47]
	v_mfma_f32_16x16x32_bf16 v[40:43], v[164:167], v[182:185], v[40:43]
	v_mfma_f32_16x16x32_bf16 v[28:31], v[156:159], v[190:193], v[28:31]
	v_mfma_f32_16x16x32_bf16 v[24:27], v[164:167], v[190:193], v[24:27]
	s_waitcnt lgkmcnt(0)
	v_mfma_f32_16x16x32_bf16 v[12:15], v[156:159], v[198:201], v[12:15]
	v_mfma_f32_16x16x32_bf16 v[8:11], v[164:167], v[198:201], v[8:11]
	s_barrier
	s_add_u32 s36, s36, 0x40080
	s_addc_u32 s37, s37, 0
	s_add_i32 s38, s38, s45
	s_mov_b32 m0, s38
	s_nop 0
	global_load_lds_dwordx4 v132, s[36:37]
	s_add_i32 m0, s38, 0x2000
	s_nop 0
	global_load_lds_dwordx4 v128, s[36:37]
	s_waitcnt vmcnt(6)
	s_barrier
	v_mfma_f32_16x16x32_bf16 v[52:55], v[202:205], v[168:171], v[52:55]
	v_mfma_f32_16x16x32_bf16 v[48:51], v[210:213], v[168:171], v[48:51]
	v_mfma_f32_16x16x32_bf16 v[36:39], v[202:205], v[176:179], v[36:39]
	v_mfma_f32_16x16x32_bf16 v[32:35], v[210:213], v[176:179], v[32:35]
	v_mfma_f32_16x16x32_bf16 v[20:23], v[202:205], v[186:189], v[20:23]
	v_mfma_f32_16x16x32_bf16 v[16:19], v[210:213], v[186:189], v[16:19]
	v_mfma_f32_16x16x32_bf16 v[4:7], v[202:205], v[194:197], v[4:7]
	v_mfma_f32_16x16x32_bf16 v[0:3], v[210:213], v[194:197], v[0:3]
	v_mfma_f32_16x16x32_bf16 v[52:55], v[206:209], v[172:175], v[52:55]
	v_mfma_f32_16x16x32_bf16 v[48:51], v[214:217], v[172:175], v[48:51]
	v_mfma_f32_16x16x32_bf16 v[36:39], v[206:209], v[182:185], v[36:39]
	v_mfma_f32_16x16x32_bf16 v[32:35], v[214:217], v[182:185], v[32:35]
	v_mfma_f32_16x16x32_bf16 v[20:23], v[206:209], v[190:193], v[20:23]
	v_mfma_f32_16x16x32_bf16 v[16:19], v[214:217], v[190:193], v[16:19]
	v_mfma_f32_16x16x32_bf16 v[4:7], v[206:209], v[198:201], v[4:7]
	v_mfma_f32_16x16x32_bf16 v[0:3], v[214:217], v[198:201], v[0:3]
	s_add_i32 s63, s63, 2
	s_add_u32 s24, s24, 0x100
	s_addc_u32 s25, s25, 0
	s_add_u32 s61, s61, 0x100
	s_addc_u32 s62, s62, 0
	s_cmp_gt_u32 s63, 13
	s_barrier
.LBB0_849:
	ds_read_b128 v[152:155], v149
	ds_read_b128 v[156:159], v149 offset:1024
	ds_read_b128 v[160:163], v149 offset:2048
	ds_read_b128 v[164:167], v149 offset:3072
	s_add_u32 s36, s24, 0xfffc0080
	s_addc_u32 s37, s25, -1
	s_cmp_eq_u32 s63, 12
	s_cselect_b32 s39, s17, s37
	s_cselect_b32 s38, s59, s36
	s_cselect_b32 s37, s15, s62
	s_cselect_b32 s36, s60, s61
	s_add_i32 m0, s23, 0xc000
	ds_read_b128 v[168:171], v150
	ds_read_b128 v[172:175], v150 offset:1024
	ds_read_b128 v[176:179], v150 offset:2048
	ds_read_b128 v[182:185], v150 offset:3072
	ds_read_b128 v[186:189], v150 offset:4096
	ds_read_b128 v[190:193], v150 offset:5120
	ds_read_b128 v[194:197], v150 offset:6144
	ds_read_b128 v[198:201], v150 offset:7168
	global_load_lds_dwordx4 v136, s[24:25]
	s_add_i32 m0, s23, 0xe000
	s_nop 0
	global_load_lds_dwordx4 v138, s[24:25]
	s_waitcnt lgkmcnt(8)
	s_barrier
	s_waitcnt lgkmcnt(7)
	v_mfma_f32_16x16x32_bf16 v[124:127], v[152:155], v[168:171], v[124:127]
	v_mfma_f32_16x16x32_bf16 v[120:123], v[160:163], v[168:171], v[120:123]
	s_waitcnt lgkmcnt(5)
	v_mfma_f32_16x16x32_bf16 v[108:111], v[152:155], v[176:179], v[108:111]
	v_mfma_f32_16x16x32_bf16 v[104:107], v[160:163], v[176:179], v[104:107]
	s_waitcnt lgkmcnt(3)
	v_mfma_f32_16x16x32_bf16 v[92:95], v[152:155], v[186:189], v[92:95]
	v_mfma_f32_16x16x32_bf16 v[88:91], v[160:163], v[186:189], v[88:91]
	s_waitcnt lgkmcnt(1)
	v_mfma_f32_16x16x32_bf16 v[76:79], v[152:155], v[194:197], v[76:79]
	v_mfma_f32_16x16x32_bf16 v[72:75], v[160:163], v[194:197], v[72:75]
	v_mfma_f32_16x16x32_bf16 v[124:127], v[156:159], v[172:175], v[124:127]
	v_mfma_f32_16x16x32_bf16 v[120:123], v[164:167], v[172:175], v[120:123]
	v_mfma_f32_16x16x32_bf16 v[108:111], v[156:159], v[182:185], v[108:111]
	v_mfma_f32_16x16x32_bf16 v[104:107], v[164:167], v[182:185], v[104:107]
	v_mfma_f32_16x16x32_bf16 v[92:95], v[156:159], v[190:193], v[92:95]
	v_mfma_f32_16x16x32_bf16 v[88:91], v[164:167], v[190:193], v[88:91]
	s_waitcnt lgkmcnt(0)
	v_mfma_f32_16x16x32_bf16 v[76:79], v[156:159], v[198:201], v[76:79]
	v_mfma_f32_16x16x32_bf16 v[72:75], v[164:167], v[198:201], v[72:75]
	s_barrier
	s_add_i32 s64, s55, s45
	s_add_u32 s86, s36, s12
	s_addc_u32 s87, s37, s13
	s_mov_b32 m0, s64
	ds_read_b128 v[202:205], v151
	ds_read_b128 v[206:209], v151 offset:1024
	ds_read_b128 v[210:213], v151 offset:2048
	ds_read_b128 v[214:217], v151 offset:3072
	global_load_lds_dwordx4 v132, s[36:37]
	s_add_i32 m0, s64, 0x2000
	s_nop 0
	global_load_lds_dwordx4 v128, s[36:37]
	s_barrier
; #define PG8_STAGE(bufoff, gbase, voff) do { _Pragma("unroll") for (int _i = 0; _i < 2; ++_i) \
;         __builtin_amdgcn_global_load_lds((const unsigned*)((const char*)(gbase) + (voff)[_i]), (LAS unsigned*)(lds + (bufoff) + ldsw + _i * 8192), 16, 0, 0); } while (0)
; #define PG8_LDA(dst, b, h) do { _Pragma("unroll") for (int m = 0; m < 4; ++m) _Pragma("unroll") for (int k = 0; k < 2; ++k) dst[m][k] = *(const LAS bf16x8*)(lds + PG8_SA(b, h) + aoff + m * 2048 + k * 1024); } while (0)
; #define PG8_LDB(dst, b, h) do { _Pragma("unroll") for (int n = 0; n < 2; ++n) _Pragma("unroll") for (int k = 0; k < 2; ++k) dst[n][k] = *(const LAS bf16x8*)(lds + PG8_SB(b, h) + boff + n * 2048 + k * 1024); } while (0)
; #define PG8_MMA(ai, bj, At, Bt) do { __builtin_amdgcn_s_setprio(1); _Pragma("unroll") for (int m = 0; m < 4; ++m) _Pragma("unroll") for (int n = 0; n < 2; ++n) _Pragma("unroll") for (int k = 0; k < 2; ++k) \
;         acc[ai][bj][m][n] = __builtin_amdgcn_mfma_f32_16x16x32_bf16(Bt[n][k], At[m][k], acc[ai][bj][m][n], 0, 0, 0); __builtin_amdgcn_s_setprio(0); } while (0)
; #define PG8_WAIT_V(n) asm volatile("s_waitcnt vmcnt(" #n ")" ::: "memory")
; #define PG8_WAIT_L(n) asm volatile("s_waitcnt lgkmcnt(" #n ")" ::: "memory")
; #define PG8_BAR __builtin_amdgcn_s_barrier()
; #define PG8_SCHED __builtin_amdgcn_sched_barrier(0)
; template <class Epi>
; DI void gemm_phase(LAS unsigned char* lds, const Gemm g, const StaticOrder& S, const Epi& E) {
;     ...
;             PG8_BAR; PG8_WAIT_L(0); PG8_MMA(0, 1, At, B1); PG8_BAR;
;             PG8_LDA(At, 0, 1); PG8_STAGE(PG8_SA(0, 0), a2, voffA);
;             PG8_BAR; PG8_WAIT_L(0); PG8_MMA(1, 0, At, B0); PG8_BAR; PG8_SCHED;
;             PG8_STAGE(PG8_SB(0, 1), b2 + hstep, voffB);
;             PG8_WAIT_V(6); PG8_BAR; PG8_MMA(1, 1, At, B1); PG8_BAR;
;             PG8_LDB(B0, 1, 0); PG8_SCHED; PG8_LDA(At, 1, 0); PG8_STAGE(PG8_SA(0, 1), a2 + hstep, voffA);
;             PG8_WAIT_L(8); PG8_BAR; PG8_WAIT_L(0); PG8_MMA(0, 0, At, B0); PG8_BAR; PG8_SCHED;
	s_waitcnt lgkmcnt(3)
	v_mfma_f32_16x16x32_bf16 v[116:119], v[202:205], v[168:171], v[116:119]
	s_waitcnt lgkmcnt(1)
	v_mfma_f32_16x16x32_bf16 v[112:115], v[210:213], v[168:171], v[112:115]
	v_mfma_f32_16x16x32_bf16 v[100:103], v[202:205], v[176:179], v[100:103]
	v_mfma_f32_16x16x32_bf16 v[96:99], v[210:213], v[176:179], v[96:99]
	v_mfma_f32_16x16x32_bf16 v[84:87], v[202:205], v[186:189], v[84:87]
	v_mfma_f32_16x16x32_bf16 v[80:83], v[210:213], v[186:189], v[80:83]
	v_mfma_f32_16x16x32_bf16 v[68:71], v[202:205], v[194:197], v[68:71]
	v_mfma_f32_16x16x32_bf16 v[64:67], v[210:213], v[194:197], v[64:67]
	v_mfma_f32_16x16x32_bf16 v[116:119], v[206:209], v[172:175], v[116:119]
	s_waitcnt lgkmcnt(0)
	v_mfma_f32_16x16x32_bf16 v[112:115], v[214:217], v[172:175], v[112:115]
	v_mfma_f32_16x16x32_bf16 v[100:103], v[206:209], v[182:185], v[100:103]
	v_mfma_f32_16x16x32_bf16 v[96:99], v[214:217], v[182:185], v[96:99]
	v_mfma_f32_16x16x32_bf16 v[84:87], v[206:209], v[190:193], v[84:87]
	v_mfma_f32_16x16x32_bf16 v[80:83], v[214:217], v[190:193], v[80:83]
	v_mfma_f32_16x16x32_bf16 v[68:71], v[206:209], v[198:201], v[68:71]
	v_mfma_f32_16x16x32_bf16 v[64:67], v[214:217], v[198:201], v[64:67]
	s_mov_b32 m0, s23
	s_add_u32 s88, s38, s12
	s_addc_u32 s89, s39, s13
	s_barrier
	ds_read_b128 v[168:171], v150 offset:16384
	ds_read_b128 v[172:175], v150 offset:17408
	ds_read_b128 v[176:179], v150 offset:18432
	ds_read_b128 v[182:185], v150 offset:19456
	ds_read_b128 v[186:189], v150 offset:20480
	ds_read_b128 v[190:193], v150 offset:21504
	ds_read_b128 v[194:197], v150 offset:22528
	ds_read_b128 v[198:201], v150 offset:23552
	global_load_lds_dwordx4 v134, s[38:39]
	s_mov_b32 m0, s48
	s_nop 0
	global_load_lds_dwordx4 v130, s[38:39]
	s_barrier
	s_waitcnt lgkmcnt(7)
	v_mfma_f32_16x16x32_bf16 v[60:63], v[152:155], v[168:171], v[60:63]
	v_mfma_f32_16x16x32_bf16 v[56:59], v[160:163], v[168:171], v[56:59]
	s_waitcnt lgkmcnt(5)
	v_mfma_f32_16x16x32_bf16 v[44:47], v[152:155], v[176:179], v[44:47]
	v_mfma_f32_16x16x32_bf16 v[40:43], v[160:163], v[176:179], v[40:43]
	s_waitcnt lgkmcnt(3)
	v_mfma_f32_16x16x32_bf16 v[28:31], v[152:155], v[186:189], v[28:31]
	v_mfma_f32_16x16x32_bf16 v[24:27], v[160:163], v[186:189], v[24:27]
	s_waitcnt lgkmcnt(1)
	v_mfma_f32_16x16x32_bf16 v[12:15], v[152:155], v[194:197], v[12:15]
	v_mfma_f32_16x16x32_bf16 v[8:11], v[160:163], v[194:197], v[8:11]
	v_mfma_f32_16x16x32_bf16 v[60:63], v[156:159], v[172:175], v[60:63]
	v_mfma_f32_16x16x32_bf16 v[56:59], v[164:167], v[172:175], v[56:59]
	v_mfma_f32_16x16x32_bf16 v[44:47], v[156:159], v[182:185], v[44:47]
	v_mfma_f32_16x16x32_bf16 v[40:43], v[164:167], v[182:185], v[40:43]
	v_mfma_f32_16x16x32_bf16 v[28:31], v[156:159], v[190:193], v[28:31]
	v_mfma_f32_16x16x32_bf16 v[24:27], v[164:167], v[190:193], v[24:27]
	s_waitcnt lgkmcnt(0)
	v_mfma_f32_16x16x32_bf16 v[12:15], v[156:159], v[198:201], v[12:15]
	v_mfma_f32_16x16x32_bf16 v[8:11], v[164:167], v[198:201], v[8:11]
	s_barrier
	s_add_u32 s64, s36, 0x40000
	s_addc_u32 s65, s37, 0
	s_add_i32 s66, s56, s45
	s_mov_b32 m0, s66
	s_nop 0
	global_load_lds_dwordx4 v132, s[64:65]
	s_add_i32 m0, s66, 0x2000
	s_nop 0
	global_load_lds_dwordx4 v128, s[64:65]
	s_waitcnt vmcnt(6)
	s_barrier
	v_mfma_f32_16x16x32_bf16 v[52:55], v[202:205], v[168:171], v[52:55]
	v_mfma_f32_16x16x32_bf16 v[48:51], v[210:213], v[168:171], v[48:51]
	v_mfma_f32_16x16x32_bf16 v[36:39], v[202:205], v[176:179], v[36:39]
	v_mfma_f32_16x16x32_bf16 v[32:35], v[210:213], v[176:179], v[32:35]
	v_mfma_f32_16x16x32_bf16 v[20:23], v[202:205], v[186:189], v[20:23]
	v_mfma_f32_16x16x32_bf16 v[16:19], v[210:213], v[186:189], v[16:19]
	v_mfma_f32_16x16x32_bf16 v[4:7], v[202:205], v[194:197], v[4:7]
	v_mfma_f32_16x16x32_bf16 v[0:3], v[210:213], v[194:197], v[0:3]
	v_mfma_f32_16x16x32_bf16 v[52:55], v[206:209], v[172:175], v[52:55]
	v_mfma_f32_16x16x32_bf16 v[48:51], v[214:217], v[172:175], v[48:51]
	v_mfma_f32_16x16x32_bf16 v[36:39], v[206:209], v[182:185], v[36:39]
	v_mfma_f32_16x16x32_bf16 v[32:35], v[214:217], v[182:185], v[32:35]
	v_mfma_f32_16x16x32_bf16 v[20:23], v[206:209], v[190:193], v[20:23]
	v_mfma_f32_16x16x32_bf16 v[16:19], v[214:217], v[190:193], v[16:19]
	v_mfma_f32_16x16x32_bf16 v[4:7], v[206:209], v[198:201], v[4:7]
	v_mfma_f32_16x16x32_bf16 v[0:3], v[214:217], v[198:201], v[0:3]
	s_add_i32 s64, 0, 0x18000
	v_add_u32_e32 v164, s64, v147
	s_barrier
	ds_read_b128 v[152:155], v164
	ds_read_b128 v[156:159], v164 offset:1024
	ds_read_b128 v[160:163], v164 offset:2048
	ds_read_b128 v[164:167], v164 offset:3072
	s_add_u32 s38, s38, 0x40000
	s_addc_u32 s39, s39, 0
	s_mov_b32 m0, s49
	ds_read_b128 v[168:171], v150 offset:32768
	ds_read_b128 v[172:175], v150 offset:33792
	ds_read_b128 v[176:179], v150 offset:34816
	ds_read_b128 v[182:185], v150 offset:35840
	ds_read_b128 v[186:189], v150 offset:36864
	ds_read_b128 v[190:193], v150 offset:37888
	ds_read_b128 v[194:197], v150 offset:38912
	ds_read_b128 v[198:201], v150 offset:39936
	global_load_lds_dwordx4 v134, s[38:39]
	s_mov_b32 m0, s50
	s_nop 0
	global_load_lds_dwordx4 v130, s[38:39]
	s_waitcnt lgkmcnt(8)
	s_barrier
; #define PG8_STAGE(bufoff, gbase, voff) do { _Pragma("unroll") for (int _i = 0; _i < 2; ++_i) \
;         __builtin_amdgcn_global_load_lds((const unsigned*)((const char*)(gbase) + (voff)[_i]), (LAS unsigned*)(lds + (bufoff) + ldsw + _i * 8192), 16, 0, 0); } while (0)
; #define PG8_LDA(dst, b, h) do { _Pragma("unroll") for (int m = 0; m < 4; ++m) _Pragma("unroll") for (int k = 0; k < 2; ++k) dst[m][k] = *(const LAS bf16x8*)(lds + PG8_SA(b, h) + aoff + m * 2048 + k * 1024); } while (0)
; #define PG8_LDB(dst, b, h) do { _Pragma("unroll") for (int n = 0; n < 2; ++n) _Pragma("unroll") for (int k = 0; k < 2; ++k) dst[n][k] = *(const LAS bf16x8*)(lds + PG8_SB(b, h) + boff + n * 2048 + k * 1024); } while (0)
; #define PG8_MMA(ai, bj, At, Bt) do { __builtin_amdgcn_s_setprio(1); _Pragma("unroll") for (int m = 0; m < 4; ++m) _Pragma("unroll") for (int n = 0; n < 2; ++n) _Pragma("unroll") for (int k = 0; k < 2; ++k) \
;         acc[ai][bj][m][n] = __builtin_amdgcn_mfma_f32_16x16x32_bf16(Bt[n][k], At[m][k], acc[ai][bj][m][n], 0, 0, 0); __builtin_amdgcn_s_setprio(0); } while (0)
; #define PG8_WAIT_V(n) asm volatile("s_waitcnt vmcnt(" #n ")" ::: "memory")
; #define PG8_WAIT_L(n) asm volatile("s_waitcnt lgkmcnt(" #n ")" ::: "memory")
; #define PG8_BAR __builtin_amdgcn_s_barrier()
; #define PG8_SCHED __builtin_amdgcn_sched_barrier(0)
; template <class Epi>
; DI void gemm_phase(LAS unsigned char* lds, const Gemm g, const StaticOrder& S, const Epi& E) {
;     ...
;             PG8_WAIT_L(8); PG8_BAR; PG8_WAIT_L(0); PG8_MMA(0, 0, At, B0); PG8_BAR; PG8_SCHED;
;             PG8_LDB(B1, 1, 1); PG8_STAGE(PG8_SB(1, 0), b3, voffB);
;             PG8_BAR; PG8_WAIT_L(0); PG8_MMA(0, 1, At, B1); PG8_BAR;
;             PG8_LDA(At, 1, 1); PG8_STAGE(PG8_SA(1, 0), a3, voffA);
;             PG8_BAR; PG8_WAIT_L(0); PG8_MMA(1, 0, At, B0); PG8_BAR; PG8_SCHED;
;             PG8_STAGE(PG8_SB(1, 1), b3 + hstep, voffB);
;             PG8_WAIT_V(6); PG8_BAR; PG8_MMA(1, 1, At, B1); PG8_BAR;
	s_waitcnt lgkmcnt(7)
	v_mfma_f32_16x16x32_bf16 v[124:127], v[152:155], v[168:171], v[124:127]
	v_mfma_f32_16x16x32_bf16 v[120:123], v[160:163], v[168:171], v[120:123]
	s_waitcnt lgkmcnt(5)
	v_mfma_f32_16x16x32_bf16 v[108:111], v[152:155], v[176:179], v[108:111]
	v_mfma_f32_16x16x32_bf16 v[104:107], v[160:163], v[176:179], v[104:107]
	s_waitcnt lgkmcnt(3)
	v_mfma_f32_16x16x32_bf16 v[92:95], v[152:155], v[186:189], v[92:95]
	v_mfma_f32_16x16x32_bf16 v[88:91], v[160:163], v[186:189], v[88:91]
	s_waitcnt lgkmcnt(1)
	v_mfma_f32_16x16x32_bf16 v[76:79], v[152:155], v[194:197], v[76:79]
	v_mfma_f32_16x16x32_bf16 v[72:75], v[160:163], v[194:197], v[72:75]
	v_mfma_f32_16x16x32_bf16 v[124:127], v[156:159], v[172:175], v[124:127]
	v_mfma_f32_16x16x32_bf16 v[120:123], v[164:167], v[172:175], v[120:123]
	v_mfma_f32_16x16x32_bf16 v[108:111], v[156:159], v[182:185], v[108:111]
	v_mfma_f32_16x16x32_bf16 v[104:107], v[164:167], v[182:185], v[104:107]
	v_mfma_f32_16x16x32_bf16 v[92:95], v[156:159], v[190:193], v[92:95]
	v_mfma_f32_16x16x32_bf16 v[88:91], v[164:167], v[190:193], v[88:91]
	s_waitcnt lgkmcnt(0)
	v_mfma_f32_16x16x32_bf16 v[76:79], v[156:159], v[198:201], v[76:79]
	v_mfma_f32_16x16x32_bf16 v[72:75], v[164:167], v[198:201], v[72:75]
	s_barrier
	s_add_i32 s38, 0, 0x1c000
	s_add_i32 s39, s64, s45
	v_add_u32_e32 v214, s38, v147
	s_mov_b32 m0, s39
	ds_read_b128 v[202:205], v214
	ds_read_b128 v[206:209], v214 offset:1024
	ds_read_b128 v[210:213], v214 offset:2048
	ds_read_b128 v[214:217], v214 offset:3072
	global_load_lds_dwordx4 v132, s[86:87]
	s_add_i32 m0, s39, 0x2000
	s_nop 0
	global_load_lds_dwordx4 v128, s[86:87]
	s_barrier
	s_waitcnt lgkmcnt(3)
	v_mfma_f32_16x16x32_bf16 v[116:119], v[202:205], v[168:171], v[116:119]
	s_waitcnt lgkmcnt(1)
	v_mfma_f32_16x16x32_bf16 v[112:115], v[210:213], v[168:171], v[112:115]
	v_mfma_f32_16x16x32_bf16 v[100:103], v[202:205], v[176:179], v[100:103]
	v_mfma_f32_16x16x32_bf16 v[96:99], v[210:213], v[176:179], v[96:99]
	v_mfma_f32_16x16x32_bf16 v[84:87], v[202:205], v[186:189], v[84:87]
	v_mfma_f32_16x16x32_bf16 v[80:83], v[210:213], v[186:189], v[80:83]
	v_mfma_f32_16x16x32_bf16 v[68:71], v[202:205], v[194:197], v[68:71]
	v_mfma_f32_16x16x32_bf16 v[64:67], v[210:213], v[194:197], v[64:67]
	v_mfma_f32_16x16x32_bf16 v[116:119], v[206:209], v[172:175], v[116:119]
	s_waitcnt lgkmcnt(0)
	v_mfma_f32_16x16x32_bf16 v[112:115], v[214:217], v[172:175], v[112:115]
	v_mfma_f32_16x16x32_bf16 v[100:103], v[206:209], v[182:185], v[100:103]
	v_mfma_f32_16x16x32_bf16 v[96:99], v[214:217], v[182:185], v[96:99]
	v_mfma_f32_16x16x32_bf16 v[84:87], v[206:209], v[190:193], v[84:87]
	v_mfma_f32_16x16x32_bf16 v[80:83], v[214:217], v[190:193], v[80:83]
	v_mfma_f32_16x16x32_bf16 v[68:71], v[206:209], v[198:201], v[68:71]
	v_mfma_f32_16x16x32_bf16 v[64:67], v[214:217], v[198:201], v[64:67]
	s_mov_b32 m0, s52
	s_barrier
	ds_read_b128 v[168:171], v150 offset:49152
	ds_read_b128 v[172:175], v150 offset:50176
	ds_read_b128 v[176:179], v150 offset:51200
	ds_read_b128 v[182:185], v150 offset:52224
	ds_read_b128 v[186:189], v150 offset:53248
	ds_read_b128 v[190:193], v150 offset:54272
	ds_read_b128 v[194:197], v150 offset:55296
	ds_read_b128 v[198:201], v150 offset:56320
	global_load_lds_dwordx4 v134, s[88:89]
	s_mov_b32 m0, s53
	s_nop 0
	global_load_lds_dwordx4 v130, s[88:89]
	s_barrier
	s_waitcnt lgkmcnt(7)
	v_mfma_f32_16x16x32_bf16 v[60:63], v[152:155], v[168:171], v[60:63]
	v_mfma_f32_16x16x32_bf16 v[56:59], v[160:163], v[168:171], v[56:59]
	s_waitcnt lgkmcnt(5)
	v_mfma_f32_16x16x32_bf16 v[44:47], v[152:155], v[176:179], v[44:47]
	v_mfma_f32_16x16x32_bf16 v[40:43], v[160:163], v[176:179], v[40:43]
	s_waitcnt lgkmcnt(3)
	v_mfma_f32_16x16x32_bf16 v[28:31], v[152:155], v[186:189], v[28:31]
	v_mfma_f32_16x16x32_bf16 v[24:27], v[160:163], v[186:189], v[24:27]
	s_waitcnt lgkmcnt(1)
	v_mfma_f32_16x16x32_bf16 v[12:15], v[152:155], v[194:197], v[12:15]
	v_mfma_f32_16x16x32_bf16 v[8:11], v[160:163], v[194:197], v[8:11]
	v_mfma_f32_16x16x32_bf16 v[60:63], v[156:159], v[172:175], v[60:63]
	v_mfma_f32_16x16x32_bf16 v[56:59], v[164:167], v[172:175], v[56:59]
	v_mfma_f32_16x16x32_bf16 v[44:47], v[156:159], v[182:185], v[44:47]
	v_mfma_f32_16x16x32_bf16 v[40:43], v[164:167], v[182:185], v[40:43]
	v_mfma_f32_16x16x32_bf16 v[28:31], v[156:159], v[190:193], v[28:31]
	v_mfma_f32_16x16x32_bf16 v[24:27], v[164:167], v[190:193], v[24:27]
	s_waitcnt lgkmcnt(0)
	v_mfma_f32_16x16x32_bf16 v[12:15], v[156:159], v[198:201], v[12:15]
	v_mfma_f32_16x16x32_bf16 v[8:11], v[164:167], v[198:201], v[8:11]
	s_barrier
	s_add_u32 s36, s36, 0x40080
	s_addc_u32 s37, s37, 0
	s_add_i32 s38, s38, s45
	s_mov_b32 m0, s38
	s_nop 0
	global_load_lds_dwordx4 v132, s[36:37]
	s_add_i32 m0, s38, 0x2000
	s_nop 0
	global_load_lds_dwordx4 v128, s[36:37]
	s_waitcnt vmcnt(6)
	s_barrier
	v_mfma_f32_16x16x32_bf16 v[52:55], v[202:205], v[168:171], v[52:55]
	v_mfma_f32_16x16x32_bf16 v[48:51], v[210:213], v[168:171], v[48:51]
	v_mfma_f32_16x16x32_bf16 v[36:39], v[202:205], v[176:179], v[36:39]
	v_mfma_f32_16x16x32_bf16 v[32:35], v[210:213], v[176:179], v[32:35]
	v_mfma_f32_16x16x32_bf16 v[20:23], v[202:205], v[186:189], v[20:23]
	v_mfma_f32_16x16x32_bf16 v[16:19], v[210:213], v[186:189], v[16:19]
	v_mfma_f32_16x16x32_bf16 v[4:7], v[202:205], v[194:197], v[4:7]
	v_mfma_f32_16x16x32_bf16 v[0:3], v[210:213], v[194:197], v[0:3]
	v_mfma_f32_16x16x32_bf16 v[52:55], v[206:209], v[172:175], v[52:55]
	v_mfma_f32_16x16x32_bf16 v[48:51], v[214:217], v[172:175], v[48:51]
	v_mfma_f32_16x16x32_bf16 v[36:39], v[206:209], v[182:185], v[36:39]
	v_mfma_f32_16x16x32_bf16 v[32:35], v[214:217], v[182:185], v[32:35]
	v_mfma_f32_16x16x32_bf16 v[20:23], v[206:209], v[190:193], v[20:23]
	v_mfma_f32_16x16x32_bf16 v[16:19], v[214:217], v[190:193], v[16:19]
	v_mfma_f32_16x16x32_bf16 v[4:7], v[206:209], v[198:201], v[4:7]
	v_mfma_f32_16x16x32_bf16 v[0:3], v[214:217], v[198:201], v[0:3]
	s_add_i32 s63, s63, 2
	s_add_u32 s24, s24, 0x100
	s_addc_u32 s25, s25, 0
	s_add_u32 s61, s61, 0x100
	s_addc_u32 s62, s62, 0
	s_cmp_gt_u32 s63, 13
	s_barrier
; DI unsigned pk2(float a, float b) { f32x2 v = {a, b}; bf16x2_t r = __builtin_convertvector(v, bf16x2_t); return __builtin_bit_cast(unsigned, r); }
; DI float siluf_(float x) { return x * __builtin_amdgcn_rcpf(1.f + __expf(-x)); }
;     DI void operator()(const f32x4 (&acc)[2][2][4][2], const Unit& u, int wr, int wc, int fr, int fq) const {
;         const int row0 = u.pm * BM + wr * 64 + fr, col0 = u.pn * HALF + wc * 32 + 8 * fq;
; #pragma unroll
;         for (int ai = 0; ai < 2; ++ai)
; #pragma unroll
;             for (int m = 0; m < 4; ++m) { bf16_t* rowp = O + (size_t)(row0 + ai * HALF + m * 16) * DFF + col0;
;                 f32x4 v0, v1;
; #pragma unroll
;                 for (int j = 0; j < 4; ++j) { v0[j] = siluf_(acc[ai][0][m][0][j]) * acc[ai][1][m][0][j]; v1[j] = siluf_(acc[ai][0][m][1][j]) * acc[ai][1][m][1][j]; }
;                 u32x4 w; w.x = pk2(v0[0], v0[1]); w.y = pk2(v0[2], v0[3]); w.z = pk2(v1[0], v1[1]); w.w = pk2(v1[2], v1[3]);
;                 *(u32x4*)rowp = w; }
;     }
	s_cbranch_scc0 .LBB0_849
	v_mul_f32_e32 v153, 0xbfb8aa3b, v124
	v_mul_f32_e32 v158, 0xbfb8aa3b, v120
	v_exp_f32_e32 v153, v153
	v_exp_f32_e32 v159, v158
	v_mul_f32_e32 v158, 0xbfb8aa3b, v125
	v_exp_f32_e32 v160, v158
	v_add_f32_e32 v153, 1.0, v153
	v_rcp_f32_e32 v158, v153
	v_add_f32_e32 v153, 1.0, v159
	v_add_f32_e32 v159, 1.0, v160
	v_rcp_f32_e32 v159, v159
	v_mul_f32_e32 v160, 0xbfb8aa3b, v121
	v_exp_f32_e32 v161, v160
	v_rcp_f32_e32 v160, v153
	v_pk_mul_f32 v[124:125], v[124:125], v[158:159]
	v_mul_f32_e32 v153, 0xbfb8aa3b, v127
	v_pk_mul_f32 v[116:117], v[124:125], v[116:117]
	v_add_f32_e32 v124, 1.0, v161
	v_mul_f32_e32 v125, 0xbfb8aa3b, v122
	v_rcp_f32_e32 v161, v124
	v_mul_f32_e32 v124, 0xbfb8aa3b, v126
	v_exp_f32_e32 v125, v125
	v_exp_f32_e32 v124, v124
	v_exp_f32_e32 v153, v153
	v_mul_f32_e32 v158, 0xbfb8aa3b, v123
	v_exp_f32_e32 v159, v158
	v_add_f32_e32 v125, 1.0, v125
	v_add_f32_e32 v124, 1.0, v124
	v_rcp_f32_e32 v158, v125
	v_add_f32_e32 v125, 1.0, v153
	v_rcp_f32_e32 v124, v124
	v_rcp_f32_e32 v125, v125
	v_add_f32_e32 v153, 1.0, v159
	v_rcp_f32_e32 v159, v153
	v_pk_mul_f32 v[120:121], v[120:121], v[160:161]
	v_lshl_or_b32 v154, s58, 7, v148
	v_pk_mul_f32 v[120:121], v[120:121], v[112:113]
	v_pk_mul_f32 v[112:113], v[126:127], v[124:125]
	v_lshl_add_u32 v152, s22, 8, v146
	v_ashrrev_i32_e32 v155, 31, v154
	v_mov_b64_e32 v[144:145], s[8:9]
	v_pk_mul_f32 v[118:119], v[112:113], v[118:119]
	v_pk_mul_f32 v[112:113], v[122:123], v[158:159]
	v_mad_i64_i32 v[156:157], s[24:25], v152, s57, v[144:145]
	v_pk_mul_f32 v[122:123], v[112:113], v[114:115]
	v_lshlrev_b64 v[112:113], 1, v[154:155]
	v_lshl_add_u64 v[124:125], v[156:157], 0, v[112:113]
	v_cvt_pk_bf16_f32 v114, v116, v117
	v_cvt_pk_bf16_f32 v115, v118, v119
	v_cvt_pk_bf16_f32 v116, v120, v121
	v_cvt_pk_bf16_f32 v117, v122, v123
	global_store_dwordx4 v[124:125], v[114:117], off
	v_mul_f32_e32 v118, 0xbfb8aa3b, v109
	v_exp_f32_e32 v118, v118
	v_mul_f32_e32 v116, 0xbfb8aa3b, v108
	v_mul_f32_e32 v117, 0xbfb8aa3b, v104
	v_exp_f32_e32 v116, v116
	v_exp_f32_e32 v117, v117
	v_or_b32_e32 v114, 16, v152
	v_mad_i64_i32 v[114:115], s[24:25], v114, s57, v[144:145]
	v_add_f32_e32 v116, 1.0, v116
	v_add_f32_e32 v119, 1.0, v117
	v_add_f32_e32 v117, 1.0, v118
	v_rcp_f32_e32 v116, v116
	v_rcp_f32_e32 v117, v117
	v_mul_f32_e32 v118, 0xbfb8aa3b, v105
	v_exp_f32_e32 v120, v118
	v_rcp_f32_e32 v118, v119
	v_pk_mul_f32 v[108:109], v[108:109], v[116:117]
	v_mul_f32_e32 v116, 0xbfb8aa3b, v111
	v_pk_mul_f32 v[100:101], v[108:109], v[100:101]
	v_add_f32_e32 v108, 1.0, v120
	v_rcp_f32_e32 v119, v108
	v_mul_f32_e32 v109, 0xbfb8aa3b, v106
	v_mul_f32_e32 v108, 0xbfb8aa3b, v110
	v_exp_f32_e32 v109, v109
	v_exp_f32_e32 v108, v108
	v_exp_f32_e32 v117, v116
	v_mul_f32_e32 v116, 0xbfb8aa3b, v107
	v_pk_mul_f32 v[104:105], v[104:105], v[118:119]
	v_exp_f32_e32 v118, v116
	v_add_f32_e32 v109, 1.0, v109
	v_add_f32_e32 v108, 1.0, v108
	v_rcp_f32_e32 v116, v109
	v_add_f32_e32 v109, 1.0, v117
	v_rcp_f32_e32 v108, v108
	v_rcp_f32_e32 v109, v109
	v_add_f32_e32 v117, 1.0, v118
	v_rcp_f32_e32 v117, v117
	v_pk_mul_f32 v[104:105], v[104:105], v[96:97]
	v_pk_mul_f32 v[96:97], v[110:111], v[108:109]
	v_lshl_add_u64 v[108:109], v[114:115], 0, v[112:113]
	v_pk_mul_f32 v[102:103], v[96:97], v[102:103]
	v_pk_mul_f32 v[96:97], v[106:107], v[116:117]
	s_and_b64 vcc, exec, s[4:5]
	v_pk_mul_f32 v[106:107], v[96:97], v[98:99]
	v_cvt_pk_bf16_f32 v96, v100, v101
	v_cvt_pk_bf16_f32 v97, v102, v103
	v_cvt_pk_bf16_f32 v98, v104, v105
	v_cvt_pk_bf16_f32 v99, v106, v107
	global_store_dwordx4 v[108:109], v[96:99], off
	v_mul_f32_e32 v100, 0xbfb8aa3b, v93
	v_exp_f32_e32 v100, v100
	v_mul_f32_e32 v98, 0xbfb8aa3b, v92
	v_mul_f32_e32 v99, 0xbfb8aa3b, v88
	v_exp_f32_e32 v98, v98
	v_exp_f32_e32 v99, v99
	v_or_b32_e32 v96, 32, v152
	v_mad_i64_i32 v[96:97], s[24:25], v96, s57, v[144:145]
	v_add_f32_e32 v98, 1.0, v98
	v_add_f32_e32 v101, 1.0, v99
	v_add_f32_e32 v99, 1.0, v100
	v_rcp_f32_e32 v98, v98
	v_rcp_f32_e32 v99, v99
	v_mul_f32_e32 v100, 0xbfb8aa3b, v89
	v_exp_f32_e32 v102, v100
	v_rcp_f32_e32 v100, v101
	v_pk_mul_f32 v[92:93], v[92:93], v[98:99]
	v_mul_f32_e32 v98, 0xbfb8aa3b, v95
	v_pk_mul_f32 v[84:85], v[92:93], v[84:85]
	v_add_f32_e32 v92, 1.0, v102
	v_rcp_f32_e32 v101, v92
	v_mul_f32_e32 v93, 0xbfb8aa3b, v90
	v_mul_f32_e32 v92, 0xbfb8aa3b, v94
	v_exp_f32_e32 v93, v93
	v_exp_f32_e32 v92, v92
	v_exp_f32_e32 v99, v98
	v_mul_f32_e32 v98, 0xbfb8aa3b, v91
	v_pk_mul_f32 v[88:89], v[88:89], v[100:101]
	v_exp_f32_e32 v100, v98
	v_add_f32_e32 v93, 1.0, v93
	v_add_f32_e32 v92, 1.0, v92
	v_rcp_f32_e32 v98, v93
	v_add_f32_e32 v93, 1.0, v99
	v_rcp_f32_e32 v92, v92
	v_rcp_f32_e32 v93, v93
	v_add_f32_e32 v99, 1.0, v100
	v_rcp_f32_e32 v99, v99
	v_pk_mul_f32 v[88:89], v[88:89], v[80:81]
	v_pk_mul_f32 v[80:81], v[94:95], v[92:93]
	v_lshl_add_u64 v[92:93], v[96:97], 0, v[112:113]
	v_pk_mul_f32 v[86:87], v[80:81], v[86:87]
	v_pk_mul_f32 v[80:81], v[90:91], v[98:99]
	s_mov_b32 s58, s14
	v_pk_mul_f32 v[90:91], v[80:81], v[82:83]
	v_cvt_pk_bf16_f32 v80, v84, v85
	v_cvt_pk_bf16_f32 v81, v86, v87
	v_cvt_pk_bf16_f32 v82, v88, v89
	v_cvt_pk_bf16_f32 v83, v90, v91
	global_store_dwordx4 v[92:93], v[80:83], off
	v_mul_f32_e32 v84, 0xbfb8aa3b, v77
	v_exp_f32_e32 v84, v84
	v_mul_f32_e32 v82, 0xbfb8aa3b, v76
	v_mul_f32_e32 v83, 0xbfb8aa3b, v72
	v_exp_f32_e32 v82, v82
	v_exp_f32_e32 v83, v83
	v_or_b32_e32 v80, 48, v152
	v_mad_i64_i32 v[80:81], s[24:25], v80, s57, v[144:145]
	v_add_f32_e32 v82, 1.0, v82
	v_add_f32_e32 v85, 1.0, v83
	v_add_f32_e32 v83, 1.0, v84
	v_rcp_f32_e32 v82, v82
	v_rcp_f32_e32 v83, v83
	v_mul_f32_e32 v84, 0xbfb8aa3b, v73
	v_exp_f32_e32 v86, v84
; DI unsigned pk2(float a, float b) { f32x2 v = {a, b}; bf16x2_t r = __builtin_convertvector(v, bf16x2_t); return __builtin_bit_cast(unsigned, r); }
; DI float siluf_(float x) { return x * __builtin_amdgcn_rcpf(1.f + __expf(-x)); }
;     DI void operator()(const f32x4 (&acc)[2][2][4][2], const Unit& u, int wr, int wc, int fr, int fq) const {
;     ...
;             for (int m = 0; m < 4; ++m) { bf16_t* rowp = O + (size_t)(row0 + ai * HALF + m * 16) * DFF + col0;
;                 f32x4 v0, v1;
; #pragma unroll
;                 for (int j = 0; j < 4; ++j) { v0[j] = siluf_(acc[ai][0][m][0][j]) * acc[ai][1][m][0][j]; v1[j] = siluf_(acc[ai][0][m][1][j]) * acc[ai][1][m][1][j]; }
;                 u32x4 w; w.x = pk2(v0[0], v0[1]); w.y = pk2(v0[2], v0[3]); w.z = pk2(v1[0], v1[1]); w.w = pk2(v1[2], v1[3]);
;                 *(u32x4*)rowp = w; }
	v_rcp_f32_e32 v84, v85
	v_pk_mul_f32 v[76:77], v[76:77], v[82:83]
	v_mul_f32_e32 v82, 0xbfb8aa3b, v79
	v_pk_mul_f32 v[68:69], v[76:77], v[68:69]
	v_add_f32_e32 v76, 1.0, v86
	v_rcp_f32_e32 v85, v76
	v_mul_f32_e32 v77, 0xbfb8aa3b, v74
	v_mul_f32_e32 v76, 0xbfb8aa3b, v78
	v_exp_f32_e32 v77, v77
	v_exp_f32_e32 v76, v76
	v_exp_f32_e32 v83, v82
	v_mul_f32_e32 v82, 0xbfb8aa3b, v75
	v_pk_mul_f32 v[72:73], v[72:73], v[84:85]
	v_exp_f32_e32 v84, v82
	v_add_f32_e32 v77, 1.0, v77
	v_add_f32_e32 v76, 1.0, v76
	v_rcp_f32_e32 v82, v77
	v_add_f32_e32 v77, 1.0, v83
	v_rcp_f32_e32 v76, v76
	v_rcp_f32_e32 v77, v77
	v_add_f32_e32 v83, 1.0, v84
	v_rcp_f32_e32 v83, v83
	v_pk_mul_f32 v[72:73], v[72:73], v[64:65]
	v_pk_mul_f32 v[64:65], v[78:79], v[76:77]
	v_lshl_add_u64 v[76:77], v[80:81], 0, v[112:113]
	v_pk_mul_f32 v[70:71], v[64:65], v[70:71]
	v_pk_mul_f32 v[64:65], v[74:75], v[82:83]
	s_mov_b32 s22, s16
	v_pk_mul_f32 v[74:75], v[64:65], v[66:67]
	v_cvt_pk_bf16_f32 v64, v68, v69
	v_cvt_pk_bf16_f32 v65, v70, v71
	v_cvt_pk_bf16_f32 v66, v72, v73
	v_cvt_pk_bf16_f32 v67, v74, v75
	global_store_dwordx4 v[76:77], v[64:67], off
	v_mul_f32_e32 v68, 0xbfb8aa3b, v61
	v_exp_f32_e32 v68, v68
	v_mul_f32_e32 v66, 0xbfb8aa3b, v60
	v_mul_f32_e32 v67, 0xbfb8aa3b, v56
	v_exp_f32_e32 v66, v66
	v_exp_f32_e32 v67, v67
	v_add_u32_e32 v64, 0x80, v152
	v_mad_i64_i32 v[64:65], s[24:25], v64, s57, v[144:145]
	v_add_f32_e32 v66, 1.0, v66
	v_add_f32_e32 v69, 1.0, v67
	v_add_f32_e32 v67, 1.0, v68
	v_rcp_f32_e32 v66, v66
	v_rcp_f32_e32 v67, v67
	v_mul_f32_e32 v68, 0xbfb8aa3b, v57
	v_exp_f32_e32 v70, v68
	v_rcp_f32_e32 v68, v69
	v_pk_mul_f32 v[60:61], v[60:61], v[66:67]
	v_mul_f32_e32 v66, 0xbfb8aa3b, v63
	v_pk_mul_f32 v[52:53], v[60:61], v[52:53]
	v_add_f32_e32 v60, 1.0, v70
	v_rcp_f32_e32 v69, v60
	v_mul_f32_e32 v61, 0xbfb8aa3b, v58
	v_mul_f32_e32 v60, 0xbfb8aa3b, v62
	v_exp_f32_e32 v61, v61
	v_exp_f32_e32 v60, v60
	v_exp_f32_e32 v67, v66
	v_mul_f32_e32 v66, 0xbfb8aa3b, v59
	v_pk_mul_f32 v[56:57], v[56:57], v[68:69]
	v_exp_f32_e32 v68, v66
	v_add_f32_e32 v61, 1.0, v61
	v_add_f32_e32 v60, 1.0, v60
	v_rcp_f32_e32 v66, v61
	v_add_f32_e32 v61, 1.0, v67
	v_rcp_f32_e32 v60, v60
	v_rcp_f32_e32 v61, v61
	v_add_f32_e32 v67, 1.0, v68
	v_rcp_f32_e32 v67, v67
	v_pk_mul_f32 v[56:57], v[56:57], v[48:49]
	v_pk_mul_f32 v[48:49], v[62:63], v[60:61]
	v_lshl_add_u64 v[60:61], v[64:65], 0, v[112:113]
	v_pk_mul_f32 v[54:55], v[48:49], v[54:55]
	v_pk_mul_f32 v[48:49], v[58:59], v[66:67]
	s_mov_b64 s[36:37], s[20:21]
	v_pk_mul_f32 v[58:59], v[48:49], v[50:51]
	v_cvt_pk_bf16_f32 v48, v52, v53
	v_cvt_pk_bf16_f32 v49, v54, v55
	v_cvt_pk_bf16_f32 v50, v56, v57
	v_cvt_pk_bf16_f32 v51, v58, v59
	global_store_dwordx4 v[60:61], v[48:51], off
	v_mul_f32_e32 v52, 0xbfb8aa3b, v45
	v_exp_f32_e32 v52, v52
	v_mul_f32_e32 v50, 0xbfb8aa3b, v44
	v_mul_f32_e32 v51, 0xbfb8aa3b, v40
	v_exp_f32_e32 v50, v50
	v_exp_f32_e32 v51, v51
	v_add_u32_e32 v48, 0x90, v152
	v_mad_i64_i32 v[48:49], s[24:25], v48, s57, v[144:145]
	v_add_f32_e32 v50, 1.0, v50
	v_add_f32_e32 v53, 1.0, v51
	v_add_f32_e32 v51, 1.0, v52
	v_rcp_f32_e32 v50, v50
	v_rcp_f32_e32 v51, v51
	v_mul_f32_e32 v52, 0xbfb8aa3b, v41
	v_exp_f32_e32 v54, v52
	v_rcp_f32_e32 v52, v53
	v_pk_mul_f32 v[44:45], v[44:45], v[50:51]
	v_mul_f32_e32 v50, 0xbfb8aa3b, v47
	v_pk_mul_f32 v[36:37], v[44:45], v[36:37]
	v_add_f32_e32 v44, 1.0, v54
	v_rcp_f32_e32 v53, v44
	v_mul_f32_e32 v45, 0xbfb8aa3b, v42
	v_mul_f32_e32 v44, 0xbfb8aa3b, v46
	v_exp_f32_e32 v45, v45
	v_exp_f32_e32 v44, v44
	v_exp_f32_e32 v51, v50
	v_mul_f32_e32 v50, 0xbfb8aa3b, v43
	v_pk_mul_f32 v[40:41], v[40:41], v[52:53]
	v_exp_f32_e32 v52, v50
	v_add_f32_e32 v45, 1.0, v45
	v_add_f32_e32 v44, 1.0, v44
	v_rcp_f32_e32 v50, v45
	v_add_f32_e32 v45, 1.0, v51
	v_rcp_f32_e32 v44, v44
; DI unsigned pk2(float a, float b) { f32x2 v = {a, b}; bf16x2_t r = __builtin_convertvector(v, bf16x2_t); return __builtin_bit_cast(unsigned, r); }
; DI float siluf_(float x) { return x * __builtin_amdgcn_rcpf(1.f + __expf(-x)); }
; #define PG8_WAIT_V(n) asm volatile("s_waitcnt vmcnt(" #n ")" ::: "memory")
; #define PG8_BAR __builtin_amdgcn_s_barrier()
; template <class Epi>
; DI void gemm_phase(LAS unsigned char* lds, const Gemm g, const StaticOrder& S, const Epi& E) {
;     ...
;         if (!has_next) break;
; #pragma unroll
;         for (int a = 0; a < 2; ++a)
; #pragma unroll
;             for (int b = 0; b < 2; ++b)
; #pragma unroll
;                 for (int m = 0; m < 4; ++m)
; #pragma unroll
;                     for (int n = 0; n < 2; ++n) acc[a][b][m][n] = (f32x4){0.f, 0.f, 0.f, 0.f};
;         cur = nxt; cA = nA; cB = nB; ++ui;
;     }
;     PG8_WAIT_V(0);
;     if (wr == 0) PG8_BAR;
;     PG8_BAR;
;     DI void operator()(const f32x4 (&acc)[2][2][4][2], const Unit& u, int wr, int wc, int fr, int fq) const {
;     ...
;             for (int m = 0; m < 4; ++m) { bf16_t* rowp = O + (size_t)(row0 + ai * HALF + m * 16) * DFF + col0;
;                 f32x4 v0, v1;
; #pragma unroll
;                 for (int j = 0; j < 4; ++j) { v0[j] = siluf_(acc[ai][0][m][0][j]) * acc[ai][1][m][0][j]; v1[j] = siluf_(acc[ai][0][m][1][j]) * acc[ai][1][m][1][j]; }
;                 u32x4 w; w.x = pk2(v0[0], v0[1]); w.y = pk2(v0[2], v0[3]); w.z = pk2(v1[0], v1[1]); w.w = pk2(v1[2], v1[3]);
;                 *(u32x4*)rowp = w; }
	v_rcp_f32_e32 v45, v45
	v_add_f32_e32 v51, 1.0, v52
	v_rcp_f32_e32 v51, v51
	v_pk_mul_f32 v[40:41], v[40:41], v[32:33]
	v_pk_mul_f32 v[32:33], v[46:47], v[44:45]
	v_lshl_add_u64 v[44:45], v[48:49], 0, v[112:113]
	v_pk_mul_f32 v[38:39], v[32:33], v[38:39]
	v_pk_mul_f32 v[32:33], v[42:43], v[50:51]
	s_nop 0
	v_pk_mul_f32 v[42:43], v[32:33], v[34:35]
	v_cvt_pk_bf16_f32 v32, v36, v37
	v_cvt_pk_bf16_f32 v33, v38, v39
	v_cvt_pk_bf16_f32 v34, v40, v41
	v_cvt_pk_bf16_f32 v35, v42, v43
	global_store_dwordx4 v[44:45], v[32:35], off
	v_mul_f32_e32 v36, 0xbfb8aa3b, v29
	v_exp_f32_e32 v36, v36
	v_mul_f32_e32 v34, 0xbfb8aa3b, v28
	v_mul_f32_e32 v35, 0xbfb8aa3b, v24
	v_exp_f32_e32 v34, v34
	v_exp_f32_e32 v35, v35
	v_add_u32_e32 v32, 0xa0, v152
	v_mad_i64_i32 v[32:33], s[24:25], v32, s57, v[144:145]
	v_add_f32_e32 v34, 1.0, v34
	v_add_f32_e32 v37, 1.0, v35
	v_add_f32_e32 v35, 1.0, v36
	v_rcp_f32_e32 v34, v34
	v_rcp_f32_e32 v35, v35
	v_mul_f32_e32 v36, 0xbfb8aa3b, v25
	v_exp_f32_e32 v38, v36
	v_rcp_f32_e32 v36, v37
	v_pk_mul_f32 v[28:29], v[28:29], v[34:35]
	v_mul_f32_e32 v34, 0xbfb8aa3b, v31
	v_pk_mul_f32 v[20:21], v[28:29], v[20:21]
	v_add_f32_e32 v28, 1.0, v38
	v_rcp_f32_e32 v37, v28
	v_mul_f32_e32 v29, 0xbfb8aa3b, v26
	v_mul_f32_e32 v28, 0xbfb8aa3b, v30
	v_exp_f32_e32 v29, v29
	v_exp_f32_e32 v28, v28
	v_exp_f32_e32 v35, v34
	v_mul_f32_e32 v34, 0xbfb8aa3b, v27
	v_pk_mul_f32 v[24:25], v[24:25], v[36:37]
	v_exp_f32_e32 v36, v34
	v_add_f32_e32 v29, 1.0, v29
	v_add_f32_e32 v28, 1.0, v28
	v_rcp_f32_e32 v34, v29
	v_add_f32_e32 v29, 1.0, v35
	v_rcp_f32_e32 v28, v28
	v_rcp_f32_e32 v29, v29
	v_add_f32_e32 v35, 1.0, v36
	v_rcp_f32_e32 v35, v35
	v_pk_mul_f32 v[24:25], v[24:25], v[16:17]
	v_pk_mul_f32 v[16:17], v[30:31], v[28:29]
	v_lshl_add_u64 v[28:29], v[32:33], 0, v[112:113]
	v_pk_mul_f32 v[22:23], v[16:17], v[22:23]
	v_pk_mul_f32 v[16:17], v[26:27], v[34:35]
	s_nop 0
	v_pk_mul_f32 v[26:27], v[16:17], v[18:19]
	v_cvt_pk_bf16_f32 v16, v20, v21
	v_cvt_pk_bf16_f32 v17, v22, v23
	v_cvt_pk_bf16_f32 v18, v24, v25
	v_cvt_pk_bf16_f32 v19, v26, v27
	global_store_dwordx4 v[28:29], v[16:19], off
	v_mul_f32_e32 v20, 0xbfb8aa3b, v13
	v_exp_f32_e32 v20, v20
	v_mul_f32_e32 v18, 0xbfb8aa3b, v12
	v_mul_f32_e32 v19, 0xbfb8aa3b, v8
	v_exp_f32_e32 v18, v18
	v_exp_f32_e32 v19, v19
	v_add_u32_e32 v16, 0xb0, v152
	v_mad_i64_i32 v[16:17], s[24:25], v16, s57, v[144:145]
	v_add_f32_e32 v18, 1.0, v18
	v_add_f32_e32 v21, 1.0, v19
	v_add_f32_e32 v19, 1.0, v20
	v_rcp_f32_e32 v18, v18
	v_rcp_f32_e32 v19, v19
	v_mul_f32_e32 v20, 0xbfb8aa3b, v9
	v_exp_f32_e32 v22, v20
	v_rcp_f32_e32 v20, v21
	v_pk_mul_f32 v[12:13], v[12:13], v[18:19]
	v_mul_f32_e32 v18, 0xbfb8aa3b, v15
	v_pk_mul_f32 v[4:5], v[12:13], v[4:5]
	v_add_f32_e32 v12, 1.0, v22
	v_rcp_f32_e32 v21, v12
	v_mul_f32_e32 v13, 0xbfb8aa3b, v10
	v_mul_f32_e32 v12, 0xbfb8aa3b, v14
	v_exp_f32_e32 v13, v13
	v_exp_f32_e32 v12, v12
	v_exp_f32_e32 v19, v18
	v_mul_f32_e32 v18, 0xbfb8aa3b, v11
	v_pk_mul_f32 v[8:9], v[8:9], v[20:21]
	v_exp_f32_e32 v20, v18
	v_add_f32_e32 v13, 1.0, v13
	v_add_f32_e32 v12, 1.0, v12
	v_rcp_f32_e32 v18, v13
	v_add_f32_e32 v13, 1.0, v19
	v_rcp_f32_e32 v12, v12
	v_rcp_f32_e32 v13, v13
	v_add_f32_e32 v19, 1.0, v20
	v_rcp_f32_e32 v19, v19
	v_pk_mul_f32 v[8:9], v[8:9], v[0:1]
	v_pk_mul_f32 v[0:1], v[14:15], v[12:13]
	v_lshl_add_u64 v[12:13], v[16:17], 0, v[112:113]
	v_pk_mul_f32 v[6:7], v[0:1], v[6:7]
	v_pk_mul_f32 v[0:1], v[10:11], v[18:19]
	s_mov_b64 s[24:25], s[18:19]
	v_pk_mul_f32 v[10:11], v[0:1], v[2:3]
	v_cvt_pk_bf16_f32 v0, v4, v5
	v_cvt_pk_bf16_f32 v1, v6, v7
	v_cvt_pk_bf16_f32 v2, v8, v9
	v_cvt_pk_bf16_f32 v3, v10, v11
	global_store_dwordx4 v[12:13], v[0:3], off
	s_cbranch_vccz .LBB0_846
	s_waitcnt vmcnt(0)
	s_cmpk_gt_u32 s40, 0xff
	s_cbranch_scc1 .LBB0_853
	s_barrier

; #define PG8_STAGE(bufoff, gbase, voff) do { _Pragma("unroll") for (int _i = 0; _i < 2; ++_i) \
;         __builtin_amdgcn_global_load_lds((const unsigned*)((const char*)(gbase) + (voff)[_i]), (LAS unsigned*)(lds + (bufoff) + ldsw + _i * 8192), 16, 0, 0); } while (0)
; #define PG8_LDA(dst, b, h) do { _Pragma("unroll") for (int m = 0; m < 4; ++m) _Pragma("unroll") for (int k = 0; k < 2; ++k) dst[m][k] = *(const LAS bf16x8*)(lds + PG8_SA(b, h) + aoff + m * 2048 + k * 1024); } while (0)
; #define PG8_LDB(dst, b, h) do { _Pragma("unroll") for (int n = 0; n < 2; ++n) _Pragma("unroll") for (int k = 0; k < 2; ++k) dst[n][k] = *(const LAS bf16x8*)(lds + PG8_SB(b, h) + boff + n * 2048 + k * 1024); } while (0)
; #define PG8_MMA(ai, bj, At, Bt) do { __builtin_amdgcn_s_setprio(1); _Pragma("unroll") for (int m = 0; m < 4; ++m) _Pragma("unroll") for (int n = 0; n < 2; ++n) _Pragma("unroll") for (int k = 0; k < 2; ++k) \
;         acc[ai][bj][m][n] = __builtin_amdgcn_mfma_f32_16x16x32_bf16(Bt[n][k], At[m][k], acc[ai][bj][m][n], 0, 0, 0); __builtin_amdgcn_s_setprio(0); } while (0)
; #define PG8_WAIT_V(n) asm volatile("s_waitcnt vmcnt(" #n ")" ::: "memory")
; #define PG8_WAIT_L(n) asm volatile("s_waitcnt lgkmcnt(" #n ")" ::: "memory")
; #define PG8_BAR __builtin_amdgcn_s_barrier()
; template <class Epi>
; DI void gemm_phase(LAS unsigned char* lds, const Gemm g, const StaticOrder& S, const Epi& E) {
;     ...
;         for (int t = 0; t < nt; t += 2) {
;             const bool last = (t == nt - 2);
;             const char* a1 = cA + (size_t)(t + 1) * kstep;
;             const char* a2 = last ? nA : cA + (size_t)(t + 2) * kstep; const char* b2 = last ? nB : cB + (size_t)(t + 2) * kstep;
;             const char* a3 = a2 + kstep; const char* b3 = b2 + kstep;
;             PG8_LDB(B0, 0, 0); PG8_SCHED; PG8_LDA(At, 0, 0); PG8_STAGE(PG8_SA(1, 1), a1 + hstep, voffA);
;             PG8_WAIT_L(8); PG8_BAR; PG8_WAIT_L(0); PG8_MMA(0, 0, At, B0); PG8_BAR; PG8_SCHED;
;             PG8_LDB(B1, 0, 1); PG8_STAGE(PG8_SB(0, 0), b2, voffB);
;             PG8_BAR; PG8_WAIT_L(0); PG8_MMA(0, 1, At, B1); PG8_BAR;
;             PG8_LDA(At, 0, 1); PG8_STAGE(PG8_SA(0, 0), a2, voffA);
;             PG8_BAR; PG8_WAIT_L(0); PG8_MMA(1, 0, At, B0); PG8_BAR; PG8_SCHED;
;             PG8_STAGE(PG8_SB(0, 1), b2 + hstep, voffB);
;             PG8_WAIT_V(6); PG8_BAR; PG8_MMA(1, 1, At, B1); PG8_BAR;
.LBB0_927:
	s_add_u32 s36, s36, 0xb0080
	s_addc_u32 s37, s37, 0
	s_add_u32 s71, s38, 0x100
	s_addc_u32 s72, s39, 0
	s_mov_b32 s73, -2
	ds_read_b128 v[128:131], v173
	ds_read_b128 v[132:135], v173 offset:1024
	ds_read_b128 v[136:139], v173 offset:2048
	ds_read_b128 v[140:143], v173 offset:3072
	s_add_u32 s38, s36, 0xfff50080
	s_addc_u32 s39, s37, -1
	s_cmp_eq_u32 s73, 40
	s_cselect_b32 s41, s7, s39
	s_cselect_b32 s40, s6, s38
	s_cselect_b32 s39, s9, s72
	s_cselect_b32 s38, s8, s71
	s_add_i32 m0, s49, 0xc000
	ds_read_b128 v[144:147], v174
	ds_read_b128 v[164:167], v174 offset:1024
	ds_read_b128 v[176:179], v174 offset:2048
	ds_read_b128 v[182:185], v174 offset:3072
	ds_read_b128 v[186:189], v174 offset:4096
	ds_read_b128 v[190:193], v174 offset:5120
	ds_read_b128 v[194:197], v174 offset:6144
	ds_read_b128 v[198:201], v174 offset:7168
	global_load_lds_dwordx4 v156, s[36:37]
	s_add_i32 m0, s49, 0xe000
	s_nop 0
	global_load_lds_dwordx4 v158, s[36:37]
	s_waitcnt lgkmcnt(8)
	s_barrier
	s_waitcnt lgkmcnt(7)
	v_mfma_f32_16x16x32_bf16 v[124:127], v[128:131], v[144:147], 0
	v_mfma_f32_16x16x32_bf16 v[120:123], v[136:139], v[144:147], 0
	s_waitcnt lgkmcnt(5)
	v_mfma_f32_16x16x32_bf16 v[116:119], v[128:131], v[176:179], 0
	v_mfma_f32_16x16x32_bf16 v[108:111], v[136:139], v[176:179], 0
	s_waitcnt lgkmcnt(3)
	v_mfma_f32_16x16x32_bf16 v[92:95], v[128:131], v[186:189], 0
	v_mfma_f32_16x16x32_bf16 v[88:91], v[136:139], v[186:189], 0
	s_waitcnt lgkmcnt(1)
	v_mfma_f32_16x16x32_bf16 v[76:79], v[128:131], v[194:197], 0
	v_mfma_f32_16x16x32_bf16 v[72:75], v[136:139], v[194:197], 0
	v_mfma_f32_16x16x32_bf16 v[124:127], v[132:135], v[164:167], v[124:127]
	v_mfma_f32_16x16x32_bf16 v[120:123], v[140:143], v[164:167], v[120:123]
	v_mfma_f32_16x16x32_bf16 v[116:119], v[132:135], v[182:185], v[116:119]
	v_mfma_f32_16x16x32_bf16 v[108:111], v[140:143], v[182:185], v[108:111]
	v_mfma_f32_16x16x32_bf16 v[92:95], v[132:135], v[190:193], v[92:95]
	v_mfma_f32_16x16x32_bf16 v[88:91], v[140:143], v[190:193], v[88:91]
	s_waitcnt lgkmcnt(0)
	v_mfma_f32_16x16x32_bf16 v[76:79], v[132:135], v[198:201], v[76:79]
	v_mfma_f32_16x16x32_bf16 v[72:75], v[140:143], v[198:201], v[72:75]
	s_barrier
	s_add_i32 s74, s59, s48
	s_add_u32 s86, s38, s16
	s_addc_u32 s87, s39, s17
	s_mov_b32 m0, s74
	ds_read_b128 v[202:205], v175
	ds_read_b128 v[206:209], v175 offset:1024
	ds_read_b128 v[210:213], v175 offset:2048
	ds_read_b128 v[214:217], v175 offset:3072
	global_load_lds_dwordx4 v150, s[38:39]
	s_add_i32 m0, s74, 0x2000
	s_nop 0
	global_load_lds_dwordx4 v154, s[38:39]
	s_barrier
	s_waitcnt lgkmcnt(3)
	v_mfma_f32_16x16x32_bf16 v[112:115], v[202:205], v[144:147], 0
	s_waitcnt lgkmcnt(1)
	v_mfma_f32_16x16x32_bf16 v[104:107], v[210:213], v[144:147], 0
	v_mfma_f32_16x16x32_bf16 v[100:103], v[202:205], v[176:179], 0
	v_mfma_f32_16x16x32_bf16 v[96:99], v[210:213], v[176:179], 0
	v_mfma_f32_16x16x32_bf16 v[84:87], v[202:205], v[186:189], 0
	v_mfma_f32_16x16x32_bf16 v[80:83], v[210:213], v[186:189], 0
	v_mfma_f32_16x16x32_bf16 v[68:71], v[202:205], v[194:197], 0
	v_mfma_f32_16x16x32_bf16 v[64:67], v[210:213], v[194:197], 0
	v_mfma_f32_16x16x32_bf16 v[112:115], v[206:209], v[164:167], v[112:115]
	s_waitcnt lgkmcnt(0)
	v_mfma_f32_16x16x32_bf16 v[104:107], v[214:217], v[164:167], v[104:107]
	v_mfma_f32_16x16x32_bf16 v[100:103], v[206:209], v[182:185], v[100:103]
	v_mfma_f32_16x16x32_bf16 v[96:99], v[214:217], v[182:185], v[96:99]
	v_mfma_f32_16x16x32_bf16 v[84:87], v[206:209], v[190:193], v[84:87]
	v_mfma_f32_16x16x32_bf16 v[80:83], v[214:217], v[190:193], v[80:83]
	v_mfma_f32_16x16x32_bf16 v[68:71], v[206:209], v[198:201], v[68:71]
	v_mfma_f32_16x16x32_bf16 v[64:67], v[214:217], v[198:201], v[64:67]
	s_mov_b32 m0, s49
	s_add_u32 s88, s40, s16
	s_addc_u32 s89, s41, s17
	s_barrier
	ds_read_b128 v[144:147], v174 offset:16384
	ds_read_b128 v[164:167], v174 offset:17408
	ds_read_b128 v[176:179], v174 offset:18432
	ds_read_b128 v[182:185], v174 offset:19456
	ds_read_b128 v[186:189], v174 offset:20480
	ds_read_b128 v[190:193], v174 offset:21504
	ds_read_b128 v[194:197], v174 offset:22528
	ds_read_b128 v[198:201], v174 offset:23552
	global_load_lds_dwordx4 v148, s[40:41]
	s_mov_b32 m0, s50
	s_nop 0
	global_load_lds_dwordx4 v152, s[40:41]
	s_barrier
	s_waitcnt lgkmcnt(7)
	v_mfma_f32_16x16x32_bf16 v[60:63], v[128:131], v[144:147], 0
	v_mfma_f32_16x16x32_bf16 v[56:59], v[136:139], v[144:147], 0
	s_waitcnt lgkmcnt(5)
	v_mfma_f32_16x16x32_bf16 v[44:47], v[128:131], v[176:179], 0
	v_mfma_f32_16x16x32_bf16 v[40:43], v[136:139], v[176:179], 0
	s_waitcnt lgkmcnt(3)
	v_mfma_f32_16x16x32_bf16 v[36:39], v[128:131], v[186:189], 0
	v_mfma_f32_16x16x32_bf16 v[32:35], v[136:139], v[186:189], 0
	s_waitcnt lgkmcnt(1)
	v_mfma_f32_16x16x32_bf16 v[20:23], v[128:131], v[194:197], 0
	v_mfma_f32_16x16x32_bf16 v[16:19], v[136:139], v[194:197], 0
	v_mfma_f32_16x16x32_bf16 v[60:63], v[132:135], v[164:167], v[60:63]
	v_mfma_f32_16x16x32_bf16 v[56:59], v[140:143], v[164:167], v[56:59]
	v_mfma_f32_16x16x32_bf16 v[44:47], v[132:135], v[182:185], v[44:47]
	v_mfma_f32_16x16x32_bf16 v[40:43], v[140:143], v[182:185], v[40:43]
	v_mfma_f32_16x16x32_bf16 v[36:39], v[132:135], v[190:193], v[36:39]
	v_mfma_f32_16x16x32_bf16 v[32:35], v[140:143], v[190:193], v[32:35]
	s_waitcnt lgkmcnt(0)
	v_mfma_f32_16x16x32_bf16 v[20:23], v[132:135], v[198:201], v[20:23]
	v_mfma_f32_16x16x32_bf16 v[16:19], v[140:143], v[198:201], v[16:19]
	s_barrier
	s_add_u32 s74, s38, 0xb0000
	s_addc_u32 s75, s39, 0
	s_add_i32 s76, s60, s48
	s_mov_b32 m0, s76
	s_nop 0
	global_load_lds_dwordx4 v150, s[74:75]
	s_add_i32 m0, s76, 0x2000
	s_nop 0
	global_load_lds_dwordx4 v154, s[74:75]
	s_waitcnt vmcnt(6)
	s_barrier
; #define PG8_STAGE(bufoff, gbase, voff) do { _Pragma("unroll") for (int _i = 0; _i < 2; ++_i) \
;         __builtin_amdgcn_global_load_lds((const unsigned*)((const char*)(gbase) + (voff)[_i]), (LAS unsigned*)(lds + (bufoff) + ldsw + _i * 8192), 16, 0, 0); } while (0)
; #define PG8_LDA(dst, b, h) do { _Pragma("unroll") for (int m = 0; m < 4; ++m) _Pragma("unroll") for (int k = 0; k < 2; ++k) dst[m][k] = *(const LAS bf16x8*)(lds + PG8_SA(b, h) + aoff + m * 2048 + k * 1024); } while (0)
; #define PG8_LDB(dst, b, h) do { _Pragma("unroll") for (int n = 0; n < 2; ++n) _Pragma("unroll") for (int k = 0; k < 2; ++k) dst[n][k] = *(const LAS bf16x8*)(lds + PG8_SB(b, h) + boff + n * 2048 + k * 1024); } while (0)
; #define PG8_MMA(ai, bj, At, Bt) do { __builtin_amdgcn_s_setprio(1); _Pragma("unroll") for (int m = 0; m < 4; ++m) _Pragma("unroll") for (int n = 0; n < 2; ++n) _Pragma("unroll") for (int k = 0; k < 2; ++k) \
;         acc[ai][bj][m][n] = __builtin_amdgcn_mfma_f32_16x16x32_bf16(Bt[n][k], At[m][k], acc[ai][bj][m][n], 0, 0, 0); __builtin_amdgcn_s_setprio(0); } while (0)
; #define PG8_WAIT_V(n) asm volatile("s_waitcnt vmcnt(" #n ")" ::: "memory")
; #define PG8_WAIT_L(n) asm volatile("s_waitcnt lgkmcnt(" #n ")" ::: "memory")
; #define PG8_BAR __builtin_amdgcn_s_barrier()
; #define PG8_SCHED __builtin_amdgcn_sched_barrier(0)
; template <class Epi>
; DI void gemm_phase(LAS unsigned char* lds, const Gemm g, const StaticOrder& S, const Epi& E) {
;     ...
;             PG8_WAIT_V(6); PG8_BAR; PG8_MMA(1, 1, At, B1); PG8_BAR;
;             PG8_LDB(B0, 1, 0); PG8_SCHED; PG8_LDA(At, 1, 0); PG8_STAGE(PG8_SA(0, 1), a2 + hstep, voffA);
;             PG8_WAIT_L(8); PG8_BAR; PG8_WAIT_L(0); PG8_MMA(0, 0, At, B0); PG8_BAR; PG8_SCHED;
;             PG8_LDB(B1, 1, 1); PG8_STAGE(PG8_SB(1, 0), b3, voffB);
;             PG8_BAR; PG8_WAIT_L(0); PG8_MMA(0, 1, At, B1); PG8_BAR;
;             PG8_LDA(At, 1, 1); PG8_STAGE(PG8_SA(1, 0), a3, voffA);
	v_mfma_f32_16x16x32_bf16 v[52:55], v[202:205], v[144:147], 0
	v_mfma_f32_16x16x32_bf16 v[48:51], v[210:213], v[144:147], 0
	v_mfma_f32_16x16x32_bf16 v[28:31], v[202:205], v[176:179], 0
	v_mfma_f32_16x16x32_bf16 v[24:27], v[210:213], v[176:179], 0
	v_mfma_f32_16x16x32_bf16 v[12:15], v[202:205], v[186:189], 0
	v_mfma_f32_16x16x32_bf16 v[8:11], v[210:213], v[186:189], 0
	v_mfma_f32_16x16x32_bf16 v[4:7], v[202:205], v[194:197], 0
	v_mfma_f32_16x16x32_bf16 v[0:3], v[210:213], v[194:197], 0
	v_mfma_f32_16x16x32_bf16 v[52:55], v[206:209], v[164:167], v[52:55]
	v_mfma_f32_16x16x32_bf16 v[48:51], v[214:217], v[164:167], v[48:51]
	v_mfma_f32_16x16x32_bf16 v[28:31], v[206:209], v[182:185], v[28:31]
	v_mfma_f32_16x16x32_bf16 v[24:27], v[214:217], v[182:185], v[24:27]
	v_mfma_f32_16x16x32_bf16 v[12:15], v[206:209], v[190:193], v[12:15]
	v_mfma_f32_16x16x32_bf16 v[8:11], v[214:217], v[190:193], v[8:11]
	v_mfma_f32_16x16x32_bf16 v[4:7], v[206:209], v[198:201], v[4:7]
	v_mfma_f32_16x16x32_bf16 v[0:3], v[214:217], v[198:201], v[0:3]
	s_add_i32 s74, 0, 0x18000
	v_add_u32_e32 v140, s74, v171
	s_barrier
	ds_read_b128 v[128:131], v140
	ds_read_b128 v[132:135], v140 offset:1024
	ds_read_b128 v[136:139], v140 offset:2048
	ds_read_b128 v[140:143], v140 offset:3072
	s_add_u32 s40, s40, 0xb0000
	s_addc_u32 s41, s41, 0
	s_mov_b32 m0, s51
	ds_read_b128 v[144:147], v174 offset:32768
	ds_read_b128 v[164:167], v174 offset:33792
	ds_read_b128 v[176:179], v174 offset:34816
	ds_read_b128 v[182:185], v174 offset:35840
	ds_read_b128 v[186:189], v174 offset:36864
	ds_read_b128 v[190:193], v174 offset:37888
	ds_read_b128 v[194:197], v174 offset:38912
	ds_read_b128 v[198:201], v174 offset:39936
	global_load_lds_dwordx4 v148, s[40:41]
	s_mov_b32 m0, s52
	s_nop 0
	global_load_lds_dwordx4 v152, s[40:41]
	s_waitcnt lgkmcnt(8)
	s_barrier
	s_waitcnt lgkmcnt(7)
	v_mfma_f32_16x16x32_bf16 v[124:127], v[128:131], v[144:147], v[124:127]
	v_mfma_f32_16x16x32_bf16 v[120:123], v[136:139], v[144:147], v[120:123]
	s_waitcnt lgkmcnt(5)
	v_mfma_f32_16x16x32_bf16 v[116:119], v[128:131], v[176:179], v[116:119]
	v_mfma_f32_16x16x32_bf16 v[108:111], v[136:139], v[176:179], v[108:111]
	s_waitcnt lgkmcnt(3)
	v_mfma_f32_16x16x32_bf16 v[92:95], v[128:131], v[186:189], v[92:95]
	v_mfma_f32_16x16x32_bf16 v[88:91], v[136:139], v[186:189], v[88:91]
	s_waitcnt lgkmcnt(1)
	v_mfma_f32_16x16x32_bf16 v[76:79], v[128:131], v[194:197], v[76:79]
	v_mfma_f32_16x16x32_bf16 v[72:75], v[136:139], v[194:197], v[72:75]
	v_mfma_f32_16x16x32_bf16 v[124:127], v[132:135], v[164:167], v[124:127]
	v_mfma_f32_16x16x32_bf16 v[120:123], v[140:143], v[164:167], v[120:123]
	v_mfma_f32_16x16x32_bf16 v[116:119], v[132:135], v[182:185], v[116:119]
	v_mfma_f32_16x16x32_bf16 v[108:111], v[140:143], v[182:185], v[108:111]
	v_mfma_f32_16x16x32_bf16 v[92:95], v[132:135], v[190:193], v[92:95]
	v_mfma_f32_16x16x32_bf16 v[88:91], v[140:143], v[190:193], v[88:91]
	s_waitcnt lgkmcnt(0)
	v_mfma_f32_16x16x32_bf16 v[76:79], v[132:135], v[198:201], v[76:79]
	v_mfma_f32_16x16x32_bf16 v[72:75], v[140:143], v[198:201], v[72:75]
	s_barrier
	s_add_i32 s40, 0, 0x1c000
	s_add_i32 s41, s74, s48
	v_add_u32_e32 v214, s40, v171
	s_mov_b32 m0, s41
	ds_read_b128 v[202:205], v214
	ds_read_b128 v[206:209], v214 offset:1024
	ds_read_b128 v[210:213], v214 offset:2048
	ds_read_b128 v[214:217], v214 offset:3072
	global_load_lds_dwordx4 v150, s[86:87]
	s_add_i32 m0, s41, 0x2000
	s_nop 0
	global_load_lds_dwordx4 v154, s[86:87]
	s_barrier
	s_waitcnt lgkmcnt(3)
	v_mfma_f32_16x16x32_bf16 v[112:115], v[202:205], v[144:147], v[112:115]
	s_waitcnt lgkmcnt(1)
	v_mfma_f32_16x16x32_bf16 v[104:107], v[210:213], v[144:147], v[104:107]
	v_mfma_f32_16x16x32_bf16 v[100:103], v[202:205], v[176:179], v[100:103]
	v_mfma_f32_16x16x32_bf16 v[96:99], v[210:213], v[176:179], v[96:99]
	v_mfma_f32_16x16x32_bf16 v[84:87], v[202:205], v[186:189], v[84:87]
	v_mfma_f32_16x16x32_bf16 v[80:83], v[210:213], v[186:189], v[80:83]
	v_mfma_f32_16x16x32_bf16 v[68:71], v[202:205], v[194:197], v[68:71]
	v_mfma_f32_16x16x32_bf16 v[64:67], v[210:213], v[194:197], v[64:67]
	v_mfma_f32_16x16x32_bf16 v[112:115], v[206:209], v[164:167], v[112:115]
	s_waitcnt lgkmcnt(0)
	v_mfma_f32_16x16x32_bf16 v[104:107], v[214:217], v[164:167], v[104:107]
	v_mfma_f32_16x16x32_bf16 v[100:103], v[206:209], v[182:185], v[100:103]
	v_mfma_f32_16x16x32_bf16 v[96:99], v[214:217], v[182:185], v[96:99]
	v_mfma_f32_16x16x32_bf16 v[84:87], v[206:209], v[190:193], v[84:87]
	v_mfma_f32_16x16x32_bf16 v[80:83], v[214:217], v[190:193], v[80:83]
	v_mfma_f32_16x16x32_bf16 v[68:71], v[206:209], v[198:201], v[68:71]
	v_mfma_f32_16x16x32_bf16 v[64:67], v[214:217], v[198:201], v[64:67]
	s_mov_b32 m0, s56
	s_barrier
	ds_read_b128 v[144:147], v174 offset:49152
	ds_read_b128 v[164:167], v174 offset:50176
	ds_read_b128 v[176:179], v174 offset:51200
	ds_read_b128 v[182:185], v174 offset:52224
	ds_read_b128 v[186:189], v174 offset:53248
	ds_read_b128 v[190:193], v174 offset:54272
	ds_read_b128 v[194:197], v174 offset:55296
	ds_read_b128 v[198:201], v174 offset:56320
	global_load_lds_dwordx4 v148, s[88:89]
	s_mov_b32 m0, s57
	s_nop 0
	global_load_lds_dwordx4 v152, s[88:89]
	s_barrier
; #define PG8_STAGE(bufoff, gbase, voff) do { _Pragma("unroll") for (int _i = 0; _i < 2; ++_i) \
;         __builtin_amdgcn_global_load_lds((const unsigned*)((const char*)(gbase) + (voff)[_i]), (LAS unsigned*)(lds + (bufoff) + ldsw + _i * 8192), 16, 0, 0); } while (0)
; #define PG8_LDA(dst, b, h) do { _Pragma("unroll") for (int m = 0; m < 4; ++m) _Pragma("unroll") for (int k = 0; k < 2; ++k) dst[m][k] = *(const LAS bf16x8*)(lds + PG8_SA(b, h) + aoff + m * 2048 + k * 1024); } while (0)
; #define PG8_LDB(dst, b, h) do { _Pragma("unroll") for (int n = 0; n < 2; ++n) _Pragma("unroll") for (int k = 0; k < 2; ++k) dst[n][k] = *(const LAS bf16x8*)(lds + PG8_SB(b, h) + boff + n * 2048 + k * 1024); } while (0)
; #define PG8_MMA(ai, bj, At, Bt) do { __builtin_amdgcn_s_setprio(1); _Pragma("unroll") for (int m = 0; m < 4; ++m) _Pragma("unroll") for (int n = 0; n < 2; ++n) _Pragma("unroll") for (int k = 0; k < 2; ++k) \
;         acc[ai][bj][m][n] = __builtin_amdgcn_mfma_f32_16x16x32_bf16(Bt[n][k], At[m][k], acc[ai][bj][m][n], 0, 0, 0); __builtin_amdgcn_s_setprio(0); } while (0)
; #define PG8_WAIT_V(n) asm volatile("s_waitcnt vmcnt(" #n ")" ::: "memory")
; #define PG8_WAIT_L(n) asm volatile("s_waitcnt lgkmcnt(" #n ")" ::: "memory")
; #define PG8_BAR __builtin_amdgcn_s_barrier()
; #define PG8_SCHED __builtin_amdgcn_sched_barrier(0)
; template <class Epi>
; DI void gemm_phase(LAS unsigned char* lds, const Gemm g, const StaticOrder& S, const Epi& E) {
;     ...
;             PG8_LDB(B0, 0, 0); PG8_SCHED; PG8_LDA(At, 0, 0); PG8_STAGE(PG8_SA(1, 1), a1 + hstep, voffA);
;             PG8_WAIT_L(8); PG8_BAR; PG8_WAIT_L(0); PG8_MMA(0, 0, At, B0); PG8_BAR; PG8_SCHED;
;             PG8_LDB(B1, 0, 1); PG8_STAGE(PG8_SB(0, 0), b2, voffB);
;     ...
;             PG8_BAR; PG8_WAIT_L(0); PG8_MMA(1, 0, At, B0); PG8_BAR; PG8_SCHED;
;             PG8_STAGE(PG8_SB(1, 1), b3 + hstep, voffB);
;             PG8_WAIT_V(6); PG8_BAR; PG8_MMA(1, 1, At, B1); PG8_BAR;
	s_waitcnt lgkmcnt(7)
	v_mfma_f32_16x16x32_bf16 v[60:63], v[128:131], v[144:147], v[60:63]
	v_mfma_f32_16x16x32_bf16 v[56:59], v[136:139], v[144:147], v[56:59]
	s_waitcnt lgkmcnt(5)
	v_mfma_f32_16x16x32_bf16 v[44:47], v[128:131], v[176:179], v[44:47]
	v_mfma_f32_16x16x32_bf16 v[40:43], v[136:139], v[176:179], v[40:43]
	s_waitcnt lgkmcnt(3)
	v_mfma_f32_16x16x32_bf16 v[36:39], v[128:131], v[186:189], v[36:39]
	v_mfma_f32_16x16x32_bf16 v[32:35], v[136:139], v[186:189], v[32:35]
	s_waitcnt lgkmcnt(1)
	v_mfma_f32_16x16x32_bf16 v[20:23], v[128:131], v[194:197], v[20:23]
	v_mfma_f32_16x16x32_bf16 v[16:19], v[136:139], v[194:197], v[16:19]
	v_mfma_f32_16x16x32_bf16 v[60:63], v[132:135], v[164:167], v[60:63]
	v_mfma_f32_16x16x32_bf16 v[56:59], v[140:143], v[164:167], v[56:59]
	v_mfma_f32_16x16x32_bf16 v[44:47], v[132:135], v[182:185], v[44:47]
	v_mfma_f32_16x16x32_bf16 v[40:43], v[140:143], v[182:185], v[40:43]
	v_mfma_f32_16x16x32_bf16 v[36:39], v[132:135], v[190:193], v[36:39]
	v_mfma_f32_16x16x32_bf16 v[32:35], v[140:143], v[190:193], v[32:35]
	s_waitcnt lgkmcnt(0)
	v_mfma_f32_16x16x32_bf16 v[20:23], v[132:135], v[198:201], v[20:23]
	v_mfma_f32_16x16x32_bf16 v[16:19], v[140:143], v[198:201], v[16:19]
	s_barrier
	s_add_u32 s38, s38, 0xb0080
	s_addc_u32 s39, s39, 0
	s_add_i32 s40, s40, s48
	s_mov_b32 m0, s40
	s_nop 0
	global_load_lds_dwordx4 v150, s[38:39]
	s_add_i32 m0, s40, 0x2000
	s_nop 0
	global_load_lds_dwordx4 v154, s[38:39]
	s_waitcnt vmcnt(6)
	s_barrier
	v_mfma_f32_16x16x32_bf16 v[52:55], v[202:205], v[144:147], v[52:55]
	v_mfma_f32_16x16x32_bf16 v[48:51], v[210:213], v[144:147], v[48:51]
	v_mfma_f32_16x16x32_bf16 v[28:31], v[202:205], v[176:179], v[28:31]
	v_mfma_f32_16x16x32_bf16 v[24:27], v[210:213], v[176:179], v[24:27]
	v_mfma_f32_16x16x32_bf16 v[12:15], v[202:205], v[186:189], v[12:15]
	v_mfma_f32_16x16x32_bf16 v[8:11], v[210:213], v[186:189], v[8:11]
	v_mfma_f32_16x16x32_bf16 v[4:7], v[202:205], v[194:197], v[4:7]
	v_mfma_f32_16x16x32_bf16 v[0:3], v[210:213], v[194:197], v[0:3]
	v_mfma_f32_16x16x32_bf16 v[52:55], v[206:209], v[164:167], v[52:55]
	v_mfma_f32_16x16x32_bf16 v[48:51], v[214:217], v[164:167], v[48:51]
	v_mfma_f32_16x16x32_bf16 v[28:31], v[206:209], v[182:185], v[28:31]
	v_mfma_f32_16x16x32_bf16 v[24:27], v[214:217], v[182:185], v[24:27]
	v_mfma_f32_16x16x32_bf16 v[12:15], v[206:209], v[190:193], v[12:15]
	v_mfma_f32_16x16x32_bf16 v[8:11], v[214:217], v[190:193], v[8:11]
	v_mfma_f32_16x16x32_bf16 v[4:7], v[206:209], v[198:201], v[4:7]
	v_mfma_f32_16x16x32_bf16 v[0:3], v[214:217], v[198:201], v[0:3]
	s_add_i32 s73, s73, 2
	s_add_u32 s36, s36, 0x100
	s_addc_u32 s37, s37, 0
	s_add_u32 s71, s71, 0x100
	s_addc_u32 s72, s72, 0
	s_cmp_gt_u32 s73, 41
	s_barrier
.LBB0_928:
	ds_read_b128 v[128:131], v173
	ds_read_b128 v[132:135], v173 offset:1024
	ds_read_b128 v[136:139], v173 offset:2048
	ds_read_b128 v[140:143], v173 offset:3072
	s_add_u32 s38, s36, 0xfff50080
	s_addc_u32 s39, s37, -1
	s_cmp_eq_u32 s73, 40
	s_cselect_b32 s41, s7, s39
	s_cselect_b32 s40, s6, s38
	s_cselect_b32 s39, s9, s72
	s_cselect_b32 s38, s8, s71
	s_add_i32 m0, s49, 0xc000
	ds_read_b128 v[144:147], v174
	ds_read_b128 v[164:167], v174 offset:1024
	ds_read_b128 v[176:179], v174 offset:2048
	ds_read_b128 v[182:185], v174 offset:3072
	ds_read_b128 v[186:189], v174 offset:4096
	ds_read_b128 v[190:193], v174 offset:5120
	ds_read_b128 v[194:197], v174 offset:6144
	ds_read_b128 v[198:201], v174 offset:7168
	global_load_lds_dwordx4 v156, s[36:37]
	s_add_i32 m0, s49, 0xe000
	s_nop 0
	global_load_lds_dwordx4 v158, s[36:37]
	s_waitcnt lgkmcnt(8)
	s_barrier
	s_waitcnt lgkmcnt(7)
	v_mfma_f32_16x16x32_bf16 v[124:127], v[128:131], v[144:147], v[124:127]
	v_mfma_f32_16x16x32_bf16 v[120:123], v[136:139], v[144:147], v[120:123]
	s_waitcnt lgkmcnt(5)
	v_mfma_f32_16x16x32_bf16 v[116:119], v[128:131], v[176:179], v[116:119]
	v_mfma_f32_16x16x32_bf16 v[108:111], v[136:139], v[176:179], v[108:111]
	s_waitcnt lgkmcnt(3)
	v_mfma_f32_16x16x32_bf16 v[92:95], v[128:131], v[186:189], v[92:95]
	v_mfma_f32_16x16x32_bf16 v[88:91], v[136:139], v[186:189], v[88:91]
	s_waitcnt lgkmcnt(1)
	v_mfma_f32_16x16x32_bf16 v[76:79], v[128:131], v[194:197], v[76:79]
	v_mfma_f32_16x16x32_bf16 v[72:75], v[136:139], v[194:197], v[72:75]
	v_mfma_f32_16x16x32_bf16 v[124:127], v[132:135], v[164:167], v[124:127]
	v_mfma_f32_16x16x32_bf16 v[120:123], v[140:143], v[164:167], v[120:123]
	v_mfma_f32_16x16x32_bf16 v[116:119], v[132:135], v[182:185], v[116:119]
	v_mfma_f32_16x16x32_bf16 v[108:111], v[140:143], v[182:185], v[108:111]
	v_mfma_f32_16x16x32_bf16 v[92:95], v[132:135], v[190:193], v[92:95]
	v_mfma_f32_16x16x32_bf16 v[88:91], v[140:143], v[190:193], v[88:91]
	s_waitcnt lgkmcnt(0)
	v_mfma_f32_16x16x32_bf16 v[76:79], v[132:135], v[198:201], v[76:79]
	v_mfma_f32_16x16x32_bf16 v[72:75], v[140:143], v[198:201], v[72:75]
	s_barrier
	s_add_i32 s74, s59, s48
	s_add_u32 s86, s38, s16
	s_addc_u32 s87, s39, s17
	s_mov_b32 m0, s74
	ds_read_b128 v[202:205], v175
	ds_read_b128 v[206:209], v175 offset:1024
	ds_read_b128 v[210:213], v175 offset:2048
	ds_read_b128 v[214:217], v175 offset:3072
	global_load_lds_dwordx4 v150, s[38:39]
	s_add_i32 m0, s74, 0x2000
	s_nop 0
	global_load_lds_dwordx4 v154, s[38:39]
	s_barrier
; #define PG8_STAGE(bufoff, gbase, voff) do { _Pragma("unroll") for (int _i = 0; _i < 2; ++_i) \
;         __builtin_amdgcn_global_load_lds((const unsigned*)((const char*)(gbase) + (voff)[_i]), (LAS unsigned*)(lds + (bufoff) + ldsw + _i * 8192), 16, 0, 0); } while (0)
; #define PG8_LDA(dst, b, h) do { _Pragma("unroll") for (int m = 0; m < 4; ++m) _Pragma("unroll") for (int k = 0; k < 2; ++k) dst[m][k] = *(const LAS bf16x8*)(lds + PG8_SA(b, h) + aoff + m * 2048 + k * 1024); } while (0)
; #define PG8_LDB(dst, b, h) do { _Pragma("unroll") for (int n = 0; n < 2; ++n) _Pragma("unroll") for (int k = 0; k < 2; ++k) dst[n][k] = *(const LAS bf16x8*)(lds + PG8_SB(b, h) + boff + n * 2048 + k * 1024); } while (0)
; #define PG8_MMA(ai, bj, At, Bt) do { __builtin_amdgcn_s_setprio(1); _Pragma("unroll") for (int m = 0; m < 4; ++m) _Pragma("unroll") for (int n = 0; n < 2; ++n) _Pragma("unroll") for (int k = 0; k < 2; ++k) \
;         acc[ai][bj][m][n] = __builtin_amdgcn_mfma_f32_16x16x32_bf16(Bt[n][k], At[m][k], acc[ai][bj][m][n], 0, 0, 0); __builtin_amdgcn_s_setprio(0); } while (0)
; #define PG8_WAIT_V(n) asm volatile("s_waitcnt vmcnt(" #n ")" ::: "memory")
; #define PG8_WAIT_L(n) asm volatile("s_waitcnt lgkmcnt(" #n ")" ::: "memory")
; #define PG8_BAR __builtin_amdgcn_s_barrier()
; #define PG8_SCHED __builtin_amdgcn_sched_barrier(0)
; template <class Epi>
; DI void gemm_phase(LAS unsigned char* lds, const Gemm g, const StaticOrder& S, const Epi& E) {
;     ...
;             PG8_BAR; PG8_WAIT_L(0); PG8_MMA(0, 1, At, B1); PG8_BAR;
;             PG8_LDA(At, 0, 1); PG8_STAGE(PG8_SA(0, 0), a2, voffA);
;             PG8_BAR; PG8_WAIT_L(0); PG8_MMA(1, 0, At, B0); PG8_BAR; PG8_SCHED;
;             PG8_STAGE(PG8_SB(0, 1), b2 + hstep, voffB);
;             PG8_WAIT_V(6); PG8_BAR; PG8_MMA(1, 1, At, B1); PG8_BAR;
;             PG8_LDB(B0, 1, 0); PG8_SCHED; PG8_LDA(At, 1, 0); PG8_STAGE(PG8_SA(0, 1), a2 + hstep, voffA);
;             PG8_WAIT_L(8); PG8_BAR; PG8_WAIT_L(0); PG8_MMA(0, 0, At, B0); PG8_BAR; PG8_SCHED;
;             PG8_LDB(B1, 1, 1); PG8_STAGE(PG8_SB(1, 0), b3, voffB);
	s_waitcnt lgkmcnt(3)
	v_mfma_f32_16x16x32_bf16 v[112:115], v[202:205], v[144:147], v[112:115]
	s_waitcnt lgkmcnt(1)
	v_mfma_f32_16x16x32_bf16 v[104:107], v[210:213], v[144:147], v[104:107]
	v_mfma_f32_16x16x32_bf16 v[100:103], v[202:205], v[176:179], v[100:103]
	v_mfma_f32_16x16x32_bf16 v[96:99], v[210:213], v[176:179], v[96:99]
	v_mfma_f32_16x16x32_bf16 v[84:87], v[202:205], v[186:189], v[84:87]
	v_mfma_f32_16x16x32_bf16 v[80:83], v[210:213], v[186:189], v[80:83]
	v_mfma_f32_16x16x32_bf16 v[68:71], v[202:205], v[194:197], v[68:71]
	v_mfma_f32_16x16x32_bf16 v[64:67], v[210:213], v[194:197], v[64:67]
	v_mfma_f32_16x16x32_bf16 v[112:115], v[206:209], v[164:167], v[112:115]
	s_waitcnt lgkmcnt(0)
	v_mfma_f32_16x16x32_bf16 v[104:107], v[214:217], v[164:167], v[104:107]
	v_mfma_f32_16x16x32_bf16 v[100:103], v[206:209], v[182:185], v[100:103]
	v_mfma_f32_16x16x32_bf16 v[96:99], v[214:217], v[182:185], v[96:99]
	v_mfma_f32_16x16x32_bf16 v[84:87], v[206:209], v[190:193], v[84:87]
	v_mfma_f32_16x16x32_bf16 v[80:83], v[214:217], v[190:193], v[80:83]
	v_mfma_f32_16x16x32_bf16 v[68:71], v[206:209], v[198:201], v[68:71]
	v_mfma_f32_16x16x32_bf16 v[64:67], v[214:217], v[198:201], v[64:67]
	s_mov_b32 m0, s49
	s_add_u32 s88, s40, s16
	s_addc_u32 s89, s41, s17
	s_barrier
	ds_read_b128 v[144:147], v174 offset:16384
	ds_read_b128 v[164:167], v174 offset:17408
	ds_read_b128 v[176:179], v174 offset:18432
	ds_read_b128 v[182:185], v174 offset:19456
	ds_read_b128 v[186:189], v174 offset:20480
	ds_read_b128 v[190:193], v174 offset:21504
	ds_read_b128 v[194:197], v174 offset:22528
	ds_read_b128 v[198:201], v174 offset:23552
	global_load_lds_dwordx4 v148, s[40:41]
	s_mov_b32 m0, s50
	s_nop 0
	global_load_lds_dwordx4 v152, s[40:41]
	s_barrier
	s_waitcnt lgkmcnt(7)
	v_mfma_f32_16x16x32_bf16 v[60:63], v[128:131], v[144:147], v[60:63]
	v_mfma_f32_16x16x32_bf16 v[56:59], v[136:139], v[144:147], v[56:59]
	s_waitcnt lgkmcnt(5)
	v_mfma_f32_16x16x32_bf16 v[44:47], v[128:131], v[176:179], v[44:47]
	v_mfma_f32_16x16x32_bf16 v[40:43], v[136:139], v[176:179], v[40:43]
	s_waitcnt lgkmcnt(3)
	v_mfma_f32_16x16x32_bf16 v[36:39], v[128:131], v[186:189], v[36:39]
	v_mfma_f32_16x16x32_bf16 v[32:35], v[136:139], v[186:189], v[32:35]
	s_waitcnt lgkmcnt(1)
	v_mfma_f32_16x16x32_bf16 v[20:23], v[128:131], v[194:197], v[20:23]
	v_mfma_f32_16x16x32_bf16 v[16:19], v[136:139], v[194:197], v[16:19]
	v_mfma_f32_16x16x32_bf16 v[60:63], v[132:135], v[164:167], v[60:63]
	v_mfma_f32_16x16x32_bf16 v[56:59], v[140:143], v[164:167], v[56:59]
	v_mfma_f32_16x16x32_bf16 v[44:47], v[132:135], v[182:185], v[44:47]
	v_mfma_f32_16x16x32_bf16 v[40:43], v[140:143], v[182:185], v[40:43]
	v_mfma_f32_16x16x32_bf16 v[36:39], v[132:135], v[190:193], v[36:39]
	v_mfma_f32_16x16x32_bf16 v[32:35], v[140:143], v[190:193], v[32:35]
	s_waitcnt lgkmcnt(0)
	v_mfma_f32_16x16x32_bf16 v[20:23], v[132:135], v[198:201], v[20:23]
	v_mfma_f32_16x16x32_bf16 v[16:19], v[140:143], v[198:201], v[16:19]
	s_barrier
	s_add_u32 s74, s38, 0xb0000
	s_addc_u32 s75, s39, 0
	s_add_i32 s76, s60, s48
	s_mov_b32 m0, s76
	s_nop 0
	global_load_lds_dwordx4 v150, s[74:75]
	s_add_i32 m0, s76, 0x2000
	s_nop 0
	global_load_lds_dwordx4 v154, s[74:75]
	s_waitcnt vmcnt(6)
	s_barrier
	v_mfma_f32_16x16x32_bf16 v[52:55], v[202:205], v[144:147], v[52:55]
	v_mfma_f32_16x16x32_bf16 v[48:51], v[210:213], v[144:147], v[48:51]
	v_mfma_f32_16x16x32_bf16 v[28:31], v[202:205], v[176:179], v[28:31]
	v_mfma_f32_16x16x32_bf16 v[24:27], v[210:213], v[176:179], v[24:27]
	v_mfma_f32_16x16x32_bf16 v[12:15], v[202:205], v[186:189], v[12:15]
	v_mfma_f32_16x16x32_bf16 v[8:11], v[210:213], v[186:189], v[8:11]
	v_mfma_f32_16x16x32_bf16 v[4:7], v[202:205], v[194:197], v[4:7]
	v_mfma_f32_16x16x32_bf16 v[0:3], v[210:213], v[194:197], v[0:3]
	v_mfma_f32_16x16x32_bf16 v[52:55], v[206:209], v[164:167], v[52:55]
	v_mfma_f32_16x16x32_bf16 v[48:51], v[214:217], v[164:167], v[48:51]
	v_mfma_f32_16x16x32_bf16 v[28:31], v[206:209], v[182:185], v[28:31]
	v_mfma_f32_16x16x32_bf16 v[24:27], v[214:217], v[182:185], v[24:27]
	v_mfma_f32_16x16x32_bf16 v[12:15], v[206:209], v[190:193], v[12:15]
	v_mfma_f32_16x16x32_bf16 v[8:11], v[214:217], v[190:193], v[8:11]
	v_mfma_f32_16x16x32_bf16 v[4:7], v[206:209], v[198:201], v[4:7]
	v_mfma_f32_16x16x32_bf16 v[0:3], v[214:217], v[198:201], v[0:3]
	s_add_i32 s74, 0, 0x18000
	v_add_u32_e32 v140, s74, v171
	s_barrier
	ds_read_b128 v[128:131], v140
	ds_read_b128 v[132:135], v140 offset:1024
	ds_read_b128 v[136:139], v140 offset:2048
	ds_read_b128 v[140:143], v140 offset:3072
	s_add_u32 s40, s40, 0xb0000
	s_addc_u32 s41, s41, 0
	s_mov_b32 m0, s51
	ds_read_b128 v[144:147], v174 offset:32768
	ds_read_b128 v[164:167], v174 offset:33792
	ds_read_b128 v[176:179], v174 offset:34816
	ds_read_b128 v[182:185], v174 offset:35840
	ds_read_b128 v[186:189], v174 offset:36864
	ds_read_b128 v[190:193], v174 offset:37888
	ds_read_b128 v[194:197], v174 offset:38912
	ds_read_b128 v[198:201], v174 offset:39936
	global_load_lds_dwordx4 v148, s[40:41]
	s_mov_b32 m0, s52
	s_nop 0
	global_load_lds_dwordx4 v152, s[40:41]
	s_waitcnt lgkmcnt(8)
	s_barrier
; #define PG8_STAGE(bufoff, gbase, voff) do { _Pragma("unroll") for (int _i = 0; _i < 2; ++_i) \
;         __builtin_amdgcn_global_load_lds((const unsigned*)((const char*)(gbase) + (voff)[_i]), (LAS unsigned*)(lds + (bufoff) + ldsw + _i * 8192), 16, 0, 0); } while (0)
; #define PG8_LDA(dst, b, h) do { _Pragma("unroll") for (int m = 0; m < 4; ++m) _Pragma("unroll") for (int k = 0; k < 2; ++k) dst[m][k] = *(const LAS bf16x8*)(lds + PG8_SA(b, h) + aoff + m * 2048 + k * 1024); } while (0)
; #define PG8_LDB(dst, b, h) do { _Pragma("unroll") for (int n = 0; n < 2; ++n) _Pragma("unroll") for (int k = 0; k < 2; ++k) dst[n][k] = *(const LAS bf16x8*)(lds + PG8_SB(b, h) + boff + n * 2048 + k * 1024); } while (0)
; #define PG8_MMA(ai, bj, At, Bt) do { __builtin_amdgcn_s_setprio(1); _Pragma("unroll") for (int m = 0; m < 4; ++m) _Pragma("unroll") for (int n = 0; n < 2; ++n) _Pragma("unroll") for (int k = 0; k < 2; ++k) \
;         acc[ai][bj][m][n] = __builtin_amdgcn_mfma_f32_16x16x32_bf16(Bt[n][k], At[m][k], acc[ai][bj][m][n], 0, 0, 0); __builtin_amdgcn_s_setprio(0); } while (0)
; #define PG8_WAIT_V(n) asm volatile("s_waitcnt vmcnt(" #n ")" ::: "memory")
; #define PG8_WAIT_L(n) asm volatile("s_waitcnt lgkmcnt(" #n ")" ::: "memory")
; #define PG8_BAR __builtin_amdgcn_s_barrier()
; #define PG8_SCHED __builtin_amdgcn_sched_barrier(0)
; template <class Epi>
; DI void gemm_phase(LAS unsigned char* lds, const Gemm g, const StaticOrder& S, const Epi& E) {
;     ...
;             PG8_WAIT_L(8); PG8_BAR; PG8_WAIT_L(0); PG8_MMA(0, 0, At, B0); PG8_BAR; PG8_SCHED;
;             PG8_LDB(B1, 1, 1); PG8_STAGE(PG8_SB(1, 0), b3, voffB);
;             PG8_BAR; PG8_WAIT_L(0); PG8_MMA(0, 1, At, B1); PG8_BAR;
;             PG8_LDA(At, 1, 1); PG8_STAGE(PG8_SA(1, 0), a3, voffA);
;             PG8_BAR; PG8_WAIT_L(0); PG8_MMA(1, 0, At, B0); PG8_BAR; PG8_SCHED;
;             PG8_STAGE(PG8_SB(1, 1), b3 + hstep, voffB);
;             PG8_WAIT_V(6); PG8_BAR; PG8_MMA(1, 1, At, B1); PG8_BAR;
	s_waitcnt lgkmcnt(7)
	v_mfma_f32_16x16x32_bf16 v[124:127], v[128:131], v[144:147], v[124:127]
	v_mfma_f32_16x16x32_bf16 v[120:123], v[136:139], v[144:147], v[120:123]
	s_waitcnt lgkmcnt(5)
	v_mfma_f32_16x16x32_bf16 v[116:119], v[128:131], v[176:179], v[116:119]
	v_mfma_f32_16x16x32_bf16 v[108:111], v[136:139], v[176:179], v[108:111]
	s_waitcnt lgkmcnt(3)
	v_mfma_f32_16x16x32_bf16 v[92:95], v[128:131], v[186:189], v[92:95]
	v_mfma_f32_16x16x32_bf16 v[88:91], v[136:139], v[186:189], v[88:91]
	s_waitcnt lgkmcnt(1)
	v_mfma_f32_16x16x32_bf16 v[76:79], v[128:131], v[194:197], v[76:79]
	v_mfma_f32_16x16x32_bf16 v[72:75], v[136:139], v[194:197], v[72:75]
	v_mfma_f32_16x16x32_bf16 v[124:127], v[132:135], v[164:167], v[124:127]
	v_mfma_f32_16x16x32_bf16 v[120:123], v[140:143], v[164:167], v[120:123]
	v_mfma_f32_16x16x32_bf16 v[116:119], v[132:135], v[182:185], v[116:119]
	v_mfma_f32_16x16x32_bf16 v[108:111], v[140:143], v[182:185], v[108:111]
	v_mfma_f32_16x16x32_bf16 v[92:95], v[132:135], v[190:193], v[92:95]
	v_mfma_f32_16x16x32_bf16 v[88:91], v[140:143], v[190:193], v[88:91]
	s_waitcnt lgkmcnt(0)
	v_mfma_f32_16x16x32_bf16 v[76:79], v[132:135], v[198:201], v[76:79]
	v_mfma_f32_16x16x32_bf16 v[72:75], v[140:143], v[198:201], v[72:75]
	s_barrier
	s_add_i32 s40, 0, 0x1c000
	s_add_i32 s41, s74, s48
	v_add_u32_e32 v214, s40, v171
	s_mov_b32 m0, s41
	ds_read_b128 v[202:205], v214
	ds_read_b128 v[206:209], v214 offset:1024
	ds_read_b128 v[210:213], v214 offset:2048
	ds_read_b128 v[214:217], v214 offset:3072
	global_load_lds_dwordx4 v150, s[86:87]
	s_add_i32 m0, s41, 0x2000
	s_nop 0
	global_load_lds_dwordx4 v154, s[86:87]
	s_barrier
	s_waitcnt lgkmcnt(3)
	v_mfma_f32_16x16x32_bf16 v[112:115], v[202:205], v[144:147], v[112:115]
	s_waitcnt lgkmcnt(1)
	v_mfma_f32_16x16x32_bf16 v[104:107], v[210:213], v[144:147], v[104:107]
	v_mfma_f32_16x16x32_bf16 v[100:103], v[202:205], v[176:179], v[100:103]
	v_mfma_f32_16x16x32_bf16 v[96:99], v[210:213], v[176:179], v[96:99]
	v_mfma_f32_16x16x32_bf16 v[84:87], v[202:205], v[186:189], v[84:87]
	v_mfma_f32_16x16x32_bf16 v[80:83], v[210:213], v[186:189], v[80:83]
	v_mfma_f32_16x16x32_bf16 v[68:71], v[202:205], v[194:197], v[68:71]
	v_mfma_f32_16x16x32_bf16 v[64:67], v[210:213], v[194:197], v[64:67]
	v_mfma_f32_16x16x32_bf16 v[112:115], v[206:209], v[164:167], v[112:115]
	s_waitcnt lgkmcnt(0)
	v_mfma_f32_16x16x32_bf16 v[104:107], v[214:217], v[164:167], v[104:107]
	v_mfma_f32_16x16x32_bf16 v[100:103], v[206:209], v[182:185], v[100:103]
	v_mfma_f32_16x16x32_bf16 v[96:99], v[214:217], v[182:185], v[96:99]
	v_mfma_f32_16x16x32_bf16 v[84:87], v[206:209], v[190:193], v[84:87]
	v_mfma_f32_16x16x32_bf16 v[80:83], v[214:217], v[190:193], v[80:83]
	v_mfma_f32_16x16x32_bf16 v[68:71], v[206:209], v[198:201], v[68:71]
	v_mfma_f32_16x16x32_bf16 v[64:67], v[214:217], v[198:201], v[64:67]
	s_mov_b32 m0, s56
	s_barrier
	ds_read_b128 v[144:147], v174 offset:49152
	ds_read_b128 v[164:167], v174 offset:50176
	ds_read_b128 v[176:179], v174 offset:51200
	ds_read_b128 v[182:185], v174 offset:52224
	ds_read_b128 v[186:189], v174 offset:53248
	ds_read_b128 v[190:193], v174 offset:54272
	ds_read_b128 v[194:197], v174 offset:55296
	ds_read_b128 v[198:201], v174 offset:56320
	global_load_lds_dwordx4 v148, s[88:89]
	s_mov_b32 m0, s57
	s_nop 0
	global_load_lds_dwordx4 v152, s[88:89]
	s_barrier
	s_waitcnt lgkmcnt(7)
	v_mfma_f32_16x16x32_bf16 v[60:63], v[128:131], v[144:147], v[60:63]
	v_mfma_f32_16x16x32_bf16 v[56:59], v[136:139], v[144:147], v[56:59]
	s_waitcnt lgkmcnt(5)
	v_mfma_f32_16x16x32_bf16 v[44:47], v[128:131], v[176:179], v[44:47]
	v_mfma_f32_16x16x32_bf16 v[40:43], v[136:139], v[176:179], v[40:43]
	s_waitcnt lgkmcnt(3)
	v_mfma_f32_16x16x32_bf16 v[36:39], v[128:131], v[186:189], v[36:39]
	v_mfma_f32_16x16x32_bf16 v[32:35], v[136:139], v[186:189], v[32:35]
	s_waitcnt lgkmcnt(1)
	v_mfma_f32_16x16x32_bf16 v[20:23], v[128:131], v[194:197], v[20:23]
	v_mfma_f32_16x16x32_bf16 v[16:19], v[136:139], v[194:197], v[16:19]
	v_mfma_f32_16x16x32_bf16 v[60:63], v[132:135], v[164:167], v[60:63]
	v_mfma_f32_16x16x32_bf16 v[56:59], v[140:143], v[164:167], v[56:59]
	v_mfma_f32_16x16x32_bf16 v[44:47], v[132:135], v[182:185], v[44:47]
	v_mfma_f32_16x16x32_bf16 v[40:43], v[140:143], v[182:185], v[40:43]
	v_mfma_f32_16x16x32_bf16 v[36:39], v[132:135], v[190:193], v[36:39]
	v_mfma_f32_16x16x32_bf16 v[32:35], v[140:143], v[190:193], v[32:35]
	s_waitcnt lgkmcnt(0)
	v_mfma_f32_16x16x32_bf16 v[20:23], v[132:135], v[198:201], v[20:23]
	v_mfma_f32_16x16x32_bf16 v[16:19], v[140:143], v[198:201], v[16:19]
	s_barrier
	s_add_u32 s38, s38, 0xb0080
	s_addc_u32 s39, s39, 0
	s_add_i32 s40, s40, s48
	s_mov_b32 m0, s40
	s_nop 0
	global_load_lds_dwordx4 v150, s[38:39]
	s_add_i32 m0, s40, 0x2000
	s_nop 0
	global_load_lds_dwordx4 v154, s[38:39]
	s_waitcnt vmcnt(6)
	s_barrier
	v_mfma_f32_16x16x32_bf16 v[52:55], v[202:205], v[144:147], v[52:55]
	v_mfma_f32_16x16x32_bf16 v[48:51], v[210:213], v[144:147], v[48:51]
	v_mfma_f32_16x16x32_bf16 v[28:31], v[202:205], v[176:179], v[28:31]
	v_mfma_f32_16x16x32_bf16 v[24:27], v[210:213], v[176:179], v[24:27]
	v_mfma_f32_16x16x32_bf16 v[12:15], v[202:205], v[186:189], v[12:15]
	v_mfma_f32_16x16x32_bf16 v[8:11], v[210:213], v[186:189], v[8:11]
	v_mfma_f32_16x16x32_bf16 v[4:7], v[202:205], v[194:197], v[4:7]
	v_mfma_f32_16x16x32_bf16 v[0:3], v[210:213], v[194:197], v[0:3]
	v_mfma_f32_16x16x32_bf16 v[52:55], v[206:209], v[164:167], v[52:55]
	v_mfma_f32_16x16x32_bf16 v[48:51], v[214:217], v[164:167], v[48:51]
	v_mfma_f32_16x16x32_bf16 v[28:31], v[206:209], v[182:185], v[28:31]
	v_mfma_f32_16x16x32_bf16 v[24:27], v[214:217], v[182:185], v[24:27]
	v_mfma_f32_16x16x32_bf16 v[12:15], v[206:209], v[190:193], v[12:15]
	v_mfma_f32_16x16x32_bf16 v[8:11], v[214:217], v[190:193], v[8:11]
	v_mfma_f32_16x16x32_bf16 v[4:7], v[206:209], v[198:201], v[4:7]
	v_mfma_f32_16x16x32_bf16 v[0:3], v[214:217], v[198:201], v[0:3]
	s_add_i32 s73, s73, 2
	s_add_u32 s36, s36, 0x100
	s_addc_u32 s37, s37, 0
	s_add_u32 s71, s71, 0x100
	s_addc_u32 s72, s72, 0
	s_cmp_gt_u32 s73, 41
	s_barrier
; DI unsigned pk2(float a, float b) { f32x2 v = {a, b}; bf16x2_t r = __builtin_convertvector(v, bf16x2_t); return __builtin_bit_cast(unsigned, r); }
; DI float bflo(unsigned u) { return __uint_as_float(u << 16); }
; DI float bfhi(unsigned u) { return __uint_as_float(u & 0xffff0000u); }
;     DI void operator()(const f32x4 (&acc)[2][2][4][2], const Unit& u, int wr, int wc, int fr, int fq) const {
;         const int row0 = u.pm * BM + wr * 64 + fr, col0 = u.pn * BM + wc * 32 + 8 * fq;
;         const float* gp = gate + (size_t)((u.pm * BM) >> 12) * NMODC + col0;
;         f32x4 gv[2][2];
; #pragma unroll
;         for (int bj = 0; bj < 2; ++bj)
; #pragma unroll
;             for (int n = 0; n < 2; ++n) gv[bj][n] = *(const f32x4*)(gp + bj * HALF + n * 4);
; #pragma unroll
;         for (int ai = 0; ai < 2; ++ai)
; #pragma unroll
;             for (int m = 0; m < 4; ++m) { const size_t ro = (size_t)(row0 + ai * HALF + m * 16) * DM + col0;
; #pragma unroll
;                 for (int bj = 0; bj < 2; ++bj) {
;                     const u32x4 q = *(const u32x4*)(xb + ro + bj * HALF);
;                     const f32x4 b0 = {bflo(q.x), bfhi(q.x), bflo(q.y), bfhi(q.y)}, b1 = {bflo(q.z), bfhi(q.z), bflo(q.w), bfhi(q.w)};
;                     const f32x4 x0 = b0 + gv[bj][0] * acc[ai][bj][m][0], x1 = b1 + gv[bj][1] * acc[ai][bj][m][1];
;                     u32x4 w; w.x = pk2(x0.x, x0.y); w.y = pk2(x0.z, x0.w); w.z = pk2(x1.x, x1.y); w.w = pk2(x1.z, x1.w);
;                     *(u32x4*)(xb + ro + bj * HALF) = w; } }
	s_cbranch_scc0 .LBB0_928
	v_lshl_add_u32 v147, s67, 8, v170
	v_lshl_or_b32 v164, s70, 8, v172
	s_ashr_i32 s36, s67, 4
	s_mul_hi_i32 s37, s36, 0x6000
	s_mulk_i32 s36, 0x6000
	s_add_u32 s36, s54, s36
	s_addc_u32 s37, s55, s37
	v_lshlrev_b32_e32 v145, 2, v164
	v_lshlrev_b32_e32 v144, 11, v147
	global_load_dwordx4 v[128:131], v145, s[36:37]
	global_load_dwordx4 v[132:135], v145, s[36:37] offset:16
	global_load_dwordx4 v[136:139], v145, s[36:37] offset:512
	global_load_dwordx4 v[140:143], v145, s[36:37] offset:528
	v_lshl_add_u32 v144, v164, 1, v144
	s_mov_b32 s70, s65
	s_mov_b32 s67, s66
	s_mov_b64 s[38:39], s[8:9]
	s_mov_b64 s[36:37], s[6:7]
	global_load_dwordx4 v[184:187], v144, s[14:15]
	global_load_dwordx4 v[188:191], v144, s[14:15] offset:256
	v_add_u32_e32 v146, 0x8000, v144
	global_load_dwordx4 v[192:195], v146, s[14:15]
	global_load_dwordx4 v[196:199], v146, s[14:15] offset:256
	v_add_u32_e32 v146, 0x10000, v144
	global_load_dwordx4 v[200:203], v146, s[14:15]
	global_load_dwordx4 v[204:207], v146, s[14:15] offset:256
	v_add_u32_e32 v146, 0x18000, v144
	global_load_dwordx4 v[208:211], v146, s[14:15]
	global_load_dwordx4 v[212:215], v146, s[14:15] offset:256
	v_add_u32_e32 v146, 0x40000, v144
	global_load_dwordx4 v[216:219], v146, s[14:15]
	global_load_dwordx4 v[220:223], v146, s[14:15] offset:256
	v_add_u32_e32 v146, 0x48000, v144
	global_load_dwordx4 v[224:227], v146, s[14:15]
	global_load_dwordx4 v[228:231], v146, s[14:15] offset:256
	v_add_u32_e32 v146, 0x50000, v144
	global_load_dwordx4 v[232:235], v146, s[14:15]
	global_load_dwordx4 v[236:239], v146, s[14:15] offset:256
	v_add_u32_e32 v146, 0x58000, v144
	global_load_dwordx4 v[240:243], v146, s[14:15]
	global_load_dwordx4 v[244:247], v146, s[14:15] offset:256
	s_waitcnt vmcnt(15)
	v_lshlrev_b32_e32 v248, 16, v184
	v_and_b32_e32 v249, 0xffff0000, v184
	v_lshlrev_b32_e32 v250, 16, v185
	v_and_b32_e32 v251, 0xffff0000, v185
	v_lshlrev_b32_e32 v252, 16, v186
	v_and_b32_e32 v253, 0xffff0000, v186
	v_lshlrev_b32_e32 v254, 16, v187
	v_and_b32_e32 v255, 0xffff0000, v187
	v_pk_fma_f32 v[124:125], v[124:125], v[128:129], v[248:249]
	v_pk_fma_f32 v[126:127], v[126:127], v[130:131], v[250:251]
	v_pk_fma_f32 v[120:121], v[120:121], v[132:133], v[252:253]
	v_pk_fma_f32 v[122:123], v[122:123], v[134:135], v[254:255]
	v_cvt_pk_bf16_f32 v124, v124, v125
	v_cvt_pk_bf16_f32 v125, v126, v127
	v_cvt_pk_bf16_f32 v126, v120, v121
	v_cvt_pk_bf16_f32 v127, v122, v123
	global_store_dwordx4 v144, v[124:127], s[14:15]
	s_waitcnt vmcnt(15)
	v_lshlrev_b32_e32 v248, 16, v188
	v_and_b32_e32 v249, 0xffff0000, v188
	v_lshlrev_b32_e32 v250, 16, v189
	v_and_b32_e32 v251, 0xffff0000, v189
	v_lshlrev_b32_e32 v252, 16, v190
	v_and_b32_e32 v253, 0xffff0000, v190
	v_lshlrev_b32_e32 v254, 16, v191
	v_and_b32_e32 v255, 0xffff0000, v191
	v_pk_fma_f32 v[112:113], v[112:113], v[136:137], v[248:249]
	v_pk_fma_f32 v[114:115], v[114:115], v[138:139], v[250:251]
	v_pk_fma_f32 v[104:105], v[104:105], v[140:141], v[252:253]
	v_pk_fma_f32 v[106:107], v[106:107], v[142:143], v[254:255]
	v_cvt_pk_bf16_f32 v112, v112, v113
	v_cvt_pk_bf16_f32 v113, v114, v115
	v_cvt_pk_bf16_f32 v114, v104, v105
	v_cvt_pk_bf16_f32 v115, v106, v107
	global_store_dwordx4 v144, v[112:115], s[14:15] offset:256
	s_waitcnt vmcnt(15)
	v_lshlrev_b32_e32 v248, 16, v192
	v_and_b32_e32 v249, 0xffff0000, v192
	v_lshlrev_b32_e32 v250, 16, v193
	v_and_b32_e32 v251, 0xffff0000, v193
	v_lshlrev_b32_e32 v252, 16, v194
	v_and_b32_e32 v253, 0xffff0000, v194
	v_lshlrev_b32_e32 v254, 16, v195
	v_and_b32_e32 v255, 0xffff0000, v195
	v_pk_fma_f32 v[116:117], v[116:117], v[128:129], v[248:249]
	v_pk_fma_f32 v[118:119], v[118:119], v[130:131], v[250:251]
	v_pk_fma_f32 v[108:109], v[108:109], v[132:133], v[252:253]
	v_pk_fma_f32 v[110:111], v[110:111], v[134:135], v[254:255]
	v_cvt_pk_bf16_f32 v116, v116, v117
	v_cvt_pk_bf16_f32 v117, v118, v119
	v_cvt_pk_bf16_f32 v118, v108, v109
	v_cvt_pk_bf16_f32 v119, v110, v111
	v_add_u32_e32 v146, 0x8000, v144
	global_store_dwordx4 v146, v[116:119], s[14:15]
	s_waitcnt vmcnt(15)
	v_lshlrev_b32_e32 v248, 16, v196
	v_and_b32_e32 v249, 0xffff0000, v196
	v_lshlrev_b32_e32 v250, 16, v197
	v_and_b32_e32 v251, 0xffff0000, v197
	v_lshlrev_b32_e32 v252, 16, v198
	v_and_b32_e32 v253, 0xffff0000, v198
	v_lshlrev_b32_e32 v254, 16, v199
	v_and_b32_e32 v255, 0xffff0000, v199
	v_pk_fma_f32 v[100:101], v[100:101], v[136:137], v[248:249]
	v_pk_fma_f32 v[102:103], v[102:103], v[138:139], v[250:251]
	v_pk_fma_f32 v[96:97], v[96:97], v[140:141], v[252:253]
	v_pk_fma_f32 v[98:99], v[98:99], v[142:143], v[254:255]
	v_cvt_pk_bf16_f32 v100, v100, v101
	v_cvt_pk_bf16_f32 v101, v102, v103
	v_cvt_pk_bf16_f32 v102, v96, v97
	v_cvt_pk_bf16_f32 v103, v98, v99
	v_add_u32_e32 v146, 0x8000, v144
	global_store_dwordx4 v146, v[100:103], s[14:15] offset:256
	s_waitcnt vmcnt(15)
	v_lshlrev_b32_e32 v248, 16, v200
	v_and_b32_e32 v249, 0xffff0000, v200
	v_lshlrev_b32_e32 v250, 16, v201
	v_and_b32_e32 v251, 0xffff0000, v201
	v_lshlrev_b32_e32 v252, 16, v202
	v_and_b32_e32 v253, 0xffff0000, v202
	v_lshlrev_b32_e32 v254, 16, v203
	v_and_b32_e32 v255, 0xffff0000, v203
	v_pk_fma_f32 v[92:93], v[92:93], v[128:129], v[248:249]
	v_pk_fma_f32 v[94:95], v[94:95], v[130:131], v[250:251]
	v_pk_fma_f32 v[88:89], v[88:89], v[132:133], v[252:253]
	v_pk_fma_f32 v[90:91], v[90:91], v[134:135], v[254:255]
	v_cvt_pk_bf16_f32 v92, v92, v93
	v_cvt_pk_bf16_f32 v93, v94, v95
	v_cvt_pk_bf16_f32 v94, v88, v89
	v_cvt_pk_bf16_f32 v95, v90, v91
	v_add_u32_e32 v146, 0x10000, v144
	global_store_dwordx4 v146, v[92:95], s[14:15]
	s_waitcnt vmcnt(15)
; DI unsigned pk2(float a, float b) { f32x2 v = {a, b}; bf16x2_t r = __builtin_convertvector(v, bf16x2_t); return __builtin_bit_cast(unsigned, r); }
; DI float bflo(unsigned u) { return __uint_as_float(u << 16); }
; DI float bfhi(unsigned u) { return __uint_as_float(u & 0xffff0000u); }
;     DI void operator()(const f32x4 (&acc)[2][2][4][2], const Unit& u, int wr, int wc, int fr, int fq) const {
;     ...
;             for (int m = 0; m < 4; ++m) { const size_t ro = (size_t)(row0 + ai * HALF + m * 16) * DM + col0;
; #pragma unroll
;                 for (int bj = 0; bj < 2; ++bj) {
;                     const u32x4 q = *(const u32x4*)(xb + ro + bj * HALF);
;                     const f32x4 b0 = {bflo(q.x), bfhi(q.x), bflo(q.y), bfhi(q.y)}, b1 = {bflo(q.z), bfhi(q.z), bflo(q.w), bfhi(q.w)};
;                     const f32x4 x0 = b0 + gv[bj][0] * acc[ai][bj][m][0], x1 = b1 + gv[bj][1] * acc[ai][bj][m][1];
;                     u32x4 w; w.x = pk2(x0.x, x0.y); w.y = pk2(x0.z, x0.w); w.z = pk2(x1.x, x1.y); w.w = pk2(x1.z, x1.w);
;                     *(u32x4*)(xb + ro + bj * HALF) = w; } }
	v_lshlrev_b32_e32 v248, 16, v204
	v_and_b32_e32 v249, 0xffff0000, v204
	v_lshlrev_b32_e32 v250, 16, v205
	v_and_b32_e32 v251, 0xffff0000, v205
	v_lshlrev_b32_e32 v252, 16, v206
	v_and_b32_e32 v253, 0xffff0000, v206
	v_lshlrev_b32_e32 v254, 16, v207
	v_and_b32_e32 v255, 0xffff0000, v207
	v_pk_fma_f32 v[84:85], v[84:85], v[136:137], v[248:249]
	v_pk_fma_f32 v[86:87], v[86:87], v[138:139], v[250:251]
	v_pk_fma_f32 v[80:81], v[80:81], v[140:141], v[252:253]
	v_pk_fma_f32 v[82:83], v[82:83], v[142:143], v[254:255]
	v_cvt_pk_bf16_f32 v84, v84, v85
	v_cvt_pk_bf16_f32 v85, v86, v87
	v_cvt_pk_bf16_f32 v86, v80, v81
	v_cvt_pk_bf16_f32 v87, v82, v83
	v_add_u32_e32 v146, 0x10000, v144
	global_store_dwordx4 v146, v[84:87], s[14:15] offset:256
	s_waitcnt vmcnt(15)
	v_lshlrev_b32_e32 v248, 16, v208
	v_and_b32_e32 v249, 0xffff0000, v208
	v_lshlrev_b32_e32 v250, 16, v209
	v_and_b32_e32 v251, 0xffff0000, v209
	v_lshlrev_b32_e32 v252, 16, v210
	v_and_b32_e32 v253, 0xffff0000, v210
	v_lshlrev_b32_e32 v254, 16, v211
	v_and_b32_e32 v255, 0xffff0000, v211
	v_pk_fma_f32 v[76:77], v[76:77], v[128:129], v[248:249]
	v_pk_fma_f32 v[78:79], v[78:79], v[130:131], v[250:251]
	v_pk_fma_f32 v[72:73], v[72:73], v[132:133], v[252:253]
	v_pk_fma_f32 v[74:75], v[74:75], v[134:135], v[254:255]
	v_cvt_pk_bf16_f32 v76, v76, v77
	v_cvt_pk_bf16_f32 v77, v78, v79
	v_cvt_pk_bf16_f32 v78, v72, v73
	v_cvt_pk_bf16_f32 v79, v74, v75
	v_add_u32_e32 v146, 0x18000, v144
	global_store_dwordx4 v146, v[76:79], s[14:15]
	s_waitcnt vmcnt(15)
	v_lshlrev_b32_e32 v248, 16, v212
	v_and_b32_e32 v249, 0xffff0000, v212
	v_lshlrev_b32_e32 v250, 16, v213
	v_and_b32_e32 v251, 0xffff0000, v213
	v_lshlrev_b32_e32 v252, 16, v214
	v_and_b32_e32 v253, 0xffff0000, v214
	v_lshlrev_b32_e32 v254, 16, v215
	v_and_b32_e32 v255, 0xffff0000, v215
	v_pk_fma_f32 v[68:69], v[68:69], v[136:137], v[248:249]
	v_pk_fma_f32 v[70:71], v[70:71], v[138:139], v[250:251]
	v_pk_fma_f32 v[64:65], v[64:65], v[140:141], v[252:253]
	v_pk_fma_f32 v[66:67], v[66:67], v[142:143], v[254:255]
	v_cvt_pk_bf16_f32 v68, v68, v69
	v_cvt_pk_bf16_f32 v69, v70, v71
	v_cvt_pk_bf16_f32 v70, v64, v65
	v_cvt_pk_bf16_f32 v71, v66, v67
	v_add_u32_e32 v146, 0x18000, v144
	global_store_dwordx4 v146, v[68:71], s[14:15] offset:256
	s_waitcnt vmcnt(15)
	v_lshlrev_b32_e32 v248, 16, v216
	v_and_b32_e32 v249, 0xffff0000, v216
	v_lshlrev_b32_e32 v250, 16, v217
	v_and_b32_e32 v251, 0xffff0000, v217
	v_lshlrev_b32_e32 v252, 16, v218
	v_and_b32_e32 v253, 0xffff0000, v218
	v_lshlrev_b32_e32 v254, 16, v219
	v_and_b32_e32 v255, 0xffff0000, v219
	v_pk_fma_f32 v[60:61], v[60:61], v[128:129], v[248:249]
	v_pk_fma_f32 v[62:63], v[62:63], v[130:131], v[250:251]
	v_pk_fma_f32 v[56:57], v[56:57], v[132:133], v[252:253]
	v_pk_fma_f32 v[58:59], v[58:59], v[134:135], v[254:255]
	v_cvt_pk_bf16_f32 v60, v60, v61
	v_cvt_pk_bf16_f32 v61, v62, v63
	v_cvt_pk_bf16_f32 v62, v56, v57
	v_cvt_pk_bf16_f32 v63, v58, v59
	v_add_u32_e32 v146, 0x40000, v144
	global_store_dwordx4 v146, v[60:63], s[14:15]
	s_waitcnt vmcnt(15)
	v_lshlrev_b32_e32 v248, 16, v220
	v_and_b32_e32 v249, 0xffff0000, v220
	v_lshlrev_b32_e32 v250, 16, v221
	v_and_b32_e32 v251, 0xffff0000, v221
	v_lshlrev_b32_e32 v252, 16, v222
	v_and_b32_e32 v253, 0xffff0000, v222
	v_lshlrev_b32_e32 v254, 16, v223
	v_and_b32_e32 v255, 0xffff0000, v223
	v_pk_fma_f32 v[52:53], v[52:53], v[136:137], v[248:249]
	v_pk_fma_f32 v[54:55], v[54:55], v[138:139], v[250:251]
	v_pk_fma_f32 v[48:49], v[48:49], v[140:141], v[252:253]
	v_pk_fma_f32 v[50:51], v[50:51], v[142:143], v[254:255]
	v_cvt_pk_bf16_f32 v52, v52, v53
	v_cvt_pk_bf16_f32 v53, v54, v55
	v_cvt_pk_bf16_f32 v54, v48, v49
	v_cvt_pk_bf16_f32 v55, v50, v51
	v_add_u32_e32 v146, 0x40000, v144
	global_store_dwordx4 v146, v[52:55], s[14:15] offset:256
	s_waitcnt vmcnt(15)
	v_lshlrev_b32_e32 v248, 16, v224
	v_and_b32_e32 v249, 0xffff0000, v224
	v_lshlrev_b32_e32 v250, 16, v225
	v_and_b32_e32 v251, 0xffff0000, v225
	v_lshlrev_b32_e32 v252, 16, v226
	v_and_b32_e32 v253, 0xffff0000, v226
	v_lshlrev_b32_e32 v254, 16, v227
	v_and_b32_e32 v255, 0xffff0000, v227
	v_pk_fma_f32 v[44:45], v[44:45], v[128:129], v[248:249]
	v_pk_fma_f32 v[46:47], v[46:47], v[130:131], v[250:251]
	v_pk_fma_f32 v[40:41], v[40:41], v[132:133], v[252:253]
	v_pk_fma_f32 v[42:43], v[42:43], v[134:135], v[254:255]
	v_cvt_pk_bf16_f32 v44, v44, v45
	v_cvt_pk_bf16_f32 v45, v46, v47
	v_cvt_pk_bf16_f32 v46, v40, v41
	v_cvt_pk_bf16_f32 v47, v42, v43
	v_add_u32_e32 v146, 0x48000, v144
	global_store_dwordx4 v146, v[44:47], s[14:15]
	s_waitcnt vmcnt(15)
; DI unsigned pk2(float a, float b) { f32x2 v = {a, b}; bf16x2_t r = __builtin_convertvector(v, bf16x2_t); return __builtin_bit_cast(unsigned, r); }
; DI float bflo(unsigned u) { return __uint_as_float(u << 16); }
; DI float bfhi(unsigned u) { return __uint_as_float(u & 0xffff0000u); }
; #define PG8_WAIT_V(n) asm volatile("s_waitcnt vmcnt(" #n ")" ::: "memory")
; #define PG8_BAR __builtin_amdgcn_s_barrier()
; template <class Epi>
; DI void gemm_phase(LAS unsigned char* lds, const Gemm g, const StaticOrder& S, const Epi& E) {
;     ...
;         if (!has_next) break;
; #pragma unroll
;         for (int a = 0; a < 2; ++a)
; #pragma unroll
;             for (int b = 0; b < 2; ++b)
; #pragma unroll
;                 for (int m = 0; m < 4; ++m)
; #pragma unroll
;                     for (int n = 0; n < 2; ++n) acc[a][b][m][n] = (f32x4){0.f, 0.f, 0.f, 0.f};
;         cur = nxt; cA = nA; cB = nB; ++ui;
;     }
;     PG8_WAIT_V(0);
;     if (wr == 0) PG8_BAR;
;     PG8_BAR;
;     DI void operator()(const f32x4 (&acc)[2][2][4][2], const Unit& u, int wr, int wc, int fr, int fq) const {
;     ...
;             for (int m = 0; m < 4; ++m) { const size_t ro = (size_t)(row0 + ai * HALF + m * 16) * DM + col0;
; #pragma unroll
;                 for (int bj = 0; bj < 2; ++bj) {
;                     const u32x4 q = *(const u32x4*)(xb + ro + bj * HALF);
;                     const f32x4 b0 = {bflo(q.x), bfhi(q.x), bflo(q.y), bfhi(q.y)}, b1 = {bflo(q.z), bfhi(q.z), bflo(q.w), bfhi(q.w)};
;                     const f32x4 x0 = b0 + gv[bj][0] * acc[ai][bj][m][0], x1 = b1 + gv[bj][1] * acc[ai][bj][m][1];
;                     u32x4 w; w.x = pk2(x0.x, x0.y); w.y = pk2(x0.z, x0.w); w.z = pk2(x1.x, x1.y); w.w = pk2(x1.z, x1.w);
;                     *(u32x4*)(xb + ro + bj * HALF) = w; } }
	v_lshlrev_b32_e32 v248, 16, v228
	v_and_b32_e32 v249, 0xffff0000, v228
	v_lshlrev_b32_e32 v250, 16, v229
	v_and_b32_e32 v251, 0xffff0000, v229
	v_lshlrev_b32_e32 v252, 16, v230
	v_and_b32_e32 v253, 0xffff0000, v230
	v_lshlrev_b32_e32 v254, 16, v231
	v_and_b32_e32 v255, 0xffff0000, v231
	v_pk_fma_f32 v[28:29], v[28:29], v[136:137], v[248:249]
	v_pk_fma_f32 v[30:31], v[30:31], v[138:139], v[250:251]
	v_pk_fma_f32 v[24:25], v[24:25], v[140:141], v[252:253]
	v_pk_fma_f32 v[26:27], v[26:27], v[142:143], v[254:255]
	v_cvt_pk_bf16_f32 v28, v28, v29
	v_cvt_pk_bf16_f32 v29, v30, v31
	v_cvt_pk_bf16_f32 v30, v24, v25
	v_cvt_pk_bf16_f32 v31, v26, v27
	v_add_u32_e32 v146, 0x48000, v144
	global_store_dwordx4 v146, v[28:31], s[14:15] offset:256
	s_waitcnt vmcnt(15)
	v_lshlrev_b32_e32 v248, 16, v232
	v_and_b32_e32 v249, 0xffff0000, v232
	v_lshlrev_b32_e32 v250, 16, v233
	v_and_b32_e32 v251, 0xffff0000, v233
	v_lshlrev_b32_e32 v252, 16, v234
	v_and_b32_e32 v253, 0xffff0000, v234
	v_lshlrev_b32_e32 v254, 16, v235
	v_and_b32_e32 v255, 0xffff0000, v235
	v_pk_fma_f32 v[36:37], v[36:37], v[128:129], v[248:249]
	v_pk_fma_f32 v[38:39], v[38:39], v[130:131], v[250:251]
	v_pk_fma_f32 v[32:33], v[32:33], v[132:133], v[252:253]
	v_pk_fma_f32 v[34:35], v[34:35], v[134:135], v[254:255]
	v_cvt_pk_bf16_f32 v36, v36, v37
	v_cvt_pk_bf16_f32 v37, v38, v39
	v_cvt_pk_bf16_f32 v38, v32, v33
	v_cvt_pk_bf16_f32 v39, v34, v35
	v_add_u32_e32 v146, 0x50000, v144
	global_store_dwordx4 v146, v[36:39], s[14:15]
	s_waitcnt vmcnt(15)
	v_lshlrev_b32_e32 v248, 16, v236
	v_and_b32_e32 v249, 0xffff0000, v236
	v_lshlrev_b32_e32 v250, 16, v237
	v_and_b32_e32 v251, 0xffff0000, v237
	v_lshlrev_b32_e32 v252, 16, v238
	v_and_b32_e32 v253, 0xffff0000, v238
	v_lshlrev_b32_e32 v254, 16, v239
	v_and_b32_e32 v255, 0xffff0000, v239
	v_pk_fma_f32 v[12:13], v[12:13], v[136:137], v[248:249]
	v_pk_fma_f32 v[14:15], v[14:15], v[138:139], v[250:251]
	v_pk_fma_f32 v[8:9], v[8:9], v[140:141], v[252:253]
	v_pk_fma_f32 v[10:11], v[10:11], v[142:143], v[254:255]
	v_cvt_pk_bf16_f32 v12, v12, v13
	v_cvt_pk_bf16_f32 v13, v14, v15
	v_cvt_pk_bf16_f32 v14, v8, v9
	v_cvt_pk_bf16_f32 v15, v10, v11
	v_add_u32_e32 v146, 0x50000, v144
	global_store_dwordx4 v146, v[12:15], s[14:15] offset:256
	s_waitcnt vmcnt(15)
	v_lshlrev_b32_e32 v248, 16, v240
	v_and_b32_e32 v249, 0xffff0000, v240
	v_lshlrev_b32_e32 v250, 16, v241
	v_and_b32_e32 v251, 0xffff0000, v241
	v_lshlrev_b32_e32 v252, 16, v242
	v_and_b32_e32 v253, 0xffff0000, v242
	v_lshlrev_b32_e32 v254, 16, v243
	v_and_b32_e32 v255, 0xffff0000, v243
	v_pk_fma_f32 v[20:21], v[20:21], v[128:129], v[248:249]
	v_pk_fma_f32 v[22:23], v[22:23], v[130:131], v[250:251]
	v_pk_fma_f32 v[16:17], v[16:17], v[132:133], v[252:253]
	v_pk_fma_f32 v[18:19], v[18:19], v[134:135], v[254:255]
	v_cvt_pk_bf16_f32 v20, v20, v21
	v_cvt_pk_bf16_f32 v21, v22, v23
	v_cvt_pk_bf16_f32 v22, v16, v17
	v_cvt_pk_bf16_f32 v23, v18, v19
	v_add_u32_e32 v146, 0x58000, v144
	global_store_dwordx4 v146, v[20:23], s[14:15]
	s_waitcnt vmcnt(15)
	v_lshlrev_b32_e32 v248, 16, v244
	v_and_b32_e32 v249, 0xffff0000, v244
	v_lshlrev_b32_e32 v250, 16, v245
	v_and_b32_e32 v251, 0xffff0000, v245
	v_lshlrev_b32_e32 v252, 16, v246
	v_and_b32_e32 v253, 0xffff0000, v246
	v_lshlrev_b32_e32 v254, 16, v247
	v_and_b32_e32 v255, 0xffff0000, v247
	v_pk_fma_f32 v[4:5], v[4:5], v[136:137], v[248:249]
	v_pk_fma_f32 v[6:7], v[6:7], v[138:139], v[250:251]
	v_pk_fma_f32 v[0:1], v[0:1], v[140:141], v[252:253]
	v_pk_fma_f32 v[2:3], v[2:3], v[142:143], v[254:255]
	v_cvt_pk_bf16_f32 v4, v4, v5
	v_cvt_pk_bf16_f32 v5, v6, v7
	v_cvt_pk_bf16_f32 v6, v0, v1
	v_cvt_pk_bf16_f32 v7, v2, v3
	v_add_u32_e32 v146, 0x58000, v144
	global_store_dwordx4 v146, v[4:7], s[14:15] offset:256
	s_and_b64 vcc, exec, s[4:5]
	s_cbranch_vccz .LBB0_917
	s_waitcnt vmcnt(0)
	s_cmpk_gt_u32 s42, 0xff
	s_cbranch_scc1 .LBB0_932
	s_barrier
